# GEMM K loops: in the 16-ds_read loader segments the ds_read burst (address adds with literal LDS offsets) is issued ahead of the scalar pointer arithmetic and the LDS-DMA pieces; on top of kprio=lo
# speedup vs baseline: 1.0012x; 1.0012x over previous
.Lkprio_311:
.LBB0_311:
	v_add_u32_e32 v164, 0x10000, v143
	v_add_u32_e32 v180, 0x14000, v143
	ds_read_b128 v[138:141], v164
	ds_read_b128 v[156:159], v164 offset:1024
	ds_read_b128 v[160:163], v164 offset:2048
	ds_read_b128 v[164:167], v164 offset:3072
	ds_read_b128 v[168:171], v180
	ds_read_b128 v[172:175], v180 offset:1024
	ds_read_b128 v[176:179], v180 offset:2048
	ds_read_b128 v[204:207], v180 offset:3072
	ds_read_b128 v[208:211], v155
	ds_read_b128 v[212:215], v155 offset:1024
	ds_read_b128 v[216:219], v155 offset:2048
	ds_read_b128 v[220:223], v155 offset:3072
	ds_read_b128 v[224:227], v155 offset:4096
	ds_read_b128 v[228:231], v155 offset:5120
	ds_read_b128 v[232:235], v155 offset:6144
	ds_read_b128 v[236:239], v155 offset:7168
	s_add_u32 s4, s62, 0xfffc0080
	s_addc_u32 s5, s63, -1
	s_add_i32 s84, 0, 0x10000
	s_cmp_eq_u32 s82, 12
	s_cselect_b32 s65, s33, s5
	s_cselect_b32 s64, s36, s4
	s_cselect_b32 s35, s53, s79
	s_cselect_b32 s34, s55, s75
	s_add_i32 s4, 0, 0x14000
	v_lshl_add_u64 v[180:181], s[62:63], 0, v[134:135]
	s_add_i32 m0, s68, 0xc000
	s_nop 0
	global_load_lds_dwordx4 v[180:181], off
	v_lshl_add_u64 v[180:181], s[62:63], 0, v[136:137]
	s_add_i32 m0, s68, 0xe000
	s_nop 0
	global_load_lds_dwordx4 v[180:181], off
	s_waitcnt vmcnt(8)
	s_waitcnt lgkmcnt(0)
	s_barrier
	s_waitcnt lgkmcnt(0)
	v_mfma_f32_16x16x32_bf16 v[124:127], v[138:141], v[208:211], v[124:127]
	v_mfma_f32_16x16x32_bf16 v[120:123], v[160:163], v[208:211], v[120:123]
	v_mfma_f32_16x16x32_bf16 v[108:111], v[138:141], v[216:219], v[108:111]
	v_mfma_f32_16x16x32_bf16 v[104:107], v[160:163], v[216:219], v[104:107]
	v_mfma_f32_16x16x32_bf16 v[92:95], v[138:141], v[224:227], v[92:95]
	v_mfma_f32_16x16x32_bf16 v[88:91], v[160:163], v[224:227], v[88:91]
	v_mfma_f32_16x16x32_bf16 v[76:79], v[138:141], v[232:235], v[76:79]
	v_mfma_f32_16x16x32_bf16 v[72:75], v[160:163], v[232:235], v[72:75]
	v_mfma_f32_16x16x32_bf16 v[124:127], v[156:159], v[212:215], v[124:127]
	v_mfma_f32_16x16x32_bf16 v[120:123], v[164:167], v[212:215], v[120:123]
	v_mfma_f32_16x16x32_bf16 v[108:111], v[156:159], v[220:223], v[108:111]
	v_mfma_f32_16x16x32_bf16 v[104:107], v[164:167], v[220:223], v[104:107]
	v_mfma_f32_16x16x32_bf16 v[92:95], v[156:159], v[228:231], v[92:95]
	v_mfma_f32_16x16x32_bf16 v[88:91], v[164:167], v[228:231], v[88:91]
	v_mfma_f32_16x16x32_bf16 v[76:79], v[156:159], v[236:239], v[76:79]
	v_mfma_f32_16x16x32_bf16 v[72:75], v[164:167], v[236:239], v[72:75]
	v_mfma_f32_16x16x32_bf16 v[116:119], v[168:171], v[208:211], v[116:119]
	v_mfma_f32_16x16x32_bf16 v[112:115], v[176:179], v[208:211], v[112:115]
	v_mfma_f32_16x16x32_bf16 v[100:103], v[168:171], v[216:219], v[100:103]
	v_mfma_f32_16x16x32_bf16 v[96:99], v[176:179], v[216:219], v[96:99]
	v_mfma_f32_16x16x32_bf16 v[84:87], v[168:171], v[224:227], v[84:87]
	v_mfma_f32_16x16x32_bf16 v[80:83], v[176:179], v[224:227], v[80:83]
	v_mfma_f32_16x16x32_bf16 v[68:71], v[168:171], v[232:235], v[68:71]
	v_mfma_f32_16x16x32_bf16 v[64:67], v[176:179], v[232:235], v[64:67]
	v_mfma_f32_16x16x32_bf16 v[116:119], v[172:175], v[212:215], v[116:119]
	v_mfma_f32_16x16x32_bf16 v[112:115], v[204:207], v[212:215], v[112:115]
	v_mfma_f32_16x16x32_bf16 v[100:103], v[172:175], v[220:223], v[100:103]
	v_mfma_f32_16x16x32_bf16 v[96:99], v[204:207], v[220:223], v[96:99]
	v_mfma_f32_16x16x32_bf16 v[84:87], v[172:175], v[228:231], v[84:87]
	v_mfma_f32_16x16x32_bf16 v[80:83], v[204:207], v[228:231], v[80:83]
	v_mfma_f32_16x16x32_bf16 v[68:71], v[172:175], v[236:239], v[68:71]
	v_mfma_f32_16x16x32_bf16 v[64:67], v[204:207], v[236:239], v[64:67]
	s_barrier
	s_add_i32 s5, s84, s28
	v_lshl_add_u64 v[180:181], s[34:35], 0, v[144:145]
	s_mov_b32 m0, s5
	ds_read_b128 v[208:211], v155 offset:16384
	ds_read_b128 v[212:215], v155 offset:17408
	ds_read_b128 v[216:219], v155 offset:18432
	ds_read_b128 v[220:223], v155 offset:19456
	ds_read_b128 v[224:227], v155 offset:20480
	ds_read_b128 v[228:231], v155 offset:21504
	ds_read_b128 v[232:235], v155 offset:22528
	ds_read_b128 v[236:239], v155 offset:23552
	global_load_lds_dwordx4 v[180:181], off
	s_add_i32 m0, s5, 0x2000
	s_add_u32 s88, s34, 0x40000
	v_lshl_add_u64 v[240:241], s[34:35], 0, v[128:129]
	s_addc_u32 s89, s35, 0
	s_add_i32 s4, s4, s28
	global_load_lds_dwordx4 v[240:241], off
	v_lshl_add_u64 v[242:243], s[88:89], 0, v[144:145]
	s_mov_b32 m0, s4
	v_lshl_add_u64 v[244:245], s[64:65], 0, v[130:131]
	global_load_lds_dwordx4 v[242:243], off
	v_lshl_add_u64 v[242:243], s[88:89], 0, v[128:129]
	s_add_i32 m0, s4, 0x2000
	s_nop 0
	global_load_lds_dwordx4 v[242:243], off
	v_lshl_add_u64 v[242:243], s[64:65], 0, v[132:133]
	s_mov_b32 m0, s68
	s_nop 0
	global_load_lds_dwordx4 v[242:243], off
	s_mov_b32 m0, s69
	s_nop 0
	global_load_lds_dwordx4 v[244:245], off
	s_waitcnt vmcnt(8)
	s_waitcnt lgkmcnt(0)
	s_barrier
	s_waitcnt lgkmcnt(0)
	v_mfma_f32_16x16x32_bf16 v[60:63], v[138:141], v[208:211], v[60:63]
	v_mfma_f32_16x16x32_bf16 v[56:59], v[160:163], v[208:211], v[56:59]
	v_mfma_f32_16x16x32_bf16 v[44:47], v[138:141], v[216:219], v[44:47]
	v_mfma_f32_16x16x32_bf16 v[40:43], v[160:163], v[216:219], v[40:43]
	v_mfma_f32_16x16x32_bf16 v[28:31], v[138:141], v[224:227], v[28:31]
	v_mfma_f32_16x16x32_bf16 v[24:27], v[160:163], v[224:227], v[24:27]
	v_mfma_f32_16x16x32_bf16 v[12:15], v[138:141], v[232:235], v[12:15]
	v_mfma_f32_16x16x32_bf16 v[8:11], v[160:163], v[232:235], v[8:11]
	v_mfma_f32_16x16x32_bf16 v[60:63], v[156:159], v[212:215], v[60:63]
	v_mfma_f32_16x16x32_bf16 v[56:59], v[164:167], v[212:215], v[56:59]
	v_mfma_f32_16x16x32_bf16 v[44:47], v[156:159], v[220:223], v[44:47]
	v_mfma_f32_16x16x32_bf16 v[40:43], v[164:167], v[220:223], v[40:43]
	v_mfma_f32_16x16x32_bf16 v[28:31], v[156:159], v[228:231], v[28:31]
	v_mfma_f32_16x16x32_bf16 v[24:27], v[164:167], v[228:231], v[24:27]
	v_mfma_f32_16x16x32_bf16 v[12:15], v[156:159], v[236:239], v[12:15]
	v_mfma_f32_16x16x32_bf16 v[8:11], v[164:167], v[236:239], v[8:11]
	v_mfma_f32_16x16x32_bf16 v[52:55], v[168:171], v[208:211], v[52:55]
	v_mfma_f32_16x16x32_bf16 v[48:51], v[176:179], v[208:211], v[48:51]
	v_mfma_f32_16x16x32_bf16 v[36:39], v[168:171], v[216:219], v[36:39]
	v_mfma_f32_16x16x32_bf16 v[32:35], v[176:179], v[216:219], v[32:35]
	v_mfma_f32_16x16x32_bf16 v[20:23], v[168:171], v[224:227], v[20:23]
	v_mfma_f32_16x16x32_bf16 v[16:19], v[176:179], v[224:227], v[16:19]
	v_mfma_f32_16x16x32_bf16 v[4:7], v[168:171], v[232:235], v[4:7]
	v_mfma_f32_16x16x32_bf16 v[0:3], v[176:179], v[232:235], v[0:3]
	v_mfma_f32_16x16x32_bf16 v[52:55], v[172:175], v[212:215], v[52:55]
	v_mfma_f32_16x16x32_bf16 v[48:51], v[204:207], v[212:215], v[48:51]
	v_mfma_f32_16x16x32_bf16 v[36:39], v[172:175], v[220:223], v[36:39]
	v_mfma_f32_16x16x32_bf16 v[32:35], v[204:207], v[220:223], v[32:35]
	v_mfma_f32_16x16x32_bf16 v[20:23], v[172:175], v[228:231], v[20:23]
	v_mfma_f32_16x16x32_bf16 v[16:19], v[204:207], v[228:231], v[16:19]
	v_mfma_f32_16x16x32_bf16 v[4:7], v[172:175], v[236:239], v[4:7]
	v_mfma_f32_16x16x32_bf16 v[0:3], v[204:207], v[236:239], v[0:3]
	s_barrier
	v_add_u32_e32 v164, 0x18000, v143
	v_add_u32_e32 v202, 0x1c000, v143
	ds_read_b128 v[138:141], v164
	ds_read_b128 v[156:159], v164 offset:1024
	ds_read_b128 v[160:163], v164 offset:2048
	ds_read_b128 v[164:167], v164 offset:3072
	ds_read_b128 v[168:171], v202
	ds_read_b128 v[172:175], v202 offset:1024
	ds_read_b128 v[176:179], v202 offset:2048
	ds_read_b128 v[204:207], v202 offset:3072
	ds_read_b128 v[208:211], v155 offset:32768
	ds_read_b128 v[212:215], v155 offset:33792
	ds_read_b128 v[216:219], v155 offset:34816
	ds_read_b128 v[220:223], v155 offset:35840
	ds_read_b128 v[224:227], v155 offset:36864
	ds_read_b128 v[228:231], v155 offset:37888
	ds_read_b128 v[232:235], v155 offset:38912
	ds_read_b128 v[236:239], v155 offset:39936
	s_add_i32 s4, 0, 0x18000
	s_add_i32 s5, 0, 0x1c000
	s_add_u32 s64, s64, 0x40000
	s_addc_u32 s65, s65, 0
	s_mov_b32 m0, s70
	v_lshl_add_u64 v[246:247], s[64:65], 0, v[132:133]
	global_load_lds_dwordx4 v[246:247], off
	v_lshl_add_u64 v[246:247], s[64:65], 0, v[130:131]
	s_mov_b32 m0, s71
	s_nop 0
	global_load_lds_dwordx4 v[246:247], off
	s_waitcnt vmcnt(8)
	s_waitcnt lgkmcnt(0)
	s_barrier
	s_waitcnt lgkmcnt(0)
	v_mfma_f32_16x16x32_bf16 v[124:127], v[138:141], v[208:211], v[124:127]
	v_mfma_f32_16x16x32_bf16 v[120:123], v[160:163], v[208:211], v[120:123]
	v_mfma_f32_16x16x32_bf16 v[108:111], v[138:141], v[216:219], v[108:111]
	v_mfma_f32_16x16x32_bf16 v[104:107], v[160:163], v[216:219], v[104:107]
	v_mfma_f32_16x16x32_bf16 v[92:95], v[138:141], v[224:227], v[92:95]
	v_mfma_f32_16x16x32_bf16 v[88:91], v[160:163], v[224:227], v[88:91]
	v_mfma_f32_16x16x32_bf16 v[76:79], v[138:141], v[232:235], v[76:79]
	v_mfma_f32_16x16x32_bf16 v[72:75], v[160:163], v[232:235], v[72:75]
	v_mfma_f32_16x16x32_bf16 v[124:127], v[156:159], v[212:215], v[124:127]
	v_mfma_f32_16x16x32_bf16 v[120:123], v[164:167], v[212:215], v[120:123]
	v_mfma_f32_16x16x32_bf16 v[108:111], v[156:159], v[220:223], v[108:111]
	v_mfma_f32_16x16x32_bf16 v[104:107], v[164:167], v[220:223], v[104:107]
	v_mfma_f32_16x16x32_bf16 v[92:95], v[156:159], v[228:231], v[92:95]
	v_mfma_f32_16x16x32_bf16 v[88:91], v[164:167], v[228:231], v[88:91]
	v_mfma_f32_16x16x32_bf16 v[76:79], v[156:159], v[236:239], v[76:79]
	v_mfma_f32_16x16x32_bf16 v[72:75], v[164:167], v[236:239], v[72:75]
	v_mfma_f32_16x16x32_bf16 v[116:119], v[168:171], v[208:211], v[116:119]
	v_mfma_f32_16x16x32_bf16 v[112:115], v[176:179], v[208:211], v[112:115]
	v_mfma_f32_16x16x32_bf16 v[100:103], v[168:171], v[216:219], v[100:103]
	v_mfma_f32_16x16x32_bf16 v[96:99], v[176:179], v[216:219], v[96:99]
	v_mfma_f32_16x16x32_bf16 v[84:87], v[168:171], v[224:227], v[84:87]
	v_mfma_f32_16x16x32_bf16 v[80:83], v[176:179], v[224:227], v[80:83]
	v_mfma_f32_16x16x32_bf16 v[68:71], v[168:171], v[232:235], v[68:71]
	v_mfma_f32_16x16x32_bf16 v[64:67], v[176:179], v[232:235], v[64:67]
	v_mfma_f32_16x16x32_bf16 v[116:119], v[172:175], v[212:215], v[116:119]
	v_mfma_f32_16x16x32_bf16 v[112:115], v[204:207], v[212:215], v[112:115]
	v_mfma_f32_16x16x32_bf16 v[100:103], v[172:175], v[220:223], v[100:103]
	v_mfma_f32_16x16x32_bf16 v[96:99], v[204:207], v[220:223], v[96:99]
	v_mfma_f32_16x16x32_bf16 v[84:87], v[172:175], v[228:231], v[84:87]
	v_mfma_f32_16x16x32_bf16 v[80:83], v[204:207], v[228:231], v[80:83]
	v_mfma_f32_16x16x32_bf16 v[68:71], v[172:175], v[236:239], v[68:71]
	v_mfma_f32_16x16x32_bf16 v[64:67], v[204:207], v[236:239], v[64:67]
	s_barrier
	s_add_i32 s4, s4, s28
	v_lshl_add_u64 v[180:181], v[180:181], 0, s[26:27]
	s_mov_b32 m0, s4
	ds_read_b128 v[208:211], v155 offset:49152
	ds_read_b128 v[212:215], v155 offset:50176
	ds_read_b128 v[216:219], v155 offset:51200
	ds_read_b128 v[220:223], v155 offset:52224
	ds_read_b128 v[224:227], v155 offset:53248
	ds_read_b128 v[228:231], v155 offset:54272
	ds_read_b128 v[232:235], v155 offset:55296
	ds_read_b128 v[236:239], v155 offset:56320
	global_load_lds_dwordx4 v[180:181], off
	s_add_i32 m0, s4, 0x2000
	s_add_u32 s34, s34, 0x40080
	v_lshl_add_u64 v[180:181], v[240:241], 0, s[26:27]
	s_addc_u32 s35, s35, 0
	s_add_i32 s4, s5, s28
	global_load_lds_dwordx4 v[180:181], off
	v_lshl_add_u64 v[180:181], s[34:35], 0, v[144:145]
	s_mov_b32 m0, s4
	s_nop 0
	global_load_lds_dwordx4 v[180:181], off
	v_lshl_add_u64 v[180:181], s[34:35], 0, v[128:129]
	s_add_i32 m0, s4, 0x2000
	s_nop 0
	global_load_lds_dwordx4 v[180:181], off
	v_lshl_add_u64 v[180:181], v[242:243], 0, s[26:27]
	s_mov_b32 m0, s72
	s_nop 0
	global_load_lds_dwordx4 v[180:181], off
	v_lshl_add_u64 v[180:181], v[244:245], 0, s[26:27]
	s_mov_b32 m0, s73
	s_nop 0
	global_load_lds_dwordx4 v[180:181], off
	s_waitcnt vmcnt(8)
	s_waitcnt lgkmcnt(0)
	s_barrier
	s_waitcnt lgkmcnt(0)
	v_mfma_f32_16x16x32_bf16 v[60:63], v[138:141], v[208:211], v[60:63]
	v_mfma_f32_16x16x32_bf16 v[56:59], v[160:163], v[208:211], v[56:59]
	v_mfma_f32_16x16x32_bf16 v[44:47], v[138:141], v[216:219], v[44:47]
	v_mfma_f32_16x16x32_bf16 v[40:43], v[160:163], v[216:219], v[40:43]
	v_mfma_f32_16x16x32_bf16 v[28:31], v[138:141], v[224:227], v[28:31]
	v_mfma_f32_16x16x32_bf16 v[24:27], v[160:163], v[224:227], v[24:27]
	v_mfma_f32_16x16x32_bf16 v[12:15], v[138:141], v[232:235], v[12:15]
	v_mfma_f32_16x16x32_bf16 v[8:11], v[160:163], v[232:235], v[8:11]
	v_mfma_f32_16x16x32_bf16 v[60:63], v[156:159], v[212:215], v[60:63]
	v_mfma_f32_16x16x32_bf16 v[56:59], v[164:167], v[212:215], v[56:59]
	v_mfma_f32_16x16x32_bf16 v[44:47], v[156:159], v[220:223], v[44:47]
	v_mfma_f32_16x16x32_bf16 v[40:43], v[164:167], v[220:223], v[40:43]
	v_mfma_f32_16x16x32_bf16 v[28:31], v[156:159], v[228:231], v[28:31]
	v_mfma_f32_16x16x32_bf16 v[24:27], v[164:167], v[228:231], v[24:27]
	v_mfma_f32_16x16x32_bf16 v[12:15], v[156:159], v[236:239], v[12:15]
	v_mfma_f32_16x16x32_bf16 v[8:11], v[164:167], v[236:239], v[8:11]
	v_mfma_f32_16x16x32_bf16 v[52:55], v[168:171], v[208:211], v[52:55]
	v_mfma_f32_16x16x32_bf16 v[48:51], v[176:179], v[208:211], v[48:51]
	v_mfma_f32_16x16x32_bf16 v[36:39], v[168:171], v[216:219], v[36:39]
	v_mfma_f32_16x16x32_bf16 v[32:35], v[176:179], v[216:219], v[32:35]
	v_mfma_f32_16x16x32_bf16 v[20:23], v[168:171], v[224:227], v[20:23]
	v_mfma_f32_16x16x32_bf16 v[16:19], v[176:179], v[224:227], v[16:19]
	v_mfma_f32_16x16x32_bf16 v[4:7], v[168:171], v[232:235], v[4:7]
	v_mfma_f32_16x16x32_bf16 v[0:3], v[176:179], v[232:235], v[0:3]
	v_mfma_f32_16x16x32_bf16 v[52:55], v[172:175], v[212:215], v[52:55]
	v_mfma_f32_16x16x32_bf16 v[48:51], v[204:207], v[212:215], v[48:51]
	v_mfma_f32_16x16x32_bf16 v[36:39], v[172:175], v[220:223], v[36:39]
	v_mfma_f32_16x16x32_bf16 v[32:35], v[204:207], v[220:223], v[32:35]
	v_mfma_f32_16x16x32_bf16 v[20:23], v[172:175], v[228:231], v[20:23]
	v_mfma_f32_16x16x32_bf16 v[16:19], v[204:207], v[228:231], v[16:19]
	v_mfma_f32_16x16x32_bf16 v[4:7], v[172:175], v[236:239], v[4:7]
	v_mfma_f32_16x16x32_bf16 v[0:3], v[204:207], v[236:239], v[0:3]
	s_barrier
	s_add_i32 s82, s82, 2
	s_add_u32 s62, s62, 0x100
	s_addc_u32 s63, s63, 0
	s_add_u32 s75, s75, 0x100
	s_addc_u32 s79, s79, 0
	s_cmp_gt_u32 s82, 13
	s_cbranch_scc0 .LBB0_311
	s_setprio 0
	v_lshl_add_u32 v140, s2, 8, v142
	v_ashrrev_i32_e32 v141, 31, v140
	v_lshl_add_u64 v[156:157], v[140:141], 4, s[48:49]
	global_load_dwordx4 v[208:211], v[156:157], off
	global_load_dwordx4 v[212:215], v[156:157], off offset:256
	global_load_dwordx4 v[216:219], v[156:157], off offset:512
	global_load_dwordx4 v[220:223], v[156:157], off offset:768
	global_load_dwordx4 v[224:227], v[156:157], off offset:2048
	global_load_dwordx4 v[228:231], v[156:157], off offset:2304
	global_load_dwordx4 v[232:235], v[156:157], off offset:2560
	global_load_dwordx4 v[236:239], v[156:157], off offset:2816
	s_and_b64 vcc, exec, s[50:51]
	s_cbranch_vccz .LBB0_314
	s_barrier

.Lkprio_406:
.LBB0_406:
	v_add_u32_e32 v142, 0x10000, v160
	ds_read_b128 v[138:141], v142
	ds_read_b128 v[154:157], v142 offset:1024
	ds_read_b128 v[172:175], v142 offset:2048
	ds_read_b128 v[176:179], v142 offset:3072
	v_add_u32_e32 v142, 0x14000, v160
	ds_read_b128 v[204:207], v142
	ds_read_b128 v[208:211], v142 offset:1024
	ds_read_b128 v[212:215], v142 offset:2048
	ds_read_b128 v[216:219], v142 offset:3072
	ds_read_b128 v[220:223], v170
	ds_read_b128 v[224:227], v170 offset:1024
	ds_read_b128 v[228:231], v170 offset:2048
	ds_read_b128 v[232:235], v170 offset:3072
	ds_read_b128 v[236:239], v170 offset:4096
	ds_read_b128 v[240:243], v170 offset:5120
	ds_read_b128 v[244:247], v170 offset:6144
	ds_read_b128 v[248:251], v170 offset:7168
	s_add_u32 s62, s60, 0x100
	s_addc_u32 s63, s61, 0
	s_add_i32 s4, 0, 0x10000
	s_cmp_eq_u32 s29, 40
	s_cselect_b32 s65, s45, s63
	s_cselect_b32 s64, s44, s62
	s_cselect_b32 s35, s59, s28
	s_cselect_b32 s34, s58, s3
	s_add_i32 s5, 0, 0x14000
	v_lshl_add_u64 v[142:143], s[60:61], 0, v[134:135]
	s_add_i32 m0, s36, 0xc000
	s_nop 0
	global_load_lds_dwordx4 v[142:143], off
	v_lshl_add_u64 v[142:143], s[60:61], 0, v[136:137]
	s_add_i32 m0, s36, 0xe000
	s_nop 0
	global_load_lds_dwordx4 v[142:143], off
	s_waitcnt vmcnt(8)
	s_waitcnt lgkmcnt(0)
	s_barrier
	s_waitcnt lgkmcnt(0)
	v_mfma_f32_16x16x32_bf16 v[124:127], v[138:141], v[220:223], v[124:127]
	v_mfma_f32_16x16x32_bf16 v[120:123], v[172:175], v[220:223], v[120:123]
	v_mfma_f32_16x16x32_bf16 v[108:111], v[138:141], v[228:231], v[108:111]
	v_mfma_f32_16x16x32_bf16 v[104:107], v[172:175], v[228:231], v[104:107]
	v_mfma_f32_16x16x32_bf16 v[92:95], v[138:141], v[236:239], v[92:95]
	v_mfma_f32_16x16x32_bf16 v[88:91], v[172:175], v[236:239], v[88:91]
	v_mfma_f32_16x16x32_bf16 v[76:79], v[138:141], v[244:247], v[76:79]
	v_mfma_f32_16x16x32_bf16 v[72:75], v[172:175], v[244:247], v[72:75]
	v_mfma_f32_16x16x32_bf16 v[124:127], v[154:157], v[224:227], v[124:127]
	v_mfma_f32_16x16x32_bf16 v[120:123], v[176:179], v[224:227], v[120:123]
	v_mfma_f32_16x16x32_bf16 v[108:111], v[154:157], v[232:235], v[108:111]
	v_mfma_f32_16x16x32_bf16 v[104:107], v[176:179], v[232:235], v[104:107]
	v_mfma_f32_16x16x32_bf16 v[92:95], v[154:157], v[240:243], v[92:95]
	v_mfma_f32_16x16x32_bf16 v[88:91], v[176:179], v[240:243], v[88:91]
	v_mfma_f32_16x16x32_bf16 v[76:79], v[154:157], v[248:251], v[76:79]
	v_mfma_f32_16x16x32_bf16 v[72:75], v[176:179], v[248:251], v[72:75]
	v_mfma_f32_16x16x32_bf16 v[116:119], v[204:207], v[220:223], v[116:119]
	v_mfma_f32_16x16x32_bf16 v[112:115], v[212:215], v[220:223], v[112:115]
	v_mfma_f32_16x16x32_bf16 v[100:103], v[204:207], v[228:231], v[100:103]
	v_mfma_f32_16x16x32_bf16 v[96:99], v[212:215], v[228:231], v[96:99]
	v_mfma_f32_16x16x32_bf16 v[84:87], v[204:207], v[236:239], v[84:87]
	v_mfma_f32_16x16x32_bf16 v[80:83], v[212:215], v[236:239], v[80:83]
	v_mfma_f32_16x16x32_bf16 v[68:71], v[204:207], v[244:247], v[68:71]
	v_mfma_f32_16x16x32_bf16 v[64:67], v[212:215], v[244:247], v[64:67]
	v_mfma_f32_16x16x32_bf16 v[116:119], v[208:211], v[224:227], v[116:119]
	v_mfma_f32_16x16x32_bf16 v[112:115], v[216:219], v[224:227], v[112:115]
	v_mfma_f32_16x16x32_bf16 v[100:103], v[208:211], v[232:235], v[100:103]
	v_mfma_f32_16x16x32_bf16 v[96:99], v[216:219], v[232:235], v[96:99]
	v_mfma_f32_16x16x32_bf16 v[84:87], v[208:211], v[240:243], v[84:87]
	v_mfma_f32_16x16x32_bf16 v[80:83], v[216:219], v[240:243], v[80:83]
	v_mfma_f32_16x16x32_bf16 v[68:71], v[208:211], v[248:251], v[68:71]
	v_mfma_f32_16x16x32_bf16 v[64:67], v[216:219], v[248:251], v[64:67]
	s_barrier
	s_add_i32 s4, s4, s33
	v_lshl_add_u64 v[142:143], s[34:35], 0, v[128:129]
	s_mov_b32 m0, s4
	ds_read_b128 v[220:223], v170 offset:16384
	ds_read_b128 v[224:227], v170 offset:17408
	ds_read_b128 v[228:231], v170 offset:18432
	ds_read_b128 v[232:235], v170 offset:19456
	ds_read_b128 v[236:239], v170 offset:20480
	ds_read_b128 v[240:243], v170 offset:21504
	ds_read_b128 v[244:247], v170 offset:22528
	ds_read_b128 v[248:251], v170 offset:23552
	global_load_lds_dwordx4 v[142:143], off
	s_add_i32 m0, s4, 0x2000
	s_add_u32 s60, s34, 0xb0000
	v_lshl_add_u64 v[158:159], s[34:35], 0, v[130:131]
	s_addc_u32 s61, s35, 0
	s_add_i32 s4, s5, s33
	global_load_lds_dwordx4 v[158:159], off
	v_lshl_add_u64 v[180:181], s[60:61], 0, v[128:129]
	s_mov_b32 m0, s4
	v_lshl_add_u64 v[202:203], s[64:65], 0, v[130:131]
	global_load_lds_dwordx4 v[180:181], off
	v_lshl_add_u64 v[180:181], s[60:61], 0, v[130:131]
	s_add_i32 m0, s4, 0x2000
	s_nop 0
	global_load_lds_dwordx4 v[180:181], off
	v_lshl_add_u64 v[180:181], s[64:65], 0, v[128:129]
	s_mov_b32 m0, s36
	s_nop 0
	global_load_lds_dwordx4 v[180:181], off
	s_mov_b32 m0, s70
	s_nop 0
	global_load_lds_dwordx4 v[202:203], off
	s_waitcnt vmcnt(8)
	s_waitcnt lgkmcnt(0)
	s_barrier
	s_waitcnt lgkmcnt(0)
	v_mfma_f32_16x16x32_bf16 v[60:63], v[138:141], v[220:223], v[60:63]
	v_mfma_f32_16x16x32_bf16 v[56:59], v[172:175], v[220:223], v[56:59]
	v_mfma_f32_16x16x32_bf16 v[44:47], v[138:141], v[228:231], v[44:47]
	v_mfma_f32_16x16x32_bf16 v[40:43], v[172:175], v[228:231], v[40:43]
	v_mfma_f32_16x16x32_bf16 v[28:31], v[138:141], v[236:239], v[28:31]
	v_mfma_f32_16x16x32_bf16 v[24:27], v[172:175], v[236:239], v[24:27]
	v_mfma_f32_16x16x32_bf16 v[12:15], v[138:141], v[244:247], v[12:15]
	v_mfma_f32_16x16x32_bf16 v[8:11], v[172:175], v[244:247], v[8:11]
	v_mfma_f32_16x16x32_bf16 v[60:63], v[154:157], v[224:227], v[60:63]
	v_mfma_f32_16x16x32_bf16 v[56:59], v[176:179], v[224:227], v[56:59]
	v_mfma_f32_16x16x32_bf16 v[44:47], v[154:157], v[232:235], v[44:47]
	v_mfma_f32_16x16x32_bf16 v[40:43], v[176:179], v[232:235], v[40:43]
	v_mfma_f32_16x16x32_bf16 v[28:31], v[154:157], v[240:243], v[28:31]
	v_mfma_f32_16x16x32_bf16 v[24:27], v[176:179], v[240:243], v[24:27]
	v_mfma_f32_16x16x32_bf16 v[12:15], v[154:157], v[248:251], v[12:15]
	v_mfma_f32_16x16x32_bf16 v[8:11], v[176:179], v[248:251], v[8:11]
	v_mfma_f32_16x16x32_bf16 v[52:55], v[204:207], v[220:223], v[52:55]
	v_mfma_f32_16x16x32_bf16 v[48:51], v[212:215], v[220:223], v[48:51]
	v_mfma_f32_16x16x32_bf16 v[36:39], v[204:207], v[228:231], v[36:39]
	v_mfma_f32_16x16x32_bf16 v[32:35], v[212:215], v[228:231], v[32:35]
	v_mfma_f32_16x16x32_bf16 v[20:23], v[204:207], v[236:239], v[20:23]
	v_mfma_f32_16x16x32_bf16 v[16:19], v[212:215], v[236:239], v[16:19]
	v_mfma_f32_16x16x32_bf16 v[4:7], v[204:207], v[244:247], v[4:7]
	v_mfma_f32_16x16x32_bf16 v[0:3], v[212:215], v[244:247], v[0:3]
	v_mfma_f32_16x16x32_bf16 v[52:55], v[208:211], v[224:227], v[52:55]
	v_mfma_f32_16x16x32_bf16 v[48:51], v[216:219], v[224:227], v[48:51]
	v_mfma_f32_16x16x32_bf16 v[36:39], v[208:211], v[232:235], v[36:39]
	v_mfma_f32_16x16x32_bf16 v[32:35], v[216:219], v[232:235], v[32:35]
	v_mfma_f32_16x16x32_bf16 v[20:23], v[208:211], v[240:243], v[20:23]
	v_mfma_f32_16x16x32_bf16 v[16:19], v[216:219], v[240:243], v[16:19]
	v_mfma_f32_16x16x32_bf16 v[4:7], v[208:211], v[248:251], v[4:7]
	v_mfma_f32_16x16x32_bf16 v[0:3], v[216:219], v[248:251], v[0:3]
	s_barrier
	v_add_u32_e32 v144, 0x18000, v160
	ds_read_b128 v[138:141], v144
	ds_read_b128 v[154:157], v144 offset:1024
	ds_read_b128 v[172:175], v144 offset:2048
	ds_read_b128 v[176:179], v144 offset:3072
	v_add_u32_e32 v144, 0x1c000, v160
	ds_read_b128 v[204:207], v144
	ds_read_b128 v[208:211], v144 offset:1024
	ds_read_b128 v[212:215], v144 offset:2048
	ds_read_b128 v[216:219], v144 offset:3072
	ds_read_b128 v[220:223], v170 offset:32768
	ds_read_b128 v[224:227], v170 offset:33792
	ds_read_b128 v[228:231], v170 offset:34816
	ds_read_b128 v[232:235], v170 offset:35840
	ds_read_b128 v[236:239], v170 offset:36864
	ds_read_b128 v[240:243], v170 offset:37888
	ds_read_b128 v[244:247], v170 offset:38912
	ds_read_b128 v[248:251], v170 offset:39936
	s_add_i32 s4, 0, 0x18000
	s_add_i32 s5, 0, 0x1c000
	s_add_u32 s60, s64, 0xb0000
	s_addc_u32 s61, s65, 0
	s_mov_b32 m0, s71
	v_lshl_add_u64 v[252:253], s[60:61], 0, v[128:129]
	global_load_lds_dwordx4 v[252:253], off
	v_lshl_add_u64 v[252:253], s[60:61], 0, v[130:131]
	s_mov_b32 m0, s72
	s_nop 0
	global_load_lds_dwordx4 v[252:253], off
	s_waitcnt vmcnt(8)
	s_waitcnt lgkmcnt(0)
	s_barrier
	s_waitcnt lgkmcnt(0)
	v_mfma_f32_16x16x32_bf16 v[124:127], v[138:141], v[220:223], v[124:127]
	v_mfma_f32_16x16x32_bf16 v[120:123], v[172:175], v[220:223], v[120:123]
	v_mfma_f32_16x16x32_bf16 v[108:111], v[138:141], v[228:231], v[108:111]
	v_mfma_f32_16x16x32_bf16 v[104:107], v[172:175], v[228:231], v[104:107]
	v_mfma_f32_16x16x32_bf16 v[92:95], v[138:141], v[236:239], v[92:95]
	v_mfma_f32_16x16x32_bf16 v[88:91], v[172:175], v[236:239], v[88:91]
	v_mfma_f32_16x16x32_bf16 v[76:79], v[138:141], v[244:247], v[76:79]
	v_mfma_f32_16x16x32_bf16 v[72:75], v[172:175], v[244:247], v[72:75]
	v_mfma_f32_16x16x32_bf16 v[124:127], v[154:157], v[224:227], v[124:127]
	v_mfma_f32_16x16x32_bf16 v[120:123], v[176:179], v[224:227], v[120:123]
	v_mfma_f32_16x16x32_bf16 v[108:111], v[154:157], v[232:235], v[108:111]
	v_mfma_f32_16x16x32_bf16 v[104:107], v[176:179], v[232:235], v[104:107]
	v_mfma_f32_16x16x32_bf16 v[92:95], v[154:157], v[240:243], v[92:95]
	v_mfma_f32_16x16x32_bf16 v[88:91], v[176:179], v[240:243], v[88:91]
	v_mfma_f32_16x16x32_bf16 v[76:79], v[154:157], v[248:251], v[76:79]
	v_mfma_f32_16x16x32_bf16 v[72:75], v[176:179], v[248:251], v[72:75]
	v_mfma_f32_16x16x32_bf16 v[116:119], v[204:207], v[220:223], v[116:119]
	v_mfma_f32_16x16x32_bf16 v[112:115], v[212:215], v[220:223], v[112:115]
	v_mfma_f32_16x16x32_bf16 v[100:103], v[204:207], v[228:231], v[100:103]
	v_mfma_f32_16x16x32_bf16 v[96:99], v[212:215], v[228:231], v[96:99]
	v_mfma_f32_16x16x32_bf16 v[84:87], v[204:207], v[236:239], v[84:87]
	v_mfma_f32_16x16x32_bf16 v[80:83], v[212:215], v[236:239], v[80:83]
	v_mfma_f32_16x16x32_bf16 v[68:71], v[204:207], v[244:247], v[68:71]
	v_mfma_f32_16x16x32_bf16 v[64:67], v[212:215], v[244:247], v[64:67]
	v_mfma_f32_16x16x32_bf16 v[116:119], v[208:211], v[224:227], v[116:119]
	v_mfma_f32_16x16x32_bf16 v[112:115], v[216:219], v[224:227], v[112:115]
	v_mfma_f32_16x16x32_bf16 v[100:103], v[208:211], v[232:235], v[100:103]
	v_mfma_f32_16x16x32_bf16 v[96:99], v[216:219], v[232:235], v[96:99]
	v_mfma_f32_16x16x32_bf16 v[84:87], v[208:211], v[240:243], v[84:87]
	v_mfma_f32_16x16x32_bf16 v[80:83], v[216:219], v[240:243], v[80:83]
	v_mfma_f32_16x16x32_bf16 v[68:71], v[208:211], v[248:251], v[68:71]
	v_mfma_f32_16x16x32_bf16 v[64:67], v[216:219], v[248:251], v[64:67]
	s_barrier
	s_add_i32 s4, s4, s33
	v_lshl_add_u64 v[142:143], v[142:143], 0, s[26:27]
	s_mov_b32 m0, s4
	ds_read_b128 v[220:223], v170 offset:49152
	ds_read_b128 v[224:227], v170 offset:50176
	ds_read_b128 v[228:231], v170 offset:51200
	ds_read_b128 v[232:235], v170 offset:52224
	ds_read_b128 v[236:239], v170 offset:53248
	ds_read_b128 v[240:243], v170 offset:54272
	ds_read_b128 v[244:247], v170 offset:55296
	ds_read_b128 v[248:251], v170 offset:56320
	global_load_lds_dwordx4 v[142:143], off
	s_add_i32 m0, s4, 0x2000
	s_add_u32 s34, s34, 0xb0080
	v_lshl_add_u64 v[142:143], v[158:159], 0, s[26:27]
	s_addc_u32 s35, s35, 0
	s_add_i32 s4, s5, s33
	global_load_lds_dwordx4 v[142:143], off
	v_lshl_add_u64 v[142:143], s[34:35], 0, v[128:129]
	s_mov_b32 m0, s4
	s_nop 0
	global_load_lds_dwordx4 v[142:143], off
	v_lshl_add_u64 v[142:143], s[34:35], 0, v[130:131]
	s_add_i32 m0, s4, 0x2000
	s_nop 0
	global_load_lds_dwordx4 v[142:143], off
	v_lshl_add_u64 v[142:143], v[180:181], 0, s[26:27]
	s_mov_b32 m0, s73
	s_nop 0
	global_load_lds_dwordx4 v[142:143], off
	v_lshl_add_u64 v[142:143], v[202:203], 0, s[26:27]
	s_mov_b32 m0, s74
	s_nop 0
	global_load_lds_dwordx4 v[142:143], off
	s_waitcnt vmcnt(8)
	s_waitcnt lgkmcnt(0)
	s_barrier
	s_waitcnt lgkmcnt(0)
	v_mfma_f32_16x16x32_bf16 v[60:63], v[138:141], v[220:223], v[60:63]
	v_mfma_f32_16x16x32_bf16 v[56:59], v[172:175], v[220:223], v[56:59]
	v_mfma_f32_16x16x32_bf16 v[44:47], v[138:141], v[228:231], v[44:47]
	v_mfma_f32_16x16x32_bf16 v[40:43], v[172:175], v[228:231], v[40:43]
	v_mfma_f32_16x16x32_bf16 v[28:31], v[138:141], v[236:239], v[28:31]
	v_mfma_f32_16x16x32_bf16 v[24:27], v[172:175], v[236:239], v[24:27]
	v_mfma_f32_16x16x32_bf16 v[12:15], v[138:141], v[244:247], v[12:15]
	v_mfma_f32_16x16x32_bf16 v[8:11], v[172:175], v[244:247], v[8:11]
	v_mfma_f32_16x16x32_bf16 v[60:63], v[154:157], v[224:227], v[60:63]
	v_mfma_f32_16x16x32_bf16 v[56:59], v[176:179], v[224:227], v[56:59]
	v_mfma_f32_16x16x32_bf16 v[44:47], v[154:157], v[232:235], v[44:47]
	v_mfma_f32_16x16x32_bf16 v[40:43], v[176:179], v[232:235], v[40:43]
	v_mfma_f32_16x16x32_bf16 v[28:31], v[154:157], v[240:243], v[28:31]
	v_mfma_f32_16x16x32_bf16 v[24:27], v[176:179], v[240:243], v[24:27]
	v_mfma_f32_16x16x32_bf16 v[12:15], v[154:157], v[248:251], v[12:15]
	v_mfma_f32_16x16x32_bf16 v[8:11], v[176:179], v[248:251], v[8:11]
	v_mfma_f32_16x16x32_bf16 v[52:55], v[204:207], v[220:223], v[52:55]
	v_mfma_f32_16x16x32_bf16 v[48:51], v[212:215], v[220:223], v[48:51]
	v_mfma_f32_16x16x32_bf16 v[36:39], v[204:207], v[228:231], v[36:39]
	v_mfma_f32_16x16x32_bf16 v[32:35], v[212:215], v[228:231], v[32:35]
	v_mfma_f32_16x16x32_bf16 v[20:23], v[204:207], v[236:239], v[20:23]
	v_mfma_f32_16x16x32_bf16 v[16:19], v[212:215], v[236:239], v[16:19]
	v_mfma_f32_16x16x32_bf16 v[4:7], v[204:207], v[244:247], v[4:7]
	v_mfma_f32_16x16x32_bf16 v[0:3], v[212:215], v[244:247], v[0:3]
	v_mfma_f32_16x16x32_bf16 v[52:55], v[208:211], v[224:227], v[52:55]
	v_mfma_f32_16x16x32_bf16 v[48:51], v[216:219], v[224:227], v[48:51]
	v_mfma_f32_16x16x32_bf16 v[36:39], v[208:211], v[232:235], v[36:39]
	v_mfma_f32_16x16x32_bf16 v[32:35], v[216:219], v[232:235], v[32:35]
	v_mfma_f32_16x16x32_bf16 v[20:23], v[208:211], v[240:243], v[20:23]
	v_mfma_f32_16x16x32_bf16 v[16:19], v[216:219], v[240:243], v[16:19]
	v_mfma_f32_16x16x32_bf16 v[4:7], v[208:211], v[248:251], v[4:7]
	v_mfma_f32_16x16x32_bf16 v[0:3], v[216:219], v[248:251], v[0:3]
	s_barrier
	s_add_i32 s29, s29, 2
	s_add_u32 s3, s3, 0x100
	s_addc_u32 s28, s28, 0
	s_cmp_gt_u32 s29, 41
	s_mov_b64 s[60:61], s[62:63]
	s_cbranch_scc0 .LBB0_406
	s_setprio 0
	s_and_b64 vcc, exec, s[54:55]
	s_cbranch_vccz .LBB0_409
	s_barrier

.Lkprio_456:
.LBB0_456:
	v_add_u32_e32 v140, 0x10000, v166
	v_add_u32_e32 v144, 0x14000, v166
	ds_read_b128 v[128:131], v140
	ds_read_b128 v[132:135], v140 offset:1024
	ds_read_b128 v[136:139], v140 offset:2048
	ds_read_b128 v[140:143], v140 offset:3072
	ds_read_b128 v[178:181], v144
	ds_read_b128 v[204:207], v144 offset:1024
	ds_read_b128 v[208:211], v144 offset:2048
	ds_read_b128 v[212:215], v144 offset:3072
	ds_read_b128 v[216:219], v176
	ds_read_b128 v[220:223], v176 offset:1024
	ds_read_b128 v[224:227], v176 offset:2048
	ds_read_b128 v[228:231], v176 offset:3072
	ds_read_b128 v[232:235], v176 offset:4096
	ds_read_b128 v[236:239], v176 offset:5120
	ds_read_b128 v[240:243], v176 offset:6144
	ds_read_b128 v[244:247], v176 offset:7168
	s_add_u32 s60, s58, 0x100
	s_addc_u32 s61, s59, 0
	s_add_i32 s4, 0, 0x10000
	s_cmp_eq_u32 s51, 40
	s_cselect_b32 s63, s45, s61
	s_cselect_b32 s62, s44, s60
	s_cselect_b32 s35, s47, s29
	s_cselect_b32 s34, s46, s28
	s_add_i32 s5, 0, 0x14000
	v_lshl_add_u64 v[164:165], s[58:59], 0, v[160:161]
	s_add_i32 m0, s36, 0xc000
	s_nop 0
	global_load_lds_dwordx4 v[164:165], off
	v_lshl_add_u64 v[164:165], s[58:59], 0, v[162:163]
	s_add_i32 m0, s36, 0xe000
	s_nop 0
	global_load_lds_dwordx4 v[164:165], off
	s_waitcnt vmcnt(8)
	s_waitcnt lgkmcnt(0)
	s_barrier
	s_waitcnt lgkmcnt(0)
	v_mfma_f32_16x16x32_bf16 v[124:127], v[128:131], v[216:219], v[124:127]
	v_mfma_f32_16x16x32_bf16 v[120:123], v[136:139], v[216:219], v[120:123]
	v_mfma_f32_16x16x32_bf16 v[108:111], v[128:131], v[224:227], v[108:111]
	v_mfma_f32_16x16x32_bf16 v[104:107], v[136:139], v[224:227], v[104:107]
	v_mfma_f32_16x16x32_bf16 v[92:95], v[128:131], v[232:235], v[92:95]
	v_mfma_f32_16x16x32_bf16 v[88:91], v[136:139], v[232:235], v[88:91]
	v_mfma_f32_16x16x32_bf16 v[76:79], v[128:131], v[240:243], v[76:79]
	v_mfma_f32_16x16x32_bf16 v[72:75], v[136:139], v[240:243], v[72:75]
	v_mfma_f32_16x16x32_bf16 v[124:127], v[132:135], v[220:223], v[124:127]
	v_mfma_f32_16x16x32_bf16 v[120:123], v[140:143], v[220:223], v[120:123]
	v_mfma_f32_16x16x32_bf16 v[108:111], v[132:135], v[228:231], v[108:111]
	v_mfma_f32_16x16x32_bf16 v[104:107], v[140:143], v[228:231], v[104:107]
	v_mfma_f32_16x16x32_bf16 v[92:95], v[132:135], v[236:239], v[92:95]
	v_mfma_f32_16x16x32_bf16 v[88:91], v[140:143], v[236:239], v[88:91]
	v_mfma_f32_16x16x32_bf16 v[76:79], v[132:135], v[244:247], v[76:79]
	v_mfma_f32_16x16x32_bf16 v[72:75], v[140:143], v[244:247], v[72:75]
	v_mfma_f32_16x16x32_bf16 v[116:119], v[178:181], v[216:219], v[116:119]
	v_mfma_f32_16x16x32_bf16 v[112:115], v[208:211], v[216:219], v[112:115]
	v_mfma_f32_16x16x32_bf16 v[100:103], v[178:181], v[224:227], v[100:103]
	v_mfma_f32_16x16x32_bf16 v[96:99], v[208:211], v[224:227], v[96:99]
	v_mfma_f32_16x16x32_bf16 v[84:87], v[178:181], v[232:235], v[84:87]
	v_mfma_f32_16x16x32_bf16 v[80:83], v[208:211], v[232:235], v[80:83]
	v_mfma_f32_16x16x32_bf16 v[68:71], v[178:181], v[240:243], v[68:71]
	v_mfma_f32_16x16x32_bf16 v[64:67], v[208:211], v[240:243], v[64:67]
	v_mfma_f32_16x16x32_bf16 v[116:119], v[204:207], v[220:223], v[116:119]
	v_mfma_f32_16x16x32_bf16 v[112:115], v[212:215], v[220:223], v[112:115]
	v_mfma_f32_16x16x32_bf16 v[100:103], v[204:207], v[228:231], v[100:103]
	v_mfma_f32_16x16x32_bf16 v[96:99], v[212:215], v[228:231], v[96:99]
	v_mfma_f32_16x16x32_bf16 v[84:87], v[204:207], v[236:239], v[84:87]
	v_mfma_f32_16x16x32_bf16 v[80:83], v[212:215], v[236:239], v[80:83]
	v_mfma_f32_16x16x32_bf16 v[68:71], v[204:207], v[244:247], v[68:71]
	v_mfma_f32_16x16x32_bf16 v[64:67], v[212:215], v[244:247], v[64:67]
	s_barrier
	s_add_i32 s4, s4, s33
	v_lshl_add_u64 v[164:165], s[34:35], 0, v[154:155]
	s_mov_b32 m0, s4
	ds_read_b128 v[216:219], v176 offset:16384
	ds_read_b128 v[220:223], v176 offset:17408
	ds_read_b128 v[224:227], v176 offset:18432
	ds_read_b128 v[228:231], v176 offset:19456
	ds_read_b128 v[232:235], v176 offset:20480
	ds_read_b128 v[236:239], v176 offset:21504
	ds_read_b128 v[240:243], v176 offset:22528
	ds_read_b128 v[244:247], v176 offset:23552
	global_load_lds_dwordx4 v[164:165], off
	s_add_i32 m0, s4, 0x2000
	s_add_u32 s58, s34, 0xb0000
	v_lshl_add_u64 v[248:249], s[34:35], 0, v[156:157]
	s_addc_u32 s59, s35, 0
	s_add_i32 s4, s5, s33
	global_load_lds_dwordx4 v[248:249], off
	v_lshl_add_u64 v[250:251], s[58:59], 0, v[154:155]
	s_mov_b32 m0, s4
	v_lshl_add_u64 v[252:253], s[62:63], 0, v[156:157]
	global_load_lds_dwordx4 v[250:251], off
	v_lshl_add_u64 v[250:251], s[58:59], 0, v[156:157]
	s_add_i32 m0, s4, 0x2000
	s_nop 0
	global_load_lds_dwordx4 v[250:251], off
	v_lshl_add_u64 v[250:251], s[62:63], 0, v[154:155]
	s_mov_b32 m0, s36
	s_nop 0
	global_load_lds_dwordx4 v[250:251], off
	s_mov_b32 m0, s64
	s_nop 0
	global_load_lds_dwordx4 v[252:253], off
	s_waitcnt vmcnt(8)
	s_waitcnt lgkmcnt(0)
	s_barrier
	s_waitcnt lgkmcnt(0)
	v_mfma_f32_16x16x32_bf16 v[60:63], v[128:131], v[216:219], v[60:63]
	v_mfma_f32_16x16x32_bf16 v[56:59], v[136:139], v[216:219], v[56:59]
	v_mfma_f32_16x16x32_bf16 v[44:47], v[128:131], v[224:227], v[44:47]
	v_mfma_f32_16x16x32_bf16 v[40:43], v[136:139], v[224:227], v[40:43]
	v_mfma_f32_16x16x32_bf16 v[28:31], v[128:131], v[232:235], v[28:31]
	v_mfma_f32_16x16x32_bf16 v[24:27], v[136:139], v[232:235], v[24:27]
	v_mfma_f32_16x16x32_bf16 v[12:15], v[128:131], v[240:243], v[12:15]
	v_mfma_f32_16x16x32_bf16 v[8:11], v[136:139], v[240:243], v[8:11]
	v_mfma_f32_16x16x32_bf16 v[60:63], v[132:135], v[220:223], v[60:63]
	v_mfma_f32_16x16x32_bf16 v[56:59], v[140:143], v[220:223], v[56:59]
	v_mfma_f32_16x16x32_bf16 v[44:47], v[132:135], v[228:231], v[44:47]
	v_mfma_f32_16x16x32_bf16 v[40:43], v[140:143], v[228:231], v[40:43]
	v_mfma_f32_16x16x32_bf16 v[28:31], v[132:135], v[236:239], v[28:31]
	v_mfma_f32_16x16x32_bf16 v[24:27], v[140:143], v[236:239], v[24:27]
	v_mfma_f32_16x16x32_bf16 v[12:15], v[132:135], v[244:247], v[12:15]
	v_mfma_f32_16x16x32_bf16 v[8:11], v[140:143], v[244:247], v[8:11]
	v_mfma_f32_16x16x32_bf16 v[52:55], v[178:181], v[216:219], v[52:55]
	v_mfma_f32_16x16x32_bf16 v[48:51], v[208:211], v[216:219], v[48:51]
	v_mfma_f32_16x16x32_bf16 v[36:39], v[178:181], v[224:227], v[36:39]
	v_mfma_f32_16x16x32_bf16 v[32:35], v[208:211], v[224:227], v[32:35]
	v_mfma_f32_16x16x32_bf16 v[20:23], v[178:181], v[232:235], v[20:23]
	v_mfma_f32_16x16x32_bf16 v[16:19], v[208:211], v[232:235], v[16:19]
	v_mfma_f32_16x16x32_bf16 v[4:7], v[178:181], v[240:243], v[4:7]
	v_mfma_f32_16x16x32_bf16 v[0:3], v[208:211], v[240:243], v[0:3]
	v_mfma_f32_16x16x32_bf16 v[52:55], v[204:207], v[220:223], v[52:55]
	v_mfma_f32_16x16x32_bf16 v[48:51], v[212:215], v[220:223], v[48:51]
	v_mfma_f32_16x16x32_bf16 v[36:39], v[204:207], v[228:231], v[36:39]
	v_mfma_f32_16x16x32_bf16 v[32:35], v[212:215], v[228:231], v[32:35]
	v_mfma_f32_16x16x32_bf16 v[20:23], v[204:207], v[236:239], v[20:23]
	v_mfma_f32_16x16x32_bf16 v[16:19], v[212:215], v[236:239], v[16:19]
	v_mfma_f32_16x16x32_bf16 v[4:7], v[204:207], v[244:247], v[4:7]
	v_mfma_f32_16x16x32_bf16 v[0:3], v[212:215], v[244:247], v[0:3]
	s_barrier
	v_add_u32_e32 v140, 0x18000, v166
	v_add_u32_e32 v144, 0x1c000, v166
	ds_read_b128 v[128:131], v140
	ds_read_b128 v[132:135], v140 offset:1024
	ds_read_b128 v[136:139], v140 offset:2048
	ds_read_b128 v[140:143], v140 offset:3072
	ds_read_b128 v[178:181], v144
	ds_read_b128 v[204:207], v144 offset:1024
	ds_read_b128 v[208:211], v144 offset:2048
	ds_read_b128 v[212:215], v144 offset:3072
	ds_read_b128 v[216:219], v176 offset:32768
	ds_read_b128 v[220:223], v176 offset:33792
	ds_read_b128 v[224:227], v176 offset:34816
	ds_read_b128 v[228:231], v176 offset:35840
	ds_read_b128 v[232:235], v176 offset:36864
	ds_read_b128 v[236:239], v176 offset:37888
	ds_read_b128 v[240:243], v176 offset:38912
	ds_read_b128 v[244:247], v176 offset:39936
	s_add_i32 s4, 0, 0x18000
	s_add_i32 s5, 0, 0x1c000
	s_add_u32 s58, s62, 0xb0000
	s_addc_u32 s59, s63, 0
	s_mov_b32 m0, s65
	v_lshl_add_u64 v[202:203], s[58:59], 0, v[154:155]
	global_load_lds_dwordx4 v[202:203], off
	v_lshl_add_u64 v[202:203], s[58:59], 0, v[156:157]
	s_mov_b32 m0, s70
	s_nop 0
	global_load_lds_dwordx4 v[202:203], off
	s_waitcnt vmcnt(8)
	s_waitcnt lgkmcnt(0)
	s_barrier
	s_waitcnt lgkmcnt(0)
	v_mfma_f32_16x16x32_bf16 v[124:127], v[128:131], v[216:219], v[124:127]
	v_mfma_f32_16x16x32_bf16 v[120:123], v[136:139], v[216:219], v[120:123]
	v_mfma_f32_16x16x32_bf16 v[108:111], v[128:131], v[224:227], v[108:111]
	v_mfma_f32_16x16x32_bf16 v[104:107], v[136:139], v[224:227], v[104:107]
	v_mfma_f32_16x16x32_bf16 v[92:95], v[128:131], v[232:235], v[92:95]
	v_mfma_f32_16x16x32_bf16 v[88:91], v[136:139], v[232:235], v[88:91]
	v_mfma_f32_16x16x32_bf16 v[76:79], v[128:131], v[240:243], v[76:79]
	v_mfma_f32_16x16x32_bf16 v[72:75], v[136:139], v[240:243], v[72:75]
	v_mfma_f32_16x16x32_bf16 v[124:127], v[132:135], v[220:223], v[124:127]
	v_mfma_f32_16x16x32_bf16 v[120:123], v[140:143], v[220:223], v[120:123]
	v_mfma_f32_16x16x32_bf16 v[108:111], v[132:135], v[228:231], v[108:111]
	v_mfma_f32_16x16x32_bf16 v[104:107], v[140:143], v[228:231], v[104:107]
	v_mfma_f32_16x16x32_bf16 v[92:95], v[132:135], v[236:239], v[92:95]
	v_mfma_f32_16x16x32_bf16 v[88:91], v[140:143], v[236:239], v[88:91]
	v_mfma_f32_16x16x32_bf16 v[76:79], v[132:135], v[244:247], v[76:79]
	v_mfma_f32_16x16x32_bf16 v[72:75], v[140:143], v[244:247], v[72:75]
	v_mfma_f32_16x16x32_bf16 v[116:119], v[178:181], v[216:219], v[116:119]
	v_mfma_f32_16x16x32_bf16 v[112:115], v[208:211], v[216:219], v[112:115]
	v_mfma_f32_16x16x32_bf16 v[100:103], v[178:181], v[224:227], v[100:103]
	v_mfma_f32_16x16x32_bf16 v[96:99], v[208:211], v[224:227], v[96:99]
	v_mfma_f32_16x16x32_bf16 v[84:87], v[178:181], v[232:235], v[84:87]
	v_mfma_f32_16x16x32_bf16 v[80:83], v[208:211], v[232:235], v[80:83]
	v_mfma_f32_16x16x32_bf16 v[68:71], v[178:181], v[240:243], v[68:71]
	v_mfma_f32_16x16x32_bf16 v[64:67], v[208:211], v[240:243], v[64:67]
	v_mfma_f32_16x16x32_bf16 v[116:119], v[204:207], v[220:223], v[116:119]
	v_mfma_f32_16x16x32_bf16 v[112:115], v[212:215], v[220:223], v[112:115]
	v_mfma_f32_16x16x32_bf16 v[100:103], v[204:207], v[228:231], v[100:103]
	v_mfma_f32_16x16x32_bf16 v[96:99], v[212:215], v[228:231], v[96:99]
	v_mfma_f32_16x16x32_bf16 v[84:87], v[204:207], v[236:239], v[84:87]
	v_mfma_f32_16x16x32_bf16 v[80:83], v[212:215], v[236:239], v[80:83]
	v_mfma_f32_16x16x32_bf16 v[68:71], v[204:207], v[244:247], v[68:71]
	v_mfma_f32_16x16x32_bf16 v[64:67], v[212:215], v[244:247], v[64:67]
	s_barrier
	s_add_i32 s4, s4, s33
	v_lshl_add_u64 v[164:165], v[164:165], 0, s[26:27]
	s_mov_b32 m0, s4
	ds_read_b128 v[216:219], v176 offset:49152
	ds_read_b128 v[220:223], v176 offset:50176
	ds_read_b128 v[224:227], v176 offset:51200
	ds_read_b128 v[228:231], v176 offset:52224
	ds_read_b128 v[232:235], v176 offset:53248
	ds_read_b128 v[236:239], v176 offset:54272
	ds_read_b128 v[240:243], v176 offset:55296
	ds_read_b128 v[244:247], v176 offset:56320
	global_load_lds_dwordx4 v[164:165], off
	s_add_i32 m0, s4, 0x2000
	s_add_u32 s34, s34, 0xb0080
	v_lshl_add_u64 v[164:165], v[248:249], 0, s[26:27]
	s_addc_u32 s35, s35, 0
	s_add_i32 s4, s5, s33
	global_load_lds_dwordx4 v[164:165], off
	v_lshl_add_u64 v[164:165], s[34:35], 0, v[154:155]
	s_mov_b32 m0, s4
	s_nop 0
	global_load_lds_dwordx4 v[164:165], off
	v_lshl_add_u64 v[164:165], s[34:35], 0, v[156:157]
	s_add_i32 m0, s4, 0x2000
	s_nop 0
	global_load_lds_dwordx4 v[164:165], off
	v_lshl_add_u64 v[164:165], v[250:251], 0, s[26:27]
	s_mov_b32 m0, s71
	s_nop 0
	global_load_lds_dwordx4 v[164:165], off
	v_lshl_add_u64 v[164:165], v[252:253], 0, s[26:27]
	s_mov_b32 m0, s72
	s_nop 0
	global_load_lds_dwordx4 v[164:165], off
	s_waitcnt vmcnt(8)
	s_waitcnt lgkmcnt(0)
	s_barrier
	s_waitcnt lgkmcnt(0)
	v_mfma_f32_16x16x32_bf16 v[60:63], v[128:131], v[216:219], v[60:63]
	v_mfma_f32_16x16x32_bf16 v[56:59], v[136:139], v[216:219], v[56:59]
	v_mfma_f32_16x16x32_bf16 v[44:47], v[128:131], v[224:227], v[44:47]
	v_mfma_f32_16x16x32_bf16 v[40:43], v[136:139], v[224:227], v[40:43]
	v_mfma_f32_16x16x32_bf16 v[28:31], v[128:131], v[232:235], v[28:31]
	v_mfma_f32_16x16x32_bf16 v[24:27], v[136:139], v[232:235], v[24:27]
	v_mfma_f32_16x16x32_bf16 v[12:15], v[128:131], v[240:243], v[12:15]
	v_mfma_f32_16x16x32_bf16 v[8:11], v[136:139], v[240:243], v[8:11]
	v_mfma_f32_16x16x32_bf16 v[60:63], v[132:135], v[220:223], v[60:63]
	v_mfma_f32_16x16x32_bf16 v[56:59], v[140:143], v[220:223], v[56:59]
	v_mfma_f32_16x16x32_bf16 v[44:47], v[132:135], v[228:231], v[44:47]
	v_mfma_f32_16x16x32_bf16 v[40:43], v[140:143], v[228:231], v[40:43]
	v_mfma_f32_16x16x32_bf16 v[28:31], v[132:135], v[236:239], v[28:31]
	v_mfma_f32_16x16x32_bf16 v[24:27], v[140:143], v[236:239], v[24:27]
	v_mfma_f32_16x16x32_bf16 v[12:15], v[132:135], v[244:247], v[12:15]
	v_mfma_f32_16x16x32_bf16 v[8:11], v[140:143], v[244:247], v[8:11]
	v_mfma_f32_16x16x32_bf16 v[52:55], v[178:181], v[216:219], v[52:55]
	v_mfma_f32_16x16x32_bf16 v[48:51], v[208:211], v[216:219], v[48:51]
	v_mfma_f32_16x16x32_bf16 v[36:39], v[178:181], v[224:227], v[36:39]
	v_mfma_f32_16x16x32_bf16 v[32:35], v[208:211], v[224:227], v[32:35]
	v_mfma_f32_16x16x32_bf16 v[20:23], v[178:181], v[232:235], v[20:23]
	v_mfma_f32_16x16x32_bf16 v[16:19], v[208:211], v[232:235], v[16:19]
	v_mfma_f32_16x16x32_bf16 v[4:7], v[178:181], v[240:243], v[4:7]
	v_mfma_f32_16x16x32_bf16 v[0:3], v[208:211], v[240:243], v[0:3]
	v_mfma_f32_16x16x32_bf16 v[52:55], v[204:207], v[220:223], v[52:55]
	v_mfma_f32_16x16x32_bf16 v[48:51], v[212:215], v[220:223], v[48:51]
	v_mfma_f32_16x16x32_bf16 v[36:39], v[204:207], v[228:231], v[36:39]
	v_mfma_f32_16x16x32_bf16 v[32:35], v[212:215], v[228:231], v[32:35]
	v_mfma_f32_16x16x32_bf16 v[20:23], v[204:207], v[236:239], v[20:23]
	v_mfma_f32_16x16x32_bf16 v[16:19], v[212:215], v[236:239], v[16:19]
	v_mfma_f32_16x16x32_bf16 v[4:7], v[204:207], v[244:247], v[4:7]
	v_mfma_f32_16x16x32_bf16 v[0:3], v[212:215], v[244:247], v[0:3]
	s_barrier
	s_add_i32 s51, s51, 2
	s_add_u32 s28, s28, 0x100
	s_addc_u32 s29, s29, 0
	s_cmp_gt_u32 s51, 41
	s_mov_b64 s[58:59], s[60:61]
	s_cbranch_scc0 .LBB0_456
	s_setprio 0
	s_and_b64 vcc, exec, s[54:55]
	s_cbranch_vccz .LBB0_459
	s_barrier

.Lkprio_605:
.LBB0_605:
	v_add_u32_e32 v140, 0x10000, v203
	v_add_u32_e32 v144, 0x14000, v203
	ds_read_b128 v[128:131], v140
	ds_read_b128 v[132:135], v140 offset:1024
	ds_read_b128 v[136:139], v140 offset:2048
	ds_read_b128 v[140:143], v140 offset:3072
	ds_read_b128 v[168:171], v144
	ds_read_b128 v[172:175], v144 offset:1024
	ds_read_b128 v[176:179], v144 offset:2048
	ds_read_b128 v[206:209], v144 offset:3072
	ds_read_b128 v[210:213], v205
	ds_read_b128 v[214:217], v205 offset:1024
	ds_read_b128 v[218:221], v205 offset:2048
	ds_read_b128 v[222:225], v205 offset:3072
	ds_read_b128 v[226:229], v205 offset:4096
	ds_read_b128 v[230:233], v205 offset:5120
	ds_read_b128 v[234:237], v205 offset:6144
	ds_read_b128 v[238:241], v205 offset:7168
	s_add_u32 s4, s0, 0xfffc0080
	s_addc_u32 s5, s1, -1
	s_add_i32 s89, 0, 0x10000
	s_cmp_eq_u32 s88, 12
	s_cselect_b32 s43, s3, s5
	s_cselect_b32 s42, s36, s4
	s_cselect_b32 s35, s39, s84
	s_cselect_b32 s34, s71, s79
	s_add_i32 s4, 0, 0x14000
	v_lshl_add_u64 v[180:181], s[0:1], 0, v[164:165]
	s_add_i32 m0, s69, 0xc000
	s_nop 0
	global_load_lds_dwordx4 v[180:181], off
	v_lshl_add_u64 v[180:181], s[0:1], 0, v[166:167]
	s_add_i32 m0, s69, 0xe000
	s_nop 0
	global_load_lds_dwordx4 v[180:181], off
	s_waitcnt vmcnt(8)
	s_waitcnt lgkmcnt(0)
	s_barrier
	s_waitcnt lgkmcnt(0)
	v_mfma_f32_16x16x32_bf16 v[124:127], v[128:131], v[210:213], v[124:127]
	v_mfma_f32_16x16x32_bf16 v[120:123], v[136:139], v[210:213], v[120:123]
	v_mfma_f32_16x16x32_bf16 v[112:115], v[128:131], v[218:221], v[112:115]
	v_mfma_f32_16x16x32_bf16 v[108:111], v[136:139], v[218:221], v[108:111]
	v_mfma_f32_16x16x32_bf16 v[100:103], v[128:131], v[226:229], v[100:103]
	v_mfma_f32_16x16x32_bf16 v[92:95], v[136:139], v[226:229], v[92:95]
	v_mfma_f32_16x16x32_bf16 v[84:87], v[128:131], v[234:237], v[84:87]
	v_mfma_f32_16x16x32_bf16 v[76:79], v[136:139], v[234:237], v[76:79]
	v_mfma_f32_16x16x32_bf16 v[124:127], v[132:135], v[214:217], v[124:127]
	v_mfma_f32_16x16x32_bf16 v[120:123], v[140:143], v[214:217], v[120:123]
	v_mfma_f32_16x16x32_bf16 v[112:115], v[132:135], v[222:225], v[112:115]
	v_mfma_f32_16x16x32_bf16 v[108:111], v[140:143], v[222:225], v[108:111]
	v_mfma_f32_16x16x32_bf16 v[100:103], v[132:135], v[230:233], v[100:103]
	v_mfma_f32_16x16x32_bf16 v[92:95], v[140:143], v[230:233], v[92:95]
	v_mfma_f32_16x16x32_bf16 v[84:87], v[132:135], v[238:241], v[84:87]
	v_mfma_f32_16x16x32_bf16 v[76:79], v[140:143], v[238:241], v[76:79]
	v_mfma_f32_16x16x32_bf16 v[116:119], v[168:171], v[210:213], v[116:119]
	v_mfma_f32_16x16x32_bf16 v[104:107], v[176:179], v[210:213], v[104:107]
	v_mfma_f32_16x16x32_bf16 v[96:99], v[168:171], v[218:221], v[96:99]
	v_mfma_f32_16x16x32_bf16 v[88:91], v[176:179], v[218:221], v[88:91]
	v_mfma_f32_16x16x32_bf16 v[80:83], v[168:171], v[226:229], v[80:83]
	v_mfma_f32_16x16x32_bf16 v[72:75], v[176:179], v[226:229], v[72:75]
	v_mfma_f32_16x16x32_bf16 v[68:71], v[168:171], v[234:237], v[68:71]
	v_mfma_f32_16x16x32_bf16 v[64:67], v[176:179], v[234:237], v[64:67]
	v_mfma_f32_16x16x32_bf16 v[116:119], v[172:175], v[214:217], v[116:119]
	v_mfma_f32_16x16x32_bf16 v[104:107], v[206:209], v[214:217], v[104:107]
	v_mfma_f32_16x16x32_bf16 v[96:99], v[172:175], v[222:225], v[96:99]
	v_mfma_f32_16x16x32_bf16 v[88:91], v[206:209], v[222:225], v[88:91]
	v_mfma_f32_16x16x32_bf16 v[80:83], v[172:175], v[230:233], v[80:83]
	v_mfma_f32_16x16x32_bf16 v[72:75], v[206:209], v[230:233], v[72:75]
	v_mfma_f32_16x16x32_bf16 v[68:71], v[172:175], v[238:241], v[68:71]
	v_mfma_f32_16x16x32_bf16 v[64:67], v[206:209], v[238:241], v[64:67]
	s_barrier
	s_add_i32 s5, s89, s28
	v_lshl_add_u64 v[180:181], s[34:35], 0, v[156:157]
	s_mov_b32 m0, s5
	ds_read_b128 v[210:213], v205 offset:16384
	ds_read_b128 v[214:217], v205 offset:17408
	ds_read_b128 v[218:221], v205 offset:18432
	ds_read_b128 v[222:225], v205 offset:19456
	ds_read_b128 v[226:229], v205 offset:20480
	ds_read_b128 v[230:233], v205 offset:21504
	ds_read_b128 v[234:237], v205 offset:22528
	ds_read_b128 v[238:241], v205 offset:23552
	global_load_lds_dwordx4 v[180:181], off
	s_add_i32 m0, s5, 0x2000
	s_add_u32 s90, s34, 0x40000
	v_lshl_add_u64 v[242:243], s[34:35], 0, v[160:161]
	s_addc_u32 s91, s35, 0
	s_add_i32 s4, s4, s28
	global_load_lds_dwordx4 v[242:243], off
	v_lshl_add_u64 v[244:245], s[90:91], 0, v[156:157]
	s_mov_b32 m0, s4
	v_lshl_add_u64 v[246:247], s[42:43], 0, v[158:159]
	global_load_lds_dwordx4 v[244:245], off
	v_lshl_add_u64 v[244:245], s[90:91], 0, v[160:161]
	s_add_i32 m0, s4, 0x2000
	s_nop 0
	global_load_lds_dwordx4 v[244:245], off
	v_lshl_add_u64 v[244:245], s[42:43], 0, v[154:155]
	s_mov_b32 m0, s69
	s_nop 0
	global_load_lds_dwordx4 v[244:245], off
	s_mov_b32 m0, s62
	s_nop 0
	global_load_lds_dwordx4 v[246:247], off
	s_waitcnt vmcnt(8)
	s_waitcnt lgkmcnt(0)
	s_barrier
	s_waitcnt lgkmcnt(0)
	v_mfma_f32_16x16x32_bf16 v[60:63], v[128:131], v[210:213], v[60:63]
	v_mfma_f32_16x16x32_bf16 v[56:59], v[136:139], v[210:213], v[56:59]
	v_mfma_f32_16x16x32_bf16 v[52:55], v[128:131], v[218:221], v[52:55]
	v_mfma_f32_16x16x32_bf16 v[44:47], v[136:139], v[218:221], v[44:47]
	v_mfma_f32_16x16x32_bf16 v[36:39], v[128:131], v[226:229], v[36:39]
	v_mfma_f32_16x16x32_bf16 v[28:31], v[136:139], v[226:229], v[28:31]
	v_mfma_f32_16x16x32_bf16 v[20:23], v[128:131], v[234:237], v[20:23]
	v_mfma_f32_16x16x32_bf16 v[12:15], v[136:139], v[234:237], v[12:15]
	v_mfma_f32_16x16x32_bf16 v[60:63], v[132:135], v[214:217], v[60:63]
	v_mfma_f32_16x16x32_bf16 v[56:59], v[140:143], v[214:217], v[56:59]
	v_mfma_f32_16x16x32_bf16 v[52:55], v[132:135], v[222:225], v[52:55]
	v_mfma_f32_16x16x32_bf16 v[44:47], v[140:143], v[222:225], v[44:47]
	v_mfma_f32_16x16x32_bf16 v[36:39], v[132:135], v[230:233], v[36:39]
	v_mfma_f32_16x16x32_bf16 v[28:31], v[140:143], v[230:233], v[28:31]
	v_mfma_f32_16x16x32_bf16 v[20:23], v[132:135], v[238:241], v[20:23]
	v_mfma_f32_16x16x32_bf16 v[12:15], v[140:143], v[238:241], v[12:15]
	v_mfma_f32_16x16x32_bf16 v[48:51], v[168:171], v[210:213], v[48:51]
	v_mfma_f32_16x16x32_bf16 v[40:43], v[176:179], v[210:213], v[40:43]
	v_mfma_f32_16x16x32_bf16 v[32:35], v[168:171], v[218:221], v[32:35]
	v_mfma_f32_16x16x32_bf16 v[24:27], v[176:179], v[218:221], v[24:27]
	v_mfma_f32_16x16x32_bf16 v[16:19], v[168:171], v[226:229], v[16:19]
	v_mfma_f32_16x16x32_bf16 v[8:11], v[176:179], v[226:229], v[8:11]
	v_mfma_f32_16x16x32_bf16 v[4:7], v[168:171], v[234:237], v[4:7]
	v_mfma_f32_16x16x32_bf16 v[0:3], v[176:179], v[234:237], v[0:3]
	v_mfma_f32_16x16x32_bf16 v[48:51], v[172:175], v[214:217], v[48:51]
	v_mfma_f32_16x16x32_bf16 v[40:43], v[206:209], v[214:217], v[40:43]
	v_mfma_f32_16x16x32_bf16 v[32:35], v[172:175], v[222:225], v[32:35]
	v_mfma_f32_16x16x32_bf16 v[24:27], v[206:209], v[222:225], v[24:27]
	v_mfma_f32_16x16x32_bf16 v[16:19], v[172:175], v[230:233], v[16:19]
	v_mfma_f32_16x16x32_bf16 v[8:11], v[206:209], v[230:233], v[8:11]
	v_mfma_f32_16x16x32_bf16 v[4:7], v[172:175], v[238:241], v[4:7]
	v_mfma_f32_16x16x32_bf16 v[0:3], v[206:209], v[238:241], v[0:3]
	s_barrier
	v_add_u32_e32 v140, 0x18000, v203
	v_add_u32_e32 v144, 0x1c000, v203
	ds_read_b128 v[128:131], v140
	ds_read_b128 v[132:135], v140 offset:1024
	ds_read_b128 v[136:139], v140 offset:2048
	ds_read_b128 v[140:143], v140 offset:3072
	ds_read_b128 v[168:171], v144
	ds_read_b128 v[172:175], v144 offset:1024
	ds_read_b128 v[176:179], v144 offset:2048
	ds_read_b128 v[206:209], v144 offset:3072
	ds_read_b128 v[210:213], v205 offset:32768
	ds_read_b128 v[214:217], v205 offset:33792
	ds_read_b128 v[218:221], v205 offset:34816
	ds_read_b128 v[222:225], v205 offset:35840
	ds_read_b128 v[226:229], v205 offset:36864
	ds_read_b128 v[230:233], v205 offset:37888
	ds_read_b128 v[234:237], v205 offset:38912
	ds_read_b128 v[238:241], v205 offset:39936
	s_add_i32 s4, 0, 0x18000
	s_add_i32 s5, 0, 0x1c000
	s_add_u32 s42, s42, 0x40000
	s_addc_u32 s43, s43, 0
	s_mov_b32 m0, s63
	v_lshl_add_u64 v[248:249], s[42:43], 0, v[154:155]
	global_load_lds_dwordx4 v[248:249], off
	v_lshl_add_u64 v[248:249], s[42:43], 0, v[158:159]
	s_mov_b32 m0, s50
	s_nop 0
	global_load_lds_dwordx4 v[248:249], off
	s_waitcnt vmcnt(8)
	s_waitcnt lgkmcnt(0)
	s_barrier
	s_waitcnt lgkmcnt(0)
	v_mfma_f32_16x16x32_bf16 v[124:127], v[128:131], v[210:213], v[124:127]
	v_mfma_f32_16x16x32_bf16 v[120:123], v[136:139], v[210:213], v[120:123]
	v_mfma_f32_16x16x32_bf16 v[112:115], v[128:131], v[218:221], v[112:115]
	v_mfma_f32_16x16x32_bf16 v[108:111], v[136:139], v[218:221], v[108:111]
	v_mfma_f32_16x16x32_bf16 v[100:103], v[128:131], v[226:229], v[100:103]
	v_mfma_f32_16x16x32_bf16 v[92:95], v[136:139], v[226:229], v[92:95]
	v_mfma_f32_16x16x32_bf16 v[84:87], v[128:131], v[234:237], v[84:87]
	v_mfma_f32_16x16x32_bf16 v[76:79], v[136:139], v[234:237], v[76:79]
	v_mfma_f32_16x16x32_bf16 v[124:127], v[132:135], v[214:217], v[124:127]
	v_mfma_f32_16x16x32_bf16 v[120:123], v[140:143], v[214:217], v[120:123]
	v_mfma_f32_16x16x32_bf16 v[112:115], v[132:135], v[222:225], v[112:115]
	v_mfma_f32_16x16x32_bf16 v[108:111], v[140:143], v[222:225], v[108:111]
	v_mfma_f32_16x16x32_bf16 v[100:103], v[132:135], v[230:233], v[100:103]
	v_mfma_f32_16x16x32_bf16 v[92:95], v[140:143], v[230:233], v[92:95]
	v_mfma_f32_16x16x32_bf16 v[84:87], v[132:135], v[238:241], v[84:87]
	v_mfma_f32_16x16x32_bf16 v[76:79], v[140:143], v[238:241], v[76:79]
	v_mfma_f32_16x16x32_bf16 v[116:119], v[168:171], v[210:213], v[116:119]
	v_mfma_f32_16x16x32_bf16 v[104:107], v[176:179], v[210:213], v[104:107]
	v_mfma_f32_16x16x32_bf16 v[96:99], v[168:171], v[218:221], v[96:99]
	v_mfma_f32_16x16x32_bf16 v[88:91], v[176:179], v[218:221], v[88:91]
	v_mfma_f32_16x16x32_bf16 v[80:83], v[168:171], v[226:229], v[80:83]
	v_mfma_f32_16x16x32_bf16 v[72:75], v[176:179], v[226:229], v[72:75]
	v_mfma_f32_16x16x32_bf16 v[68:71], v[168:171], v[234:237], v[68:71]
	v_mfma_f32_16x16x32_bf16 v[64:67], v[176:179], v[234:237], v[64:67]
	v_mfma_f32_16x16x32_bf16 v[116:119], v[172:175], v[214:217], v[116:119]
	v_mfma_f32_16x16x32_bf16 v[104:107], v[206:209], v[214:217], v[104:107]
	v_mfma_f32_16x16x32_bf16 v[96:99], v[172:175], v[222:225], v[96:99]
	v_mfma_f32_16x16x32_bf16 v[88:91], v[206:209], v[222:225], v[88:91]
	v_mfma_f32_16x16x32_bf16 v[80:83], v[172:175], v[230:233], v[80:83]
	v_mfma_f32_16x16x32_bf16 v[72:75], v[206:209], v[230:233], v[72:75]
	v_mfma_f32_16x16x32_bf16 v[68:71], v[172:175], v[238:241], v[68:71]
	v_mfma_f32_16x16x32_bf16 v[64:67], v[206:209], v[238:241], v[64:67]
	s_barrier
	s_add_i32 s4, s4, s28
	v_lshl_add_u64 v[180:181], v[180:181], 0, s[26:27]
	s_mov_b32 m0, s4
	ds_read_b128 v[210:213], v205 offset:49152
	ds_read_b128 v[214:217], v205 offset:50176
	ds_read_b128 v[218:221], v205 offset:51200
	ds_read_b128 v[222:225], v205 offset:52224
	ds_read_b128 v[226:229], v205 offset:53248
	ds_read_b128 v[230:233], v205 offset:54272
	ds_read_b128 v[234:237], v205 offset:55296
	ds_read_b128 v[238:241], v205 offset:56320
	global_load_lds_dwordx4 v[180:181], off
	s_add_i32 m0, s4, 0x2000
	s_add_u32 s34, s34, 0x40080
	v_lshl_add_u64 v[180:181], v[242:243], 0, s[26:27]
	s_addc_u32 s35, s35, 0
	s_add_i32 s4, s5, s28
	global_load_lds_dwordx4 v[180:181], off
	v_lshl_add_u64 v[180:181], s[34:35], 0, v[156:157]
	s_mov_b32 m0, s4
	s_nop 0
	global_load_lds_dwordx4 v[180:181], off
	v_lshl_add_u64 v[180:181], s[34:35], 0, v[160:161]
	s_add_i32 m0, s4, 0x2000
	s_nop 0
	global_load_lds_dwordx4 v[180:181], off
	v_lshl_add_u64 v[180:181], v[244:245], 0, s[26:27]
	s_mov_b32 m0, s51
	s_nop 0
	global_load_lds_dwordx4 v[180:181], off
	v_lshl_add_u64 v[180:181], v[246:247], 0, s[26:27]
	s_mov_b32 m0, s64
	s_nop 0
	global_load_lds_dwordx4 v[180:181], off
	s_waitcnt vmcnt(8)
	s_waitcnt lgkmcnt(0)
	s_barrier
	s_waitcnt lgkmcnt(0)
	v_mfma_f32_16x16x32_bf16 v[60:63], v[128:131], v[210:213], v[60:63]
	v_mfma_f32_16x16x32_bf16 v[56:59], v[136:139], v[210:213], v[56:59]
	v_mfma_f32_16x16x32_bf16 v[52:55], v[128:131], v[218:221], v[52:55]
	v_mfma_f32_16x16x32_bf16 v[44:47], v[136:139], v[218:221], v[44:47]
	v_mfma_f32_16x16x32_bf16 v[36:39], v[128:131], v[226:229], v[36:39]
	v_mfma_f32_16x16x32_bf16 v[28:31], v[136:139], v[226:229], v[28:31]
	v_mfma_f32_16x16x32_bf16 v[20:23], v[128:131], v[234:237], v[20:23]
	v_mfma_f32_16x16x32_bf16 v[12:15], v[136:139], v[234:237], v[12:15]
	v_mfma_f32_16x16x32_bf16 v[60:63], v[132:135], v[214:217], v[60:63]
	v_mfma_f32_16x16x32_bf16 v[56:59], v[140:143], v[214:217], v[56:59]
	v_mfma_f32_16x16x32_bf16 v[52:55], v[132:135], v[222:225], v[52:55]
	v_mfma_f32_16x16x32_bf16 v[44:47], v[140:143], v[222:225], v[44:47]
	v_mfma_f32_16x16x32_bf16 v[36:39], v[132:135], v[230:233], v[36:39]
	v_mfma_f32_16x16x32_bf16 v[28:31], v[140:143], v[230:233], v[28:31]
	v_mfma_f32_16x16x32_bf16 v[20:23], v[132:135], v[238:241], v[20:23]
	v_mfma_f32_16x16x32_bf16 v[12:15], v[140:143], v[238:241], v[12:15]
	v_mfma_f32_16x16x32_bf16 v[48:51], v[168:171], v[210:213], v[48:51]
	v_mfma_f32_16x16x32_bf16 v[40:43], v[176:179], v[210:213], v[40:43]
	v_mfma_f32_16x16x32_bf16 v[32:35], v[168:171], v[218:221], v[32:35]
	v_mfma_f32_16x16x32_bf16 v[24:27], v[176:179], v[218:221], v[24:27]
	v_mfma_f32_16x16x32_bf16 v[16:19], v[168:171], v[226:229], v[16:19]
	v_mfma_f32_16x16x32_bf16 v[8:11], v[176:179], v[226:229], v[8:11]
	v_mfma_f32_16x16x32_bf16 v[4:7], v[168:171], v[234:237], v[4:7]
	v_mfma_f32_16x16x32_bf16 v[0:3], v[176:179], v[234:237], v[0:3]
	v_mfma_f32_16x16x32_bf16 v[48:51], v[172:175], v[214:217], v[48:51]
	v_mfma_f32_16x16x32_bf16 v[40:43], v[206:209], v[214:217], v[40:43]
	v_mfma_f32_16x16x32_bf16 v[32:35], v[172:175], v[222:225], v[32:35]
	v_mfma_f32_16x16x32_bf16 v[24:27], v[206:209], v[222:225], v[24:27]
	v_mfma_f32_16x16x32_bf16 v[16:19], v[172:175], v[230:233], v[16:19]
	v_mfma_f32_16x16x32_bf16 v[8:11], v[206:209], v[230:233], v[8:11]
	v_mfma_f32_16x16x32_bf16 v[4:7], v[172:175], v[238:241], v[4:7]
	v_mfma_f32_16x16x32_bf16 v[0:3], v[206:209], v[238:241], v[0:3]
	s_barrier
	s_add_i32 s88, s88, 2
	s_add_u32 s0, s0, 0x100
	s_addc_u32 s1, s1, 0
	s_add_u32 s79, s79, 0x100
	s_addc_u32 s84, s84, 0
	s_cmp_gt_u32 s88, 13
	s_cbranch_scc0 .LBB0_605
	s_setprio 0
	s_and_b64 vcc, exec, s[66:67]
	s_cbranch_vccz .LBB0_608
	s_barrier

.Lkprio_1005:
.LBB0_1005:
	v_add_u32_e32 v138, 0x10000, v141
	ds_read_b128 v[154:157], v138
	ds_read_b128 v[158:161], v138 offset:1024
	ds_read_b128 v[162:165], v138 offset:2048
	ds_read_b128 v[166:169], v138 offset:3072
	v_add_u32_e32 v138, 0x14000, v141
	ds_read_b128 v[170:173], v138
	ds_read_b128 v[174:177], v138 offset:1024
	ds_read_b128 v[178:181], v138 offset:2048
	ds_read_b128 v[204:207], v138 offset:3072
	ds_read_b128 v[208:211], v143
	ds_read_b128 v[212:215], v143 offset:1024
	ds_read_b128 v[216:219], v143 offset:2048
	ds_read_b128 v[220:223], v143 offset:3072
	ds_read_b128 v[224:227], v143 offset:4096
	ds_read_b128 v[228:231], v143 offset:5120
	ds_read_b128 v[232:235], v143 offset:6144
	ds_read_b128 v[236:239], v143 offset:7168
	s_add_u32 s4, s54, 0xfffe0080
	s_addc_u32 s5, s55, -1
	s_add_i32 s72, 0, 0x10000
	s_cmp_eq_u32 s71, 4
	s_cselect_b32 s59, s29, s5
	s_cselect_b32 s58, s47, s4
	s_cselect_b32 s35, s45, s70
	s_cselect_b32 s34, s68, s69
	s_add_i32 s73, 0, 0x14000
	v_lshl_add_u64 v[138:139], s[54:55], 0, v[134:135]
	s_add_i32 m0, s53, 0xc000
	s_nop 0
	global_load_lds_dwordx4 v[138:139], off
	v_lshl_add_u64 v[138:139], s[54:55], 0, v[136:137]
	s_add_i32 m0, s53, 0xe000
	s_nop 0
	global_load_lds_dwordx4 v[138:139], off
	s_waitcnt vmcnt(8)
	s_waitcnt lgkmcnt(0)
	s_barrier
	s_waitcnt lgkmcnt(0)
	v_mfma_f32_16x16x32_bf16 v[120:123], v[154:157], v[208:211], v[120:123]
	v_mfma_f32_16x16x32_bf16 v[124:127], v[162:165], v[208:211], v[124:127]
	v_mfma_f32_16x16x32_bf16 v[104:107], v[154:157], v[216:219], v[104:107]
	v_mfma_f32_16x16x32_bf16 v[108:111], v[162:165], v[216:219], v[108:111]
	v_mfma_f32_16x16x32_bf16 v[88:91], v[154:157], v[224:227], v[88:91]
	v_mfma_f32_16x16x32_bf16 v[92:95], v[162:165], v[224:227], v[92:95]
	v_mfma_f32_16x16x32_bf16 v[72:75], v[154:157], v[232:235], v[72:75]
	v_mfma_f32_16x16x32_bf16 v[76:79], v[162:165], v[232:235], v[76:79]
	v_mfma_f32_16x16x32_bf16 v[120:123], v[158:161], v[212:215], v[120:123]
	v_mfma_f32_16x16x32_bf16 v[124:127], v[166:169], v[212:215], v[124:127]
	v_mfma_f32_16x16x32_bf16 v[104:107], v[158:161], v[220:223], v[104:107]
	v_mfma_f32_16x16x32_bf16 v[108:111], v[166:169], v[220:223], v[108:111]
	v_mfma_f32_16x16x32_bf16 v[88:91], v[158:161], v[228:231], v[88:91]
	v_mfma_f32_16x16x32_bf16 v[92:95], v[166:169], v[228:231], v[92:95]
	v_mfma_f32_16x16x32_bf16 v[72:75], v[158:161], v[236:239], v[72:75]
	v_mfma_f32_16x16x32_bf16 v[76:79], v[166:169], v[236:239], v[76:79]
	v_mfma_f32_16x16x32_bf16 v[112:115], v[170:173], v[208:211], v[112:115]
	v_mfma_f32_16x16x32_bf16 v[116:119], v[178:181], v[208:211], v[116:119]
	v_mfma_f32_16x16x32_bf16 v[96:99], v[170:173], v[216:219], v[96:99]
	v_mfma_f32_16x16x32_bf16 v[100:103], v[178:181], v[216:219], v[100:103]
	v_mfma_f32_16x16x32_bf16 v[80:83], v[170:173], v[224:227], v[80:83]
	v_mfma_f32_16x16x32_bf16 v[84:87], v[178:181], v[224:227], v[84:87]
	v_mfma_f32_16x16x32_bf16 v[64:67], v[170:173], v[232:235], v[64:67]
	v_mfma_f32_16x16x32_bf16 v[68:71], v[178:181], v[232:235], v[68:71]
	v_mfma_f32_16x16x32_bf16 v[112:115], v[174:177], v[212:215], v[112:115]
	v_mfma_f32_16x16x32_bf16 v[116:119], v[204:207], v[212:215], v[116:119]
	v_mfma_f32_16x16x32_bf16 v[96:99], v[174:177], v[220:223], v[96:99]
	v_mfma_f32_16x16x32_bf16 v[100:103], v[204:207], v[220:223], v[100:103]
	v_mfma_f32_16x16x32_bf16 v[80:83], v[174:177], v[228:231], v[80:83]
	v_mfma_f32_16x16x32_bf16 v[84:87], v[204:207], v[228:231], v[84:87]
	v_mfma_f32_16x16x32_bf16 v[64:67], v[174:177], v[236:239], v[64:67]
	v_mfma_f32_16x16x32_bf16 v[68:71], v[204:207], v[236:239], v[68:71]
	s_barrier
	s_add_i32 s4, s72, s30
	v_lshl_add_u64 v[138:139], s[34:35], 0, v[144:145]
	s_mov_b32 m0, s4
	ds_read_b128 v[208:211], v143 offset:16384
	ds_read_b128 v[212:215], v143 offset:17408
	ds_read_b128 v[216:219], v143 offset:18432
	ds_read_b128 v[220:223], v143 offset:19456
	ds_read_b128 v[224:227], v143 offset:20480
	ds_read_b128 v[228:231], v143 offset:21504
	ds_read_b128 v[232:235], v143 offset:22528
	ds_read_b128 v[236:239], v143 offset:23552
	global_load_lds_dwordx4 v[138:139], off
	s_add_i32 m0, s4, 0x2000
	s_add_u32 s4, s34, 0x20000
	v_lshl_add_u64 v[202:203], s[34:35], 0, v[132:133]
	s_addc_u32 s5, s35, 0
	s_add_i32 s72, s73, s30
	global_load_lds_dwordx4 v[202:203], off
	v_lshl_add_u64 v[240:241], s[4:5], 0, v[144:145]
	s_mov_b32 m0, s72
	v_lshl_add_u64 v[242:243], s[58:59], 0, v[130:131]
	global_load_lds_dwordx4 v[240:241], off
	v_lshl_add_u64 v[240:241], s[4:5], 0, v[132:133]
	s_add_i32 m0, s72, 0x2000
	s_nop 0
	global_load_lds_dwordx4 v[240:241], off
	v_lshl_add_u64 v[240:241], s[58:59], 0, v[128:129]
	s_mov_b32 m0, s53
	s_nop 0
	global_load_lds_dwordx4 v[240:241], off
	s_mov_b32 m0, s62
	s_nop 0
	global_load_lds_dwordx4 v[242:243], off
	s_waitcnt vmcnt(8)
	s_waitcnt lgkmcnt(0)
	s_barrier
	s_waitcnt lgkmcnt(0)
	v_mfma_f32_16x16x32_bf16 v[56:59], v[154:157], v[208:211], v[56:59]
	v_mfma_f32_16x16x32_bf16 v[60:63], v[162:165], v[208:211], v[60:63]
	v_mfma_f32_16x16x32_bf16 v[40:43], v[154:157], v[216:219], v[40:43]
	v_mfma_f32_16x16x32_bf16 v[44:47], v[162:165], v[216:219], v[44:47]
	v_mfma_f32_16x16x32_bf16 v[24:27], v[154:157], v[224:227], v[24:27]
	v_mfma_f32_16x16x32_bf16 v[28:31], v[162:165], v[224:227], v[28:31]
	v_mfma_f32_16x16x32_bf16 v[8:11], v[154:157], v[232:235], v[8:11]
	v_mfma_f32_16x16x32_bf16 v[12:15], v[162:165], v[232:235], v[12:15]
	v_mfma_f32_16x16x32_bf16 v[56:59], v[158:161], v[212:215], v[56:59]
	v_mfma_f32_16x16x32_bf16 v[60:63], v[166:169], v[212:215], v[60:63]
	v_mfma_f32_16x16x32_bf16 v[40:43], v[158:161], v[220:223], v[40:43]
	v_mfma_f32_16x16x32_bf16 v[44:47], v[166:169], v[220:223], v[44:47]
	v_mfma_f32_16x16x32_bf16 v[24:27], v[158:161], v[228:231], v[24:27]
	v_mfma_f32_16x16x32_bf16 v[28:31], v[166:169], v[228:231], v[28:31]
	v_mfma_f32_16x16x32_bf16 v[8:11], v[158:161], v[236:239], v[8:11]
	v_mfma_f32_16x16x32_bf16 v[12:15], v[166:169], v[236:239], v[12:15]
	v_mfma_f32_16x16x32_bf16 v[48:51], v[170:173], v[208:211], v[48:51]
	v_mfma_f32_16x16x32_bf16 v[52:55], v[178:181], v[208:211], v[52:55]
	v_mfma_f32_16x16x32_bf16 v[32:35], v[170:173], v[216:219], v[32:35]
	v_mfma_f32_16x16x32_bf16 v[36:39], v[178:181], v[216:219], v[36:39]
	v_mfma_f32_16x16x32_bf16 v[16:19], v[170:173], v[224:227], v[16:19]
	v_mfma_f32_16x16x32_bf16 v[20:23], v[178:181], v[224:227], v[20:23]
	v_mfma_f32_16x16x32_bf16 v[0:3], v[170:173], v[232:235], v[0:3]
	v_mfma_f32_16x16x32_bf16 v[4:7], v[178:181], v[232:235], v[4:7]
	v_mfma_f32_16x16x32_bf16 v[48:51], v[174:177], v[212:215], v[48:51]
	v_mfma_f32_16x16x32_bf16 v[52:55], v[204:207], v[212:215], v[52:55]
	v_mfma_f32_16x16x32_bf16 v[32:35], v[174:177], v[220:223], v[32:35]
	v_mfma_f32_16x16x32_bf16 v[36:39], v[204:207], v[220:223], v[36:39]
	v_mfma_f32_16x16x32_bf16 v[16:19], v[174:177], v[228:231], v[16:19]
	v_mfma_f32_16x16x32_bf16 v[20:23], v[204:207], v[228:231], v[20:23]
	v_mfma_f32_16x16x32_bf16 v[0:3], v[174:177], v[236:239], v[0:3]
	v_mfma_f32_16x16x32_bf16 v[4:7], v[204:207], v[236:239], v[4:7]
	s_barrier
	v_add_u32_e32 v166, 0x18000, v141
	v_add_u32_e32 v204, 0x1c000, v141
	ds_read_b128 v[154:157], v166
	ds_read_b128 v[158:161], v166 offset:1024
	ds_read_b128 v[162:165], v166 offset:2048
	ds_read_b128 v[166:169], v166 offset:3072
	ds_read_b128 v[170:173], v204
	ds_read_b128 v[174:177], v204 offset:1024
	ds_read_b128 v[178:181], v204 offset:2048
	ds_read_b128 v[204:207], v204 offset:3072
	ds_read_b128 v[208:211], v143 offset:32768
	ds_read_b128 v[212:215], v143 offset:33792
	ds_read_b128 v[216:219], v143 offset:34816
	ds_read_b128 v[220:223], v143 offset:35840
	ds_read_b128 v[224:227], v143 offset:36864
	ds_read_b128 v[228:231], v143 offset:37888
	ds_read_b128 v[232:235], v143 offset:38912
	ds_read_b128 v[236:239], v143 offset:39936
	s_add_i32 s72, 0, 0x18000
	s_add_i32 s73, 0, 0x1c000
	s_add_u32 s4, s58, 0x20000
	s_addc_u32 s5, s59, 0
	s_mov_b32 m0, s63
	v_lshl_add_u64 v[244:245], s[4:5], 0, v[128:129]
	global_load_lds_dwordx4 v[244:245], off
	v_lshl_add_u64 v[244:245], s[4:5], 0, v[130:131]
	s_mov_b32 m0, s64
	s_nop 0
	global_load_lds_dwordx4 v[244:245], off
	s_waitcnt vmcnt(8)
	s_waitcnt lgkmcnt(0)
	s_barrier
	s_waitcnt lgkmcnt(0)
	v_mfma_f32_16x16x32_bf16 v[120:123], v[154:157], v[208:211], v[120:123]
	v_mfma_f32_16x16x32_bf16 v[124:127], v[162:165], v[208:211], v[124:127]
	v_mfma_f32_16x16x32_bf16 v[104:107], v[154:157], v[216:219], v[104:107]
	v_mfma_f32_16x16x32_bf16 v[108:111], v[162:165], v[216:219], v[108:111]
	v_mfma_f32_16x16x32_bf16 v[88:91], v[154:157], v[224:227], v[88:91]
	v_mfma_f32_16x16x32_bf16 v[92:95], v[162:165], v[224:227], v[92:95]
	v_mfma_f32_16x16x32_bf16 v[72:75], v[154:157], v[232:235], v[72:75]
	v_mfma_f32_16x16x32_bf16 v[76:79], v[162:165], v[232:235], v[76:79]
	v_mfma_f32_16x16x32_bf16 v[120:123], v[158:161], v[212:215], v[120:123]
	v_mfma_f32_16x16x32_bf16 v[124:127], v[166:169], v[212:215], v[124:127]
	v_mfma_f32_16x16x32_bf16 v[104:107], v[158:161], v[220:223], v[104:107]
	v_mfma_f32_16x16x32_bf16 v[108:111], v[166:169], v[220:223], v[108:111]
	v_mfma_f32_16x16x32_bf16 v[88:91], v[158:161], v[228:231], v[88:91]
	v_mfma_f32_16x16x32_bf16 v[92:95], v[166:169], v[228:231], v[92:95]
	v_mfma_f32_16x16x32_bf16 v[72:75], v[158:161], v[236:239], v[72:75]
	v_mfma_f32_16x16x32_bf16 v[76:79], v[166:169], v[236:239], v[76:79]
	v_mfma_f32_16x16x32_bf16 v[112:115], v[170:173], v[208:211], v[112:115]
	v_mfma_f32_16x16x32_bf16 v[116:119], v[178:181], v[208:211], v[116:119]
	v_mfma_f32_16x16x32_bf16 v[96:99], v[170:173], v[216:219], v[96:99]
	v_mfma_f32_16x16x32_bf16 v[100:103], v[178:181], v[216:219], v[100:103]
	v_mfma_f32_16x16x32_bf16 v[80:83], v[170:173], v[224:227], v[80:83]
	v_mfma_f32_16x16x32_bf16 v[84:87], v[178:181], v[224:227], v[84:87]
	v_mfma_f32_16x16x32_bf16 v[64:67], v[170:173], v[232:235], v[64:67]
	v_mfma_f32_16x16x32_bf16 v[68:71], v[178:181], v[232:235], v[68:71]
	v_mfma_f32_16x16x32_bf16 v[112:115], v[174:177], v[212:215], v[112:115]
	v_mfma_f32_16x16x32_bf16 v[116:119], v[204:207], v[212:215], v[116:119]
	v_mfma_f32_16x16x32_bf16 v[96:99], v[174:177], v[220:223], v[96:99]
	v_mfma_f32_16x16x32_bf16 v[100:103], v[204:207], v[220:223], v[100:103]
	v_mfma_f32_16x16x32_bf16 v[80:83], v[174:177], v[228:231], v[80:83]
	v_mfma_f32_16x16x32_bf16 v[84:87], v[204:207], v[228:231], v[84:87]
	v_mfma_f32_16x16x32_bf16 v[64:67], v[174:177], v[236:239], v[64:67]
	v_mfma_f32_16x16x32_bf16 v[68:71], v[204:207], v[236:239], v[68:71]
	s_barrier
	s_add_i32 s4, s72, s30
	v_lshl_add_u64 v[138:139], v[138:139], 0, s[26:27]
	s_mov_b32 m0, s4
	ds_read_b128 v[208:211], v143 offset:49152
	ds_read_b128 v[212:215], v143 offset:50176
	ds_read_b128 v[216:219], v143 offset:51200
	ds_read_b128 v[220:223], v143 offset:52224
	ds_read_b128 v[224:227], v143 offset:53248
	ds_read_b128 v[228:231], v143 offset:54272
	ds_read_b128 v[232:235], v143 offset:55296
	ds_read_b128 v[236:239], v143 offset:56320
	global_load_lds_dwordx4 v[138:139], off
	s_add_i32 m0, s4, 0x2000
	s_add_u32 s4, s34, 0x20080
	v_lshl_add_u64 v[138:139], v[202:203], 0, s[26:27]
	s_addc_u32 s5, s35, 0
	s_add_i32 s34, s73, s30
	global_load_lds_dwordx4 v[138:139], off
	v_lshl_add_u64 v[138:139], s[4:5], 0, v[144:145]
	s_mov_b32 m0, s34
	s_nop 0
	global_load_lds_dwordx4 v[138:139], off
	v_lshl_add_u64 v[138:139], s[4:5], 0, v[132:133]
	s_add_i32 m0, s34, 0x2000
	s_nop 0
	global_load_lds_dwordx4 v[138:139], off
	v_lshl_add_u64 v[138:139], v[240:241], 0, s[26:27]
	s_mov_b32 m0, s65
	s_nop 0
	global_load_lds_dwordx4 v[138:139], off
	v_lshl_add_u64 v[138:139], v[242:243], 0, s[26:27]
	s_mov_b32 m0, s66
	s_nop 0
	global_load_lds_dwordx4 v[138:139], off
	s_waitcnt vmcnt(8)
	s_waitcnt lgkmcnt(0)
	s_barrier
	s_waitcnt lgkmcnt(0)
	v_mfma_f32_16x16x32_bf16 v[56:59], v[154:157], v[208:211], v[56:59]
	v_mfma_f32_16x16x32_bf16 v[60:63], v[162:165], v[208:211], v[60:63]
	v_mfma_f32_16x16x32_bf16 v[40:43], v[154:157], v[216:219], v[40:43]
	v_mfma_f32_16x16x32_bf16 v[44:47], v[162:165], v[216:219], v[44:47]
	v_mfma_f32_16x16x32_bf16 v[24:27], v[154:157], v[224:227], v[24:27]
	v_mfma_f32_16x16x32_bf16 v[28:31], v[162:165], v[224:227], v[28:31]
	v_mfma_f32_16x16x32_bf16 v[8:11], v[154:157], v[232:235], v[8:11]
	v_mfma_f32_16x16x32_bf16 v[12:15], v[162:165], v[232:235], v[12:15]
	v_mfma_f32_16x16x32_bf16 v[56:59], v[158:161], v[212:215], v[56:59]
	v_mfma_f32_16x16x32_bf16 v[60:63], v[166:169], v[212:215], v[60:63]
	v_mfma_f32_16x16x32_bf16 v[40:43], v[158:161], v[220:223], v[40:43]
	v_mfma_f32_16x16x32_bf16 v[44:47], v[166:169], v[220:223], v[44:47]
	v_mfma_f32_16x16x32_bf16 v[24:27], v[158:161], v[228:231], v[24:27]
	v_mfma_f32_16x16x32_bf16 v[28:31], v[166:169], v[228:231], v[28:31]
	v_mfma_f32_16x16x32_bf16 v[8:11], v[158:161], v[236:239], v[8:11]
	v_mfma_f32_16x16x32_bf16 v[12:15], v[166:169], v[236:239], v[12:15]
	v_mfma_f32_16x16x32_bf16 v[48:51], v[170:173], v[208:211], v[48:51]
	v_mfma_f32_16x16x32_bf16 v[52:55], v[178:181], v[208:211], v[52:55]
	v_mfma_f32_16x16x32_bf16 v[32:35], v[170:173], v[216:219], v[32:35]
	v_mfma_f32_16x16x32_bf16 v[36:39], v[178:181], v[216:219], v[36:39]
	v_mfma_f32_16x16x32_bf16 v[16:19], v[170:173], v[224:227], v[16:19]
	v_mfma_f32_16x16x32_bf16 v[20:23], v[178:181], v[224:227], v[20:23]
	v_mfma_f32_16x16x32_bf16 v[0:3], v[170:173], v[232:235], v[0:3]
	v_mfma_f32_16x16x32_bf16 v[4:7], v[178:181], v[232:235], v[4:7]
	v_mfma_f32_16x16x32_bf16 v[48:51], v[174:177], v[212:215], v[48:51]
	v_mfma_f32_16x16x32_bf16 v[52:55], v[204:207], v[212:215], v[52:55]
	v_mfma_f32_16x16x32_bf16 v[32:35], v[174:177], v[220:223], v[32:35]
	v_mfma_f32_16x16x32_bf16 v[36:39], v[204:207], v[220:223], v[36:39]
	v_mfma_f32_16x16x32_bf16 v[16:19], v[174:177], v[228:231], v[16:19]
	v_mfma_f32_16x16x32_bf16 v[20:23], v[204:207], v[228:231], v[20:23]
	v_mfma_f32_16x16x32_bf16 v[0:3], v[174:177], v[236:239], v[0:3]
	v_mfma_f32_16x16x32_bf16 v[4:7], v[204:207], v[236:239], v[4:7]
	s_barrier
	s_add_i32 s71, s71, 2
	s_add_u32 s54, s54, 0x100
	s_addc_u32 s55, s55, 0
	s_add_u32 s69, s69, 0x100
	s_addc_u32 s70, s70, 0
	s_cmp_gt_u32 s71, 5
	s_cbranch_scc0 .LBB0_1005
	s_setprio 0
	v_readlane_b32 s68, v255, 7
	s_and_b64 vcc, exec, s[42:43]
	v_readlane_b32 s69, v255, 8
	s_cbranch_vccz .LBB0_1008
	s_barrier

.Lkprio_1093:
.LBB0_1093:
	v_add_u32_e32 v164, 0x10000, v143
	v_add_u32_e32 v180, 0x14000, v143
	ds_read_b128 v[138:141], v164
	ds_read_b128 v[156:159], v164 offset:1024
	ds_read_b128 v[160:163], v164 offset:2048
	ds_read_b128 v[164:167], v164 offset:3072
	ds_read_b128 v[168:171], v180
	ds_read_b128 v[172:175], v180 offset:1024
	ds_read_b128 v[176:179], v180 offset:2048
	ds_read_b128 v[204:207], v180 offset:3072
	ds_read_b128 v[208:211], v155
	ds_read_b128 v[212:215], v155 offset:1024
	ds_read_b128 v[216:219], v155 offset:2048
	ds_read_b128 v[220:223], v155 offset:3072
	ds_read_b128 v[224:227], v155 offset:4096
	ds_read_b128 v[228:231], v155 offset:5120
	ds_read_b128 v[232:235], v155 offset:6144
	ds_read_b128 v[236:239], v155 offset:7168
	s_add_u32 s4, s58, 0xfffe0080
	s_addc_u32 s5, s59, -1
	s_add_i32 s74, 0, 0x10000
	s_cmp_eq_u32 s73, 4
	s_cselect_b32 s61, s33, s5
	s_cselect_b32 s60, s36, s4
	s_cselect_b32 s35, s49, s72
	s_cselect_b32 s34, s51, s71
	s_add_i32 s75, 0, 0x14000
	v_lshl_add_u64 v[180:181], s[58:59], 0, v[134:135]
	s_add_i32 m0, s64, 0xc000
	s_nop 0
	global_load_lds_dwordx4 v[180:181], off
	v_lshl_add_u64 v[180:181], s[58:59], 0, v[136:137]
	s_add_i32 m0, s64, 0xe000
	s_nop 0
	global_load_lds_dwordx4 v[180:181], off
	s_waitcnt vmcnt(8)
	s_waitcnt lgkmcnt(0)
	s_barrier
	s_waitcnt lgkmcnt(0)
	v_mfma_f32_16x16x32_bf16 v[124:127], v[138:141], v[208:211], v[124:127]
	v_mfma_f32_16x16x32_bf16 v[120:123], v[160:163], v[208:211], v[120:123]
	v_mfma_f32_16x16x32_bf16 v[108:111], v[138:141], v[216:219], v[108:111]
	v_mfma_f32_16x16x32_bf16 v[104:107], v[160:163], v[216:219], v[104:107]
	v_mfma_f32_16x16x32_bf16 v[92:95], v[138:141], v[224:227], v[92:95]
	v_mfma_f32_16x16x32_bf16 v[88:91], v[160:163], v[224:227], v[88:91]
	v_mfma_f32_16x16x32_bf16 v[76:79], v[138:141], v[232:235], v[76:79]
	v_mfma_f32_16x16x32_bf16 v[72:75], v[160:163], v[232:235], v[72:75]
	v_mfma_f32_16x16x32_bf16 v[124:127], v[156:159], v[212:215], v[124:127]
	v_mfma_f32_16x16x32_bf16 v[120:123], v[164:167], v[212:215], v[120:123]
	v_mfma_f32_16x16x32_bf16 v[108:111], v[156:159], v[220:223], v[108:111]
	v_mfma_f32_16x16x32_bf16 v[104:107], v[164:167], v[220:223], v[104:107]
	v_mfma_f32_16x16x32_bf16 v[92:95], v[156:159], v[228:231], v[92:95]
	v_mfma_f32_16x16x32_bf16 v[88:91], v[164:167], v[228:231], v[88:91]
	v_mfma_f32_16x16x32_bf16 v[76:79], v[156:159], v[236:239], v[76:79]
	v_mfma_f32_16x16x32_bf16 v[72:75], v[164:167], v[236:239], v[72:75]
	v_mfma_f32_16x16x32_bf16 v[116:119], v[168:171], v[208:211], v[116:119]
	v_mfma_f32_16x16x32_bf16 v[112:115], v[176:179], v[208:211], v[112:115]
	v_mfma_f32_16x16x32_bf16 v[100:103], v[168:171], v[216:219], v[100:103]
	v_mfma_f32_16x16x32_bf16 v[96:99], v[176:179], v[216:219], v[96:99]
	v_mfma_f32_16x16x32_bf16 v[84:87], v[168:171], v[224:227], v[84:87]
	v_mfma_f32_16x16x32_bf16 v[80:83], v[176:179], v[224:227], v[80:83]
	v_mfma_f32_16x16x32_bf16 v[68:71], v[168:171], v[232:235], v[68:71]
	v_mfma_f32_16x16x32_bf16 v[64:67], v[176:179], v[232:235], v[64:67]
	v_mfma_f32_16x16x32_bf16 v[116:119], v[172:175], v[212:215], v[116:119]
	v_mfma_f32_16x16x32_bf16 v[112:115], v[204:207], v[212:215], v[112:115]
	v_mfma_f32_16x16x32_bf16 v[100:103], v[172:175], v[220:223], v[100:103]
	v_mfma_f32_16x16x32_bf16 v[96:99], v[204:207], v[220:223], v[96:99]
	v_mfma_f32_16x16x32_bf16 v[84:87], v[172:175], v[228:231], v[84:87]
	v_mfma_f32_16x16x32_bf16 v[80:83], v[204:207], v[228:231], v[80:83]
	v_mfma_f32_16x16x32_bf16 v[68:71], v[172:175], v[236:239], v[68:71]
	v_mfma_f32_16x16x32_bf16 v[64:67], v[204:207], v[236:239], v[64:67]
	s_barrier
	s_add_i32 s4, s74, s28
	v_lshl_add_u64 v[180:181], s[34:35], 0, v[144:145]
	s_mov_b32 m0, s4
	ds_read_b128 v[208:211], v155 offset:16384
	ds_read_b128 v[212:215], v155 offset:17408
	ds_read_b128 v[216:219], v155 offset:18432
	ds_read_b128 v[220:223], v155 offset:19456
	ds_read_b128 v[224:227], v155 offset:20480
	ds_read_b128 v[228:231], v155 offset:21504
	ds_read_b128 v[232:235], v155 offset:22528
	ds_read_b128 v[236:239], v155 offset:23552
	global_load_lds_dwordx4 v[180:181], off
	s_add_i32 m0, s4, 0x2000
	s_add_u32 s4, s34, 0x20000
	v_lshl_add_u64 v[202:203], s[34:35], 0, v[132:133]
	s_addc_u32 s5, s35, 0
	s_add_i32 s74, s75, s28
	global_load_lds_dwordx4 v[202:203], off
	v_lshl_add_u64 v[240:241], s[4:5], 0, v[144:145]
	s_mov_b32 m0, s74
	v_lshl_add_u64 v[242:243], s[60:61], 0, v[130:131]
	global_load_lds_dwordx4 v[240:241], off
	v_lshl_add_u64 v[240:241], s[4:5], 0, v[132:133]
	s_add_i32 m0, s74, 0x2000
	s_nop 0
	global_load_lds_dwordx4 v[240:241], off
	v_lshl_add_u64 v[240:241], s[60:61], 0, v[128:129]
	s_mov_b32 m0, s64
	s_nop 0
	global_load_lds_dwordx4 v[240:241], off
	s_mov_b32 m0, s65
	s_nop 0
	global_load_lds_dwordx4 v[242:243], off
	s_waitcnt vmcnt(8)
	s_waitcnt lgkmcnt(0)
	s_barrier
	s_waitcnt lgkmcnt(0)
	v_mfma_f32_16x16x32_bf16 v[60:63], v[138:141], v[208:211], v[60:63]
	v_mfma_f32_16x16x32_bf16 v[56:59], v[160:163], v[208:211], v[56:59]
	v_mfma_f32_16x16x32_bf16 v[44:47], v[138:141], v[216:219], v[44:47]
	v_mfma_f32_16x16x32_bf16 v[40:43], v[160:163], v[216:219], v[40:43]
	v_mfma_f32_16x16x32_bf16 v[28:31], v[138:141], v[224:227], v[28:31]
	v_mfma_f32_16x16x32_bf16 v[24:27], v[160:163], v[224:227], v[24:27]
	v_mfma_f32_16x16x32_bf16 v[12:15], v[138:141], v[232:235], v[12:15]
	v_mfma_f32_16x16x32_bf16 v[8:11], v[160:163], v[232:235], v[8:11]
	v_mfma_f32_16x16x32_bf16 v[60:63], v[156:159], v[212:215], v[60:63]
	v_mfma_f32_16x16x32_bf16 v[56:59], v[164:167], v[212:215], v[56:59]
	v_mfma_f32_16x16x32_bf16 v[44:47], v[156:159], v[220:223], v[44:47]
	v_mfma_f32_16x16x32_bf16 v[40:43], v[164:167], v[220:223], v[40:43]
	v_mfma_f32_16x16x32_bf16 v[28:31], v[156:159], v[228:231], v[28:31]
	v_mfma_f32_16x16x32_bf16 v[24:27], v[164:167], v[228:231], v[24:27]
	v_mfma_f32_16x16x32_bf16 v[12:15], v[156:159], v[236:239], v[12:15]
	v_mfma_f32_16x16x32_bf16 v[8:11], v[164:167], v[236:239], v[8:11]
	v_mfma_f32_16x16x32_bf16 v[52:55], v[168:171], v[208:211], v[52:55]
	v_mfma_f32_16x16x32_bf16 v[48:51], v[176:179], v[208:211], v[48:51]
	v_mfma_f32_16x16x32_bf16 v[36:39], v[168:171], v[216:219], v[36:39]
	v_mfma_f32_16x16x32_bf16 v[32:35], v[176:179], v[216:219], v[32:35]
	v_mfma_f32_16x16x32_bf16 v[20:23], v[168:171], v[224:227], v[20:23]
	v_mfma_f32_16x16x32_bf16 v[16:19], v[176:179], v[224:227], v[16:19]
	v_mfma_f32_16x16x32_bf16 v[4:7], v[168:171], v[232:235], v[4:7]
	v_mfma_f32_16x16x32_bf16 v[0:3], v[176:179], v[232:235], v[0:3]
	v_mfma_f32_16x16x32_bf16 v[52:55], v[172:175], v[212:215], v[52:55]
	v_mfma_f32_16x16x32_bf16 v[48:51], v[204:207], v[212:215], v[48:51]
	v_mfma_f32_16x16x32_bf16 v[36:39], v[172:175], v[220:223], v[36:39]
	v_mfma_f32_16x16x32_bf16 v[32:35], v[204:207], v[220:223], v[32:35]
	v_mfma_f32_16x16x32_bf16 v[20:23], v[172:175], v[228:231], v[20:23]
	v_mfma_f32_16x16x32_bf16 v[16:19], v[204:207], v[228:231], v[16:19]
	v_mfma_f32_16x16x32_bf16 v[4:7], v[172:175], v[236:239], v[4:7]
	v_mfma_f32_16x16x32_bf16 v[0:3], v[204:207], v[236:239], v[0:3]
	s_barrier
	v_add_u32_e32 v164, 0x18000, v143
	v_add_u32_e32 v204, 0x1c000, v143
	ds_read_b128 v[138:141], v164
	ds_read_b128 v[156:159], v164 offset:1024
	ds_read_b128 v[160:163], v164 offset:2048
	ds_read_b128 v[164:167], v164 offset:3072
	ds_read_b128 v[168:171], v204
	ds_read_b128 v[172:175], v204 offset:1024
	ds_read_b128 v[176:179], v204 offset:2048
	ds_read_b128 v[204:207], v204 offset:3072
	ds_read_b128 v[208:211], v155 offset:32768
	ds_read_b128 v[212:215], v155 offset:33792
	ds_read_b128 v[216:219], v155 offset:34816
	ds_read_b128 v[220:223], v155 offset:35840
	ds_read_b128 v[224:227], v155 offset:36864
	ds_read_b128 v[228:231], v155 offset:37888
	ds_read_b128 v[232:235], v155 offset:38912
	ds_read_b128 v[236:239], v155 offset:39936
	s_add_i32 s74, 0, 0x18000
	s_add_i32 s75, 0, 0x1c000
	s_add_u32 s4, s60, 0x20000
	s_addc_u32 s5, s61, 0
	s_mov_b32 m0, s66
	v_lshl_add_u64 v[244:245], s[4:5], 0, v[128:129]
	global_load_lds_dwordx4 v[244:245], off
	v_lshl_add_u64 v[244:245], s[4:5], 0, v[130:131]
	s_mov_b32 m0, s67
	s_nop 0
	global_load_lds_dwordx4 v[244:245], off
	s_waitcnt vmcnt(8)
	s_waitcnt lgkmcnt(0)
	s_barrier
	s_waitcnt lgkmcnt(0)
	v_mfma_f32_16x16x32_bf16 v[124:127], v[138:141], v[208:211], v[124:127]
	v_mfma_f32_16x16x32_bf16 v[120:123], v[160:163], v[208:211], v[120:123]
	v_mfma_f32_16x16x32_bf16 v[108:111], v[138:141], v[216:219], v[108:111]
	v_mfma_f32_16x16x32_bf16 v[104:107], v[160:163], v[216:219], v[104:107]
	v_mfma_f32_16x16x32_bf16 v[92:95], v[138:141], v[224:227], v[92:95]
	v_mfma_f32_16x16x32_bf16 v[88:91], v[160:163], v[224:227], v[88:91]
	v_mfma_f32_16x16x32_bf16 v[76:79], v[138:141], v[232:235], v[76:79]
	v_mfma_f32_16x16x32_bf16 v[72:75], v[160:163], v[232:235], v[72:75]
	v_mfma_f32_16x16x32_bf16 v[124:127], v[156:159], v[212:215], v[124:127]
	v_mfma_f32_16x16x32_bf16 v[120:123], v[164:167], v[212:215], v[120:123]
	v_mfma_f32_16x16x32_bf16 v[108:111], v[156:159], v[220:223], v[108:111]
	v_mfma_f32_16x16x32_bf16 v[104:107], v[164:167], v[220:223], v[104:107]
	v_mfma_f32_16x16x32_bf16 v[92:95], v[156:159], v[228:231], v[92:95]
	v_mfma_f32_16x16x32_bf16 v[88:91], v[164:167], v[228:231], v[88:91]
	v_mfma_f32_16x16x32_bf16 v[76:79], v[156:159], v[236:239], v[76:79]
	v_mfma_f32_16x16x32_bf16 v[72:75], v[164:167], v[236:239], v[72:75]
	v_mfma_f32_16x16x32_bf16 v[116:119], v[168:171], v[208:211], v[116:119]
	v_mfma_f32_16x16x32_bf16 v[112:115], v[176:179], v[208:211], v[112:115]
	v_mfma_f32_16x16x32_bf16 v[100:103], v[168:171], v[216:219], v[100:103]
	v_mfma_f32_16x16x32_bf16 v[96:99], v[176:179], v[216:219], v[96:99]
	v_mfma_f32_16x16x32_bf16 v[84:87], v[168:171], v[224:227], v[84:87]
	v_mfma_f32_16x16x32_bf16 v[80:83], v[176:179], v[224:227], v[80:83]
	v_mfma_f32_16x16x32_bf16 v[68:71], v[168:171], v[232:235], v[68:71]
	v_mfma_f32_16x16x32_bf16 v[64:67], v[176:179], v[232:235], v[64:67]
	v_mfma_f32_16x16x32_bf16 v[116:119], v[172:175], v[212:215], v[116:119]
	v_mfma_f32_16x16x32_bf16 v[112:115], v[204:207], v[212:215], v[112:115]
	v_mfma_f32_16x16x32_bf16 v[100:103], v[172:175], v[220:223], v[100:103]
	v_mfma_f32_16x16x32_bf16 v[96:99], v[204:207], v[220:223], v[96:99]
	v_mfma_f32_16x16x32_bf16 v[84:87], v[172:175], v[228:231], v[84:87]
	v_mfma_f32_16x16x32_bf16 v[80:83], v[204:207], v[228:231], v[80:83]
	v_mfma_f32_16x16x32_bf16 v[68:71], v[172:175], v[236:239], v[68:71]
	v_mfma_f32_16x16x32_bf16 v[64:67], v[204:207], v[236:239], v[64:67]
	s_barrier
	s_add_i32 s4, s74, s28
	v_lshl_add_u64 v[180:181], v[180:181], 0, s[26:27]
	s_mov_b32 m0, s4
	ds_read_b128 v[208:211], v155 offset:49152
	ds_read_b128 v[212:215], v155 offset:50176
	ds_read_b128 v[216:219], v155 offset:51200
	ds_read_b128 v[220:223], v155 offset:52224
	ds_read_b128 v[224:227], v155 offset:53248
	ds_read_b128 v[228:231], v155 offset:54272
	ds_read_b128 v[232:235], v155 offset:55296
	ds_read_b128 v[236:239], v155 offset:56320
	global_load_lds_dwordx4 v[180:181], off
	s_add_i32 m0, s4, 0x2000
	s_add_u32 s4, s34, 0x20080
	v_lshl_add_u64 v[180:181], v[202:203], 0, s[26:27]
	s_addc_u32 s5, s35, 0
	s_add_i32 s34, s75, s28
	global_load_lds_dwordx4 v[180:181], off
	v_lshl_add_u64 v[180:181], s[4:5], 0, v[144:145]
	s_mov_b32 m0, s34
	s_nop 0
	global_load_lds_dwordx4 v[180:181], off
	v_lshl_add_u64 v[180:181], s[4:5], 0, v[132:133]
	s_add_i32 m0, s34, 0x2000
	s_nop 0
	global_load_lds_dwordx4 v[180:181], off
	v_lshl_add_u64 v[180:181], v[240:241], 0, s[26:27]
	s_mov_b32 m0, s68
	s_nop 0
	global_load_lds_dwordx4 v[180:181], off
	v_lshl_add_u64 v[180:181], v[242:243], 0, s[26:27]
	s_mov_b32 m0, s69
	s_nop 0
	global_load_lds_dwordx4 v[180:181], off
	s_waitcnt vmcnt(8)
	s_waitcnt lgkmcnt(0)
	s_barrier
	s_waitcnt lgkmcnt(0)
	v_mfma_f32_16x16x32_bf16 v[60:63], v[138:141], v[208:211], v[60:63]
	v_mfma_f32_16x16x32_bf16 v[56:59], v[160:163], v[208:211], v[56:59]
	v_mfma_f32_16x16x32_bf16 v[44:47], v[138:141], v[216:219], v[44:47]
	v_mfma_f32_16x16x32_bf16 v[40:43], v[160:163], v[216:219], v[40:43]
	v_mfma_f32_16x16x32_bf16 v[28:31], v[138:141], v[224:227], v[28:31]
	v_mfma_f32_16x16x32_bf16 v[24:27], v[160:163], v[224:227], v[24:27]
	v_mfma_f32_16x16x32_bf16 v[12:15], v[138:141], v[232:235], v[12:15]
	v_mfma_f32_16x16x32_bf16 v[8:11], v[160:163], v[232:235], v[8:11]
	v_mfma_f32_16x16x32_bf16 v[60:63], v[156:159], v[212:215], v[60:63]
	v_mfma_f32_16x16x32_bf16 v[56:59], v[164:167], v[212:215], v[56:59]
	v_mfma_f32_16x16x32_bf16 v[44:47], v[156:159], v[220:223], v[44:47]
	v_mfma_f32_16x16x32_bf16 v[40:43], v[164:167], v[220:223], v[40:43]
	v_mfma_f32_16x16x32_bf16 v[28:31], v[156:159], v[228:231], v[28:31]
	v_mfma_f32_16x16x32_bf16 v[24:27], v[164:167], v[228:231], v[24:27]
	v_mfma_f32_16x16x32_bf16 v[12:15], v[156:159], v[236:239], v[12:15]
	v_mfma_f32_16x16x32_bf16 v[8:11], v[164:167], v[236:239], v[8:11]
	v_mfma_f32_16x16x32_bf16 v[52:55], v[168:171], v[208:211], v[52:55]
	v_mfma_f32_16x16x32_bf16 v[48:51], v[176:179], v[208:211], v[48:51]
	v_mfma_f32_16x16x32_bf16 v[36:39], v[168:171], v[216:219], v[36:39]
	v_mfma_f32_16x16x32_bf16 v[32:35], v[176:179], v[216:219], v[32:35]
	v_mfma_f32_16x16x32_bf16 v[20:23], v[168:171], v[224:227], v[20:23]
	v_mfma_f32_16x16x32_bf16 v[16:19], v[176:179], v[224:227], v[16:19]
	v_mfma_f32_16x16x32_bf16 v[4:7], v[168:171], v[232:235], v[4:7]
	v_mfma_f32_16x16x32_bf16 v[0:3], v[176:179], v[232:235], v[0:3]
	v_mfma_f32_16x16x32_bf16 v[52:55], v[172:175], v[212:215], v[52:55]
	v_mfma_f32_16x16x32_bf16 v[48:51], v[204:207], v[212:215], v[48:51]
	v_mfma_f32_16x16x32_bf16 v[36:39], v[172:175], v[220:223], v[36:39]
	v_mfma_f32_16x16x32_bf16 v[32:35], v[204:207], v[220:223], v[32:35]
	v_mfma_f32_16x16x32_bf16 v[20:23], v[172:175], v[228:231], v[20:23]
	v_mfma_f32_16x16x32_bf16 v[16:19], v[204:207], v[228:231], v[16:19]
	v_mfma_f32_16x16x32_bf16 v[4:7], v[172:175], v[236:239], v[4:7]
	v_mfma_f32_16x16x32_bf16 v[0:3], v[204:207], v[236:239], v[0:3]
	s_barrier
	s_add_i32 s73, s73, 2
	s_add_u32 s58, s58, 0x100
	s_addc_u32 s59, s59, 0
	s_add_u32 s71, s71, 0x100
	s_addc_u32 s72, s72, 0
	s_cmp_gt_u32 s73, 5
	s_cbranch_scc0 .LBB0_1093
	s_setprio 0
	s_and_b64 vcc, exec, s[46:47]
	s_cbranch_vccz .LBB0_1096
	s_barrier

.Lkprio_1117:
.LBB0_1117:
	v_add_u32_e32 v164, 0x10000, v143
	v_add_u32_e32 v180, 0x14000, v143
	ds_read_b128 v[138:141], v164
	ds_read_b128 v[156:159], v164 offset:1024
	ds_read_b128 v[160:163], v164 offset:2048
	ds_read_b128 v[164:167], v164 offset:3072
	ds_read_b128 v[168:171], v180
	ds_read_b128 v[172:175], v180 offset:1024
	ds_read_b128 v[176:179], v180 offset:2048
	ds_read_b128 v[204:207], v180 offset:3072
	ds_read_b128 v[208:211], v155
	ds_read_b128 v[212:215], v155 offset:1024
	ds_read_b128 v[216:219], v155 offset:2048
	ds_read_b128 v[220:223], v155 offset:3072
	ds_read_b128 v[224:227], v155 offset:4096
	ds_read_b128 v[228:231], v155 offset:5120
	ds_read_b128 v[232:235], v155 offset:6144
	ds_read_b128 v[236:239], v155 offset:7168
	s_add_u32 s4, s54, 0xfffe0080
	s_addc_u32 s5, s55, -1
	s_add_i32 s74, 0, 0x10000
	s_cmp_eq_u32 s73, 4
	s_cselect_b32 s59, s33, s5
	s_cselect_b32 s58, s36, s4
	s_cselect_b32 s35, s47, s72
	s_cselect_b32 s34, s49, s71
	s_add_i32 s75, 0, 0x14000
	v_lshl_add_u64 v[180:181], s[54:55], 0, v[134:135]
	s_add_i32 m0, s64, 0xc000
	s_nop 0
	global_load_lds_dwordx4 v[180:181], off
	v_lshl_add_u64 v[180:181], s[54:55], 0, v[136:137]
	s_add_i32 m0, s64, 0xe000
	s_nop 0
	global_load_lds_dwordx4 v[180:181], off
	s_waitcnt vmcnt(8)
	s_waitcnt lgkmcnt(0)
	s_barrier
	s_waitcnt lgkmcnt(0)
	v_mfma_f32_16x16x32_bf16 v[124:127], v[138:141], v[208:211], v[124:127]
	v_mfma_f32_16x16x32_bf16 v[120:123], v[160:163], v[208:211], v[120:123]
	v_mfma_f32_16x16x32_bf16 v[108:111], v[138:141], v[216:219], v[108:111]
	v_mfma_f32_16x16x32_bf16 v[104:107], v[160:163], v[216:219], v[104:107]
	v_mfma_f32_16x16x32_bf16 v[92:95], v[138:141], v[224:227], v[92:95]
	v_mfma_f32_16x16x32_bf16 v[88:91], v[160:163], v[224:227], v[88:91]
	v_mfma_f32_16x16x32_bf16 v[76:79], v[138:141], v[232:235], v[76:79]
	v_mfma_f32_16x16x32_bf16 v[72:75], v[160:163], v[232:235], v[72:75]
	v_mfma_f32_16x16x32_bf16 v[124:127], v[156:159], v[212:215], v[124:127]
	v_mfma_f32_16x16x32_bf16 v[120:123], v[164:167], v[212:215], v[120:123]
	v_mfma_f32_16x16x32_bf16 v[108:111], v[156:159], v[220:223], v[108:111]
	v_mfma_f32_16x16x32_bf16 v[104:107], v[164:167], v[220:223], v[104:107]
	v_mfma_f32_16x16x32_bf16 v[92:95], v[156:159], v[228:231], v[92:95]
	v_mfma_f32_16x16x32_bf16 v[88:91], v[164:167], v[228:231], v[88:91]
	v_mfma_f32_16x16x32_bf16 v[76:79], v[156:159], v[236:239], v[76:79]
	v_mfma_f32_16x16x32_bf16 v[72:75], v[164:167], v[236:239], v[72:75]
	v_mfma_f32_16x16x32_bf16 v[116:119], v[168:171], v[208:211], v[116:119]
	v_mfma_f32_16x16x32_bf16 v[112:115], v[176:179], v[208:211], v[112:115]
	v_mfma_f32_16x16x32_bf16 v[100:103], v[168:171], v[216:219], v[100:103]
	v_mfma_f32_16x16x32_bf16 v[96:99], v[176:179], v[216:219], v[96:99]
	v_mfma_f32_16x16x32_bf16 v[84:87], v[168:171], v[224:227], v[84:87]
	v_mfma_f32_16x16x32_bf16 v[80:83], v[176:179], v[224:227], v[80:83]
	v_mfma_f32_16x16x32_bf16 v[68:71], v[168:171], v[232:235], v[68:71]
	v_mfma_f32_16x16x32_bf16 v[64:67], v[176:179], v[232:235], v[64:67]
	v_mfma_f32_16x16x32_bf16 v[116:119], v[172:175], v[212:215], v[116:119]
	v_mfma_f32_16x16x32_bf16 v[112:115], v[204:207], v[212:215], v[112:115]
	v_mfma_f32_16x16x32_bf16 v[100:103], v[172:175], v[220:223], v[100:103]
	v_mfma_f32_16x16x32_bf16 v[96:99], v[204:207], v[220:223], v[96:99]
	v_mfma_f32_16x16x32_bf16 v[84:87], v[172:175], v[228:231], v[84:87]
	v_mfma_f32_16x16x32_bf16 v[80:83], v[204:207], v[228:231], v[80:83]
	v_mfma_f32_16x16x32_bf16 v[68:71], v[172:175], v[236:239], v[68:71]
	v_mfma_f32_16x16x32_bf16 v[64:67], v[204:207], v[236:239], v[64:67]
	s_barrier
	s_add_i32 s4, s74, s63
	v_lshl_add_u64 v[180:181], s[34:35], 0, v[144:145]
	s_mov_b32 m0, s4
	ds_read_b128 v[208:211], v155 offset:16384
	ds_read_b128 v[212:215], v155 offset:17408
	ds_read_b128 v[216:219], v155 offset:18432
	ds_read_b128 v[220:223], v155 offset:19456
	ds_read_b128 v[224:227], v155 offset:20480
	ds_read_b128 v[228:231], v155 offset:21504
	ds_read_b128 v[232:235], v155 offset:22528
	ds_read_b128 v[236:239], v155 offset:23552
	global_load_lds_dwordx4 v[180:181], off
	s_add_i32 m0, s4, 0x2000
	s_add_u32 s4, s34, 0x20000
	v_lshl_add_u64 v[202:203], s[34:35], 0, v[132:133]
	s_addc_u32 s5, s35, 0
	s_add_i32 s74, s75, s63
	global_load_lds_dwordx4 v[202:203], off
	v_lshl_add_u64 v[240:241], s[4:5], 0, v[144:145]
	s_mov_b32 m0, s74
	v_lshl_add_u64 v[242:243], s[58:59], 0, v[130:131]
	global_load_lds_dwordx4 v[240:241], off
	v_lshl_add_u64 v[240:241], s[4:5], 0, v[132:133]
	s_add_i32 m0, s74, 0x2000
	s_nop 0
	global_load_lds_dwordx4 v[240:241], off
	v_lshl_add_u64 v[240:241], s[58:59], 0, v[128:129]
	s_mov_b32 m0, s64
	s_nop 0
	global_load_lds_dwordx4 v[240:241], off
	s_mov_b32 m0, s65
	s_nop 0
	global_load_lds_dwordx4 v[242:243], off
	s_waitcnt vmcnt(8)
	s_waitcnt lgkmcnt(0)
	s_barrier
	s_waitcnt lgkmcnt(0)
	v_mfma_f32_16x16x32_bf16 v[60:63], v[138:141], v[208:211], v[60:63]
	v_mfma_f32_16x16x32_bf16 v[56:59], v[160:163], v[208:211], v[56:59]
	v_mfma_f32_16x16x32_bf16 v[44:47], v[138:141], v[216:219], v[44:47]
	v_mfma_f32_16x16x32_bf16 v[40:43], v[160:163], v[216:219], v[40:43]
	v_mfma_f32_16x16x32_bf16 v[28:31], v[138:141], v[224:227], v[28:31]
	v_mfma_f32_16x16x32_bf16 v[24:27], v[160:163], v[224:227], v[24:27]
	v_mfma_f32_16x16x32_bf16 v[12:15], v[138:141], v[232:235], v[12:15]
	v_mfma_f32_16x16x32_bf16 v[8:11], v[160:163], v[232:235], v[8:11]
	v_mfma_f32_16x16x32_bf16 v[60:63], v[156:159], v[212:215], v[60:63]
	v_mfma_f32_16x16x32_bf16 v[56:59], v[164:167], v[212:215], v[56:59]
	v_mfma_f32_16x16x32_bf16 v[44:47], v[156:159], v[220:223], v[44:47]
	v_mfma_f32_16x16x32_bf16 v[40:43], v[164:167], v[220:223], v[40:43]
	v_mfma_f32_16x16x32_bf16 v[28:31], v[156:159], v[228:231], v[28:31]
	v_mfma_f32_16x16x32_bf16 v[24:27], v[164:167], v[228:231], v[24:27]
	v_mfma_f32_16x16x32_bf16 v[12:15], v[156:159], v[236:239], v[12:15]
	v_mfma_f32_16x16x32_bf16 v[8:11], v[164:167], v[236:239], v[8:11]
	v_mfma_f32_16x16x32_bf16 v[52:55], v[168:171], v[208:211], v[52:55]
	v_mfma_f32_16x16x32_bf16 v[48:51], v[176:179], v[208:211], v[48:51]
	v_mfma_f32_16x16x32_bf16 v[36:39], v[168:171], v[216:219], v[36:39]
	v_mfma_f32_16x16x32_bf16 v[32:35], v[176:179], v[216:219], v[32:35]
	v_mfma_f32_16x16x32_bf16 v[20:23], v[168:171], v[224:227], v[20:23]
	v_mfma_f32_16x16x32_bf16 v[16:19], v[176:179], v[224:227], v[16:19]
	v_mfma_f32_16x16x32_bf16 v[4:7], v[168:171], v[232:235], v[4:7]
	v_mfma_f32_16x16x32_bf16 v[0:3], v[176:179], v[232:235], v[0:3]
	v_mfma_f32_16x16x32_bf16 v[52:55], v[172:175], v[212:215], v[52:55]
	v_mfma_f32_16x16x32_bf16 v[48:51], v[204:207], v[212:215], v[48:51]
	v_mfma_f32_16x16x32_bf16 v[36:39], v[172:175], v[220:223], v[36:39]
	v_mfma_f32_16x16x32_bf16 v[32:35], v[204:207], v[220:223], v[32:35]
	v_mfma_f32_16x16x32_bf16 v[20:23], v[172:175], v[228:231], v[20:23]
	v_mfma_f32_16x16x32_bf16 v[16:19], v[204:207], v[228:231], v[16:19]
	v_mfma_f32_16x16x32_bf16 v[4:7], v[172:175], v[236:239], v[4:7]
	v_mfma_f32_16x16x32_bf16 v[0:3], v[204:207], v[236:239], v[0:3]
	s_barrier
	v_add_u32_e32 v164, 0x18000, v143
	v_add_u32_e32 v204, 0x1c000, v143
	ds_read_b128 v[138:141], v164
	ds_read_b128 v[156:159], v164 offset:1024
	ds_read_b128 v[160:163], v164 offset:2048
	ds_read_b128 v[164:167], v164 offset:3072
	ds_read_b128 v[168:171], v204
	ds_read_b128 v[172:175], v204 offset:1024
	ds_read_b128 v[176:179], v204 offset:2048
	ds_read_b128 v[204:207], v204 offset:3072
	ds_read_b128 v[208:211], v155 offset:32768
	ds_read_b128 v[212:215], v155 offset:33792
	ds_read_b128 v[216:219], v155 offset:34816
	ds_read_b128 v[220:223], v155 offset:35840
	ds_read_b128 v[224:227], v155 offset:36864
	ds_read_b128 v[228:231], v155 offset:37888
	ds_read_b128 v[232:235], v155 offset:38912
	ds_read_b128 v[236:239], v155 offset:39936
	s_add_i32 s74, 0, 0x18000
	s_add_i32 s75, 0, 0x1c000
	s_add_u32 s4, s58, 0x20000
	s_addc_u32 s5, s59, 0
	s_mov_b32 m0, s66
	v_lshl_add_u64 v[244:245], s[4:5], 0, v[128:129]
	global_load_lds_dwordx4 v[244:245], off
	v_lshl_add_u64 v[244:245], s[4:5], 0, v[130:131]
	s_mov_b32 m0, s67
	s_nop 0
	global_load_lds_dwordx4 v[244:245], off
	s_waitcnt vmcnt(8)
	s_waitcnt lgkmcnt(0)
	s_barrier
	s_waitcnt lgkmcnt(0)
	v_mfma_f32_16x16x32_bf16 v[124:127], v[138:141], v[208:211], v[124:127]
	v_mfma_f32_16x16x32_bf16 v[120:123], v[160:163], v[208:211], v[120:123]
	v_mfma_f32_16x16x32_bf16 v[108:111], v[138:141], v[216:219], v[108:111]
	v_mfma_f32_16x16x32_bf16 v[104:107], v[160:163], v[216:219], v[104:107]
	v_mfma_f32_16x16x32_bf16 v[92:95], v[138:141], v[224:227], v[92:95]
	v_mfma_f32_16x16x32_bf16 v[88:91], v[160:163], v[224:227], v[88:91]
	v_mfma_f32_16x16x32_bf16 v[76:79], v[138:141], v[232:235], v[76:79]
	v_mfma_f32_16x16x32_bf16 v[72:75], v[160:163], v[232:235], v[72:75]
	v_mfma_f32_16x16x32_bf16 v[124:127], v[156:159], v[212:215], v[124:127]
	v_mfma_f32_16x16x32_bf16 v[120:123], v[164:167], v[212:215], v[120:123]
	v_mfma_f32_16x16x32_bf16 v[108:111], v[156:159], v[220:223], v[108:111]
	v_mfma_f32_16x16x32_bf16 v[104:107], v[164:167], v[220:223], v[104:107]
	v_mfma_f32_16x16x32_bf16 v[92:95], v[156:159], v[228:231], v[92:95]
	v_mfma_f32_16x16x32_bf16 v[88:91], v[164:167], v[228:231], v[88:91]
	v_mfma_f32_16x16x32_bf16 v[76:79], v[156:159], v[236:239], v[76:79]
	v_mfma_f32_16x16x32_bf16 v[72:75], v[164:167], v[236:239], v[72:75]
	v_mfma_f32_16x16x32_bf16 v[116:119], v[168:171], v[208:211], v[116:119]
	v_mfma_f32_16x16x32_bf16 v[112:115], v[176:179], v[208:211], v[112:115]
	v_mfma_f32_16x16x32_bf16 v[100:103], v[168:171], v[216:219], v[100:103]
	v_mfma_f32_16x16x32_bf16 v[96:99], v[176:179], v[216:219], v[96:99]
	v_mfma_f32_16x16x32_bf16 v[84:87], v[168:171], v[224:227], v[84:87]
	v_mfma_f32_16x16x32_bf16 v[80:83], v[176:179], v[224:227], v[80:83]
	v_mfma_f32_16x16x32_bf16 v[68:71], v[168:171], v[232:235], v[68:71]
	v_mfma_f32_16x16x32_bf16 v[64:67], v[176:179], v[232:235], v[64:67]
	v_mfma_f32_16x16x32_bf16 v[116:119], v[172:175], v[212:215], v[116:119]
	v_mfma_f32_16x16x32_bf16 v[112:115], v[204:207], v[212:215], v[112:115]
	v_mfma_f32_16x16x32_bf16 v[100:103], v[172:175], v[220:223], v[100:103]
	v_mfma_f32_16x16x32_bf16 v[96:99], v[204:207], v[220:223], v[96:99]
	v_mfma_f32_16x16x32_bf16 v[84:87], v[172:175], v[228:231], v[84:87]
	v_mfma_f32_16x16x32_bf16 v[80:83], v[204:207], v[228:231], v[80:83]
	v_mfma_f32_16x16x32_bf16 v[68:71], v[172:175], v[236:239], v[68:71]
	v_mfma_f32_16x16x32_bf16 v[64:67], v[204:207], v[236:239], v[64:67]
	s_barrier
	s_add_i32 s4, s74, s63
	v_lshl_add_u64 v[180:181], v[180:181], 0, s[26:27]
	s_mov_b32 m0, s4
	ds_read_b128 v[208:211], v155 offset:49152
	ds_read_b128 v[212:215], v155 offset:50176
	ds_read_b128 v[216:219], v155 offset:51200
	ds_read_b128 v[220:223], v155 offset:52224
	ds_read_b128 v[224:227], v155 offset:53248
	ds_read_b128 v[228:231], v155 offset:54272
	ds_read_b128 v[232:235], v155 offset:55296
	ds_read_b128 v[236:239], v155 offset:56320
	global_load_lds_dwordx4 v[180:181], off
	s_add_i32 m0, s4, 0x2000
	s_add_u32 s4, s34, 0x20080
	v_lshl_add_u64 v[180:181], v[202:203], 0, s[26:27]
	s_addc_u32 s5, s35, 0
	s_add_i32 s34, s75, s63
	global_load_lds_dwordx4 v[180:181], off
	v_lshl_add_u64 v[180:181], s[4:5], 0, v[144:145]
	s_mov_b32 m0, s34
	s_nop 0
	global_load_lds_dwordx4 v[180:181], off
	v_lshl_add_u64 v[180:181], s[4:5], 0, v[132:133]
	s_add_i32 m0, s34, 0x2000
	s_nop 0
	global_load_lds_dwordx4 v[180:181], off
	v_lshl_add_u64 v[180:181], v[240:241], 0, s[26:27]
	s_mov_b32 m0, s68
	s_nop 0
	global_load_lds_dwordx4 v[180:181], off
	v_lshl_add_u64 v[180:181], v[242:243], 0, s[26:27]
	s_mov_b32 m0, s69
	s_nop 0
	global_load_lds_dwordx4 v[180:181], off
	s_waitcnt vmcnt(8)
	s_waitcnt lgkmcnt(0)
	s_barrier
	s_waitcnt lgkmcnt(0)
	v_mfma_f32_16x16x32_bf16 v[60:63], v[138:141], v[208:211], v[60:63]
	v_mfma_f32_16x16x32_bf16 v[56:59], v[160:163], v[208:211], v[56:59]
	v_mfma_f32_16x16x32_bf16 v[44:47], v[138:141], v[216:219], v[44:47]
	v_mfma_f32_16x16x32_bf16 v[40:43], v[160:163], v[216:219], v[40:43]
	v_mfma_f32_16x16x32_bf16 v[28:31], v[138:141], v[224:227], v[28:31]
	v_mfma_f32_16x16x32_bf16 v[24:27], v[160:163], v[224:227], v[24:27]
	v_mfma_f32_16x16x32_bf16 v[12:15], v[138:141], v[232:235], v[12:15]
	v_mfma_f32_16x16x32_bf16 v[8:11], v[160:163], v[232:235], v[8:11]
	v_mfma_f32_16x16x32_bf16 v[60:63], v[156:159], v[212:215], v[60:63]
	v_mfma_f32_16x16x32_bf16 v[56:59], v[164:167], v[212:215], v[56:59]
	v_mfma_f32_16x16x32_bf16 v[44:47], v[156:159], v[220:223], v[44:47]
	v_mfma_f32_16x16x32_bf16 v[40:43], v[164:167], v[220:223], v[40:43]
	v_mfma_f32_16x16x32_bf16 v[28:31], v[156:159], v[228:231], v[28:31]
	v_mfma_f32_16x16x32_bf16 v[24:27], v[164:167], v[228:231], v[24:27]
	v_mfma_f32_16x16x32_bf16 v[12:15], v[156:159], v[236:239], v[12:15]
	v_mfma_f32_16x16x32_bf16 v[8:11], v[164:167], v[236:239], v[8:11]
	v_mfma_f32_16x16x32_bf16 v[52:55], v[168:171], v[208:211], v[52:55]
	v_mfma_f32_16x16x32_bf16 v[48:51], v[176:179], v[208:211], v[48:51]
	v_mfma_f32_16x16x32_bf16 v[36:39], v[168:171], v[216:219], v[36:39]
	v_mfma_f32_16x16x32_bf16 v[32:35], v[176:179], v[216:219], v[32:35]
	v_mfma_f32_16x16x32_bf16 v[20:23], v[168:171], v[224:227], v[20:23]
	v_mfma_f32_16x16x32_bf16 v[16:19], v[176:179], v[224:227], v[16:19]
	v_mfma_f32_16x16x32_bf16 v[4:7], v[168:171], v[232:235], v[4:7]
	v_mfma_f32_16x16x32_bf16 v[0:3], v[176:179], v[232:235], v[0:3]
	v_mfma_f32_16x16x32_bf16 v[52:55], v[172:175], v[212:215], v[52:55]
	v_mfma_f32_16x16x32_bf16 v[48:51], v[204:207], v[212:215], v[48:51]
	v_mfma_f32_16x16x32_bf16 v[36:39], v[172:175], v[220:223], v[36:39]
	v_mfma_f32_16x16x32_bf16 v[32:35], v[204:207], v[220:223], v[32:35]
	v_mfma_f32_16x16x32_bf16 v[20:23], v[172:175], v[228:231], v[20:23]
	v_mfma_f32_16x16x32_bf16 v[16:19], v[204:207], v[228:231], v[16:19]
	v_mfma_f32_16x16x32_bf16 v[4:7], v[172:175], v[236:239], v[4:7]
	v_mfma_f32_16x16x32_bf16 v[0:3], v[204:207], v[236:239], v[0:3]
	s_barrier
	s_add_i32 s73, s73, 2
	s_add_u32 s54, s54, 0x100
	s_addc_u32 s55, s55, 0
	s_add_u32 s71, s71, 0x100
	s_addc_u32 s72, s72, 0
	s_cmp_gt_u32 s73, 5
	s_cbranch_scc0 .LBB0_1117
	s_setprio 0
	s_and_b64 vcc, exec, s[44:45]
	s_cbranch_vccz .LBB0_1120
	s_barrier

.Lkprio_1207:
.LBB0_1207:
	v_add_u32_e32 v142, 0x10000, v160
	ds_read_b128 v[138:141], v142
	ds_read_b128 v[154:157], v142 offset:1024
	ds_read_b128 v[172:175], v142 offset:2048
	ds_read_b128 v[176:179], v142 offset:3072
	v_add_u32_e32 v142, 0x14000, v160
	ds_read_b128 v[204:207], v142
	ds_read_b128 v[208:211], v142 offset:1024
	ds_read_b128 v[212:215], v142 offset:2048
	ds_read_b128 v[216:219], v142 offset:3072
	ds_read_b128 v[220:223], v170
	ds_read_b128 v[224:227], v170 offset:1024
	ds_read_b128 v[228:231], v170 offset:2048
	ds_read_b128 v[232:235], v170 offset:3072
	ds_read_b128 v[236:239], v170 offset:4096
	ds_read_b128 v[240:243], v170 offset:5120
	ds_read_b128 v[244:247], v170 offset:6144
	ds_read_b128 v[248:251], v170 offset:7168
	s_add_u32 s62, s60, 0x100
	s_addc_u32 s63, s61, 0
	s_add_i32 s4, 0, 0x10000
	s_cmp_eq_u32 s29, 12
	s_cselect_b32 s65, s55, s63
	s_cselect_b32 s64, s54, s62
	s_cselect_b32 s35, s59, s28
	s_cselect_b32 s34, s58, s3
	s_add_i32 s45, 0, 0x14000
	v_lshl_add_u64 v[142:143], s[60:61], 0, v[134:135]
	s_add_i32 m0, s69, 0xc000
	s_nop 0
	global_load_lds_dwordx4 v[142:143], off
	v_lshl_add_u64 v[142:143], s[60:61], 0, v[136:137]
	s_add_i32 m0, s69, 0xe000
	s_nop 0
	global_load_lds_dwordx4 v[142:143], off
	s_waitcnt vmcnt(8)
	s_waitcnt lgkmcnt(0)
	s_barrier
	s_waitcnt lgkmcnt(0)
	v_mfma_f32_16x16x32_bf16 v[124:127], v[138:141], v[220:223], v[124:127]
	v_mfma_f32_16x16x32_bf16 v[120:123], v[172:175], v[220:223], v[120:123]
	v_mfma_f32_16x16x32_bf16 v[108:111], v[138:141], v[228:231], v[108:111]
	v_mfma_f32_16x16x32_bf16 v[104:107], v[172:175], v[228:231], v[104:107]
	v_mfma_f32_16x16x32_bf16 v[92:95], v[138:141], v[236:239], v[92:95]
	v_mfma_f32_16x16x32_bf16 v[88:91], v[172:175], v[236:239], v[88:91]
	v_mfma_f32_16x16x32_bf16 v[76:79], v[138:141], v[244:247], v[76:79]
	v_mfma_f32_16x16x32_bf16 v[72:75], v[172:175], v[244:247], v[72:75]
	v_mfma_f32_16x16x32_bf16 v[124:127], v[154:157], v[224:227], v[124:127]
	v_mfma_f32_16x16x32_bf16 v[120:123], v[176:179], v[224:227], v[120:123]
	v_mfma_f32_16x16x32_bf16 v[108:111], v[154:157], v[232:235], v[108:111]
	v_mfma_f32_16x16x32_bf16 v[104:107], v[176:179], v[232:235], v[104:107]
	v_mfma_f32_16x16x32_bf16 v[92:95], v[154:157], v[240:243], v[92:95]
	v_mfma_f32_16x16x32_bf16 v[88:91], v[176:179], v[240:243], v[88:91]
	v_mfma_f32_16x16x32_bf16 v[76:79], v[154:157], v[248:251], v[76:79]
	v_mfma_f32_16x16x32_bf16 v[72:75], v[176:179], v[248:251], v[72:75]
	v_mfma_f32_16x16x32_bf16 v[116:119], v[204:207], v[220:223], v[116:119]
	v_mfma_f32_16x16x32_bf16 v[112:115], v[212:215], v[220:223], v[112:115]
	v_mfma_f32_16x16x32_bf16 v[100:103], v[204:207], v[228:231], v[100:103]
	v_mfma_f32_16x16x32_bf16 v[96:99], v[212:215], v[228:231], v[96:99]
	v_mfma_f32_16x16x32_bf16 v[84:87], v[204:207], v[236:239], v[84:87]
	v_mfma_f32_16x16x32_bf16 v[80:83], v[212:215], v[236:239], v[80:83]
	v_mfma_f32_16x16x32_bf16 v[68:71], v[204:207], v[244:247], v[68:71]
	v_mfma_f32_16x16x32_bf16 v[64:67], v[212:215], v[244:247], v[64:67]
	v_mfma_f32_16x16x32_bf16 v[116:119], v[208:211], v[224:227], v[116:119]
	v_mfma_f32_16x16x32_bf16 v[112:115], v[216:219], v[224:227], v[112:115]
	v_mfma_f32_16x16x32_bf16 v[100:103], v[208:211], v[232:235], v[100:103]
	v_mfma_f32_16x16x32_bf16 v[96:99], v[216:219], v[232:235], v[96:99]
	v_mfma_f32_16x16x32_bf16 v[84:87], v[208:211], v[240:243], v[84:87]
	v_mfma_f32_16x16x32_bf16 v[80:83], v[216:219], v[240:243], v[80:83]
	v_mfma_f32_16x16x32_bf16 v[68:71], v[208:211], v[248:251], v[68:71]
	v_mfma_f32_16x16x32_bf16 v[64:67], v[216:219], v[248:251], v[64:67]
	s_barrier
	s_add_i32 s4, s4, s33
	v_lshl_add_u64 v[142:143], s[34:35], 0, v[128:129]
	s_mov_b32 m0, s4
	ds_read_b128 v[220:223], v170 offset:16384
	ds_read_b128 v[224:227], v170 offset:17408
	ds_read_b128 v[228:231], v170 offset:18432
	ds_read_b128 v[232:235], v170 offset:19456
	ds_read_b128 v[236:239], v170 offset:20480
	ds_read_b128 v[240:243], v170 offset:21504
	ds_read_b128 v[244:247], v170 offset:22528
	ds_read_b128 v[248:251], v170 offset:23552
	global_load_lds_dwordx4 v[142:143], off
	s_add_i32 m0, s4, 0x2000
	s_add_u32 s4, s34, 0x40000
	v_lshl_add_u64 v[158:159], s[34:35], 0, v[130:131]
	s_addc_u32 s5, s35, 0
	s_add_i32 s45, s45, s33
	global_load_lds_dwordx4 v[158:159], off
	v_lshl_add_u64 v[180:181], s[4:5], 0, v[128:129]
	s_mov_b32 m0, s45
	v_lshl_add_u64 v[202:203], s[64:65], 0, v[130:131]
	global_load_lds_dwordx4 v[180:181], off
	v_lshl_add_u64 v[180:181], s[4:5], 0, v[130:131]
	s_add_i32 m0, s45, 0x2000
	s_nop 0
	global_load_lds_dwordx4 v[180:181], off
	v_lshl_add_u64 v[180:181], s[64:65], 0, v[128:129]
	s_mov_b32 m0, s69
	s_nop 0
	global_load_lds_dwordx4 v[180:181], off
	s_mov_b32 m0, s70
	s_nop 0
	global_load_lds_dwordx4 v[202:203], off
	s_waitcnt vmcnt(8)
	s_waitcnt lgkmcnt(0)
	s_barrier
	s_waitcnt lgkmcnt(0)
	v_mfma_f32_16x16x32_bf16 v[60:63], v[138:141], v[220:223], v[60:63]
	v_mfma_f32_16x16x32_bf16 v[56:59], v[172:175], v[220:223], v[56:59]
	v_mfma_f32_16x16x32_bf16 v[44:47], v[138:141], v[228:231], v[44:47]
	v_mfma_f32_16x16x32_bf16 v[40:43], v[172:175], v[228:231], v[40:43]
	v_mfma_f32_16x16x32_bf16 v[28:31], v[138:141], v[236:239], v[28:31]
	v_mfma_f32_16x16x32_bf16 v[24:27], v[172:175], v[236:239], v[24:27]
	v_mfma_f32_16x16x32_bf16 v[12:15], v[138:141], v[244:247], v[12:15]
	v_mfma_f32_16x16x32_bf16 v[8:11], v[172:175], v[244:247], v[8:11]
	v_mfma_f32_16x16x32_bf16 v[60:63], v[154:157], v[224:227], v[60:63]
	v_mfma_f32_16x16x32_bf16 v[56:59], v[176:179], v[224:227], v[56:59]
	v_mfma_f32_16x16x32_bf16 v[44:47], v[154:157], v[232:235], v[44:47]
	v_mfma_f32_16x16x32_bf16 v[40:43], v[176:179], v[232:235], v[40:43]
	v_mfma_f32_16x16x32_bf16 v[28:31], v[154:157], v[240:243], v[28:31]
	v_mfma_f32_16x16x32_bf16 v[24:27], v[176:179], v[240:243], v[24:27]
	v_mfma_f32_16x16x32_bf16 v[12:15], v[154:157], v[248:251], v[12:15]
	v_mfma_f32_16x16x32_bf16 v[8:11], v[176:179], v[248:251], v[8:11]
	v_mfma_f32_16x16x32_bf16 v[52:55], v[204:207], v[220:223], v[52:55]
	v_mfma_f32_16x16x32_bf16 v[48:51], v[212:215], v[220:223], v[48:51]
	v_mfma_f32_16x16x32_bf16 v[36:39], v[204:207], v[228:231], v[36:39]
	v_mfma_f32_16x16x32_bf16 v[32:35], v[212:215], v[228:231], v[32:35]
	v_mfma_f32_16x16x32_bf16 v[20:23], v[204:207], v[236:239], v[20:23]
	v_mfma_f32_16x16x32_bf16 v[16:19], v[212:215], v[236:239], v[16:19]
	v_mfma_f32_16x16x32_bf16 v[4:7], v[204:207], v[244:247], v[4:7]
	v_mfma_f32_16x16x32_bf16 v[0:3], v[212:215], v[244:247], v[0:3]
	v_mfma_f32_16x16x32_bf16 v[52:55], v[208:211], v[224:227], v[52:55]
	v_mfma_f32_16x16x32_bf16 v[48:51], v[216:219], v[224:227], v[48:51]
	v_mfma_f32_16x16x32_bf16 v[36:39], v[208:211], v[232:235], v[36:39]
	v_mfma_f32_16x16x32_bf16 v[32:35], v[216:219], v[232:235], v[32:35]
	v_mfma_f32_16x16x32_bf16 v[20:23], v[208:211], v[240:243], v[20:23]
	v_mfma_f32_16x16x32_bf16 v[16:19], v[216:219], v[240:243], v[16:19]
	v_mfma_f32_16x16x32_bf16 v[4:7], v[208:211], v[248:251], v[4:7]
	v_mfma_f32_16x16x32_bf16 v[0:3], v[216:219], v[248:251], v[0:3]
	s_barrier
	v_add_u32_e32 v144, 0x18000, v160
	ds_read_b128 v[138:141], v144
	ds_read_b128 v[154:157], v144 offset:1024
	ds_read_b128 v[172:175], v144 offset:2048
	ds_read_b128 v[176:179], v144 offset:3072
	v_add_u32_e32 v144, 0x1c000, v160
	ds_read_b128 v[204:207], v144
	ds_read_b128 v[208:211], v144 offset:1024
	ds_read_b128 v[212:215], v144 offset:2048
	ds_read_b128 v[216:219], v144 offset:3072
	ds_read_b128 v[220:223], v170 offset:32768
	ds_read_b128 v[224:227], v170 offset:33792
	ds_read_b128 v[228:231], v170 offset:34816
	ds_read_b128 v[232:235], v170 offset:35840
	ds_read_b128 v[236:239], v170 offset:36864
	ds_read_b128 v[240:243], v170 offset:37888
	ds_read_b128 v[244:247], v170 offset:38912
	ds_read_b128 v[248:251], v170 offset:39936
	s_add_i32 s45, 0, 0x18000
	s_add_i32 s51, 0, 0x1c000
	s_add_u32 s4, s64, 0x40000
	s_addc_u32 s5, s65, 0
	s_mov_b32 m0, s71
	v_lshl_add_u64 v[252:253], s[4:5], 0, v[128:129]
	global_load_lds_dwordx4 v[252:253], off
	v_lshl_add_u64 v[252:253], s[4:5], 0, v[130:131]
	s_mov_b32 m0, s72
	s_nop 0
	global_load_lds_dwordx4 v[252:253], off
	s_waitcnt vmcnt(8)
	s_waitcnt lgkmcnt(0)
	s_barrier
	s_waitcnt lgkmcnt(0)
	v_mfma_f32_16x16x32_bf16 v[124:127], v[138:141], v[220:223], v[124:127]
	v_mfma_f32_16x16x32_bf16 v[120:123], v[172:175], v[220:223], v[120:123]
	v_mfma_f32_16x16x32_bf16 v[108:111], v[138:141], v[228:231], v[108:111]
	v_mfma_f32_16x16x32_bf16 v[104:107], v[172:175], v[228:231], v[104:107]
	v_mfma_f32_16x16x32_bf16 v[92:95], v[138:141], v[236:239], v[92:95]
	v_mfma_f32_16x16x32_bf16 v[88:91], v[172:175], v[236:239], v[88:91]
	v_mfma_f32_16x16x32_bf16 v[76:79], v[138:141], v[244:247], v[76:79]
	v_mfma_f32_16x16x32_bf16 v[72:75], v[172:175], v[244:247], v[72:75]
	v_mfma_f32_16x16x32_bf16 v[124:127], v[154:157], v[224:227], v[124:127]
	v_mfma_f32_16x16x32_bf16 v[120:123], v[176:179], v[224:227], v[120:123]
	v_mfma_f32_16x16x32_bf16 v[108:111], v[154:157], v[232:235], v[108:111]
	v_mfma_f32_16x16x32_bf16 v[104:107], v[176:179], v[232:235], v[104:107]
	v_mfma_f32_16x16x32_bf16 v[92:95], v[154:157], v[240:243], v[92:95]
	v_mfma_f32_16x16x32_bf16 v[88:91], v[176:179], v[240:243], v[88:91]
	v_mfma_f32_16x16x32_bf16 v[76:79], v[154:157], v[248:251], v[76:79]
	v_mfma_f32_16x16x32_bf16 v[72:75], v[176:179], v[248:251], v[72:75]
	v_mfma_f32_16x16x32_bf16 v[116:119], v[204:207], v[220:223], v[116:119]
	v_mfma_f32_16x16x32_bf16 v[112:115], v[212:215], v[220:223], v[112:115]
	v_mfma_f32_16x16x32_bf16 v[100:103], v[204:207], v[228:231], v[100:103]
	v_mfma_f32_16x16x32_bf16 v[96:99], v[212:215], v[228:231], v[96:99]
	v_mfma_f32_16x16x32_bf16 v[84:87], v[204:207], v[236:239], v[84:87]
	v_mfma_f32_16x16x32_bf16 v[80:83], v[212:215], v[236:239], v[80:83]
	v_mfma_f32_16x16x32_bf16 v[68:71], v[204:207], v[244:247], v[68:71]
	v_mfma_f32_16x16x32_bf16 v[64:67], v[212:215], v[244:247], v[64:67]
	v_mfma_f32_16x16x32_bf16 v[116:119], v[208:211], v[224:227], v[116:119]
	v_mfma_f32_16x16x32_bf16 v[112:115], v[216:219], v[224:227], v[112:115]
	v_mfma_f32_16x16x32_bf16 v[100:103], v[208:211], v[232:235], v[100:103]
	v_mfma_f32_16x16x32_bf16 v[96:99], v[216:219], v[232:235], v[96:99]
	v_mfma_f32_16x16x32_bf16 v[84:87], v[208:211], v[240:243], v[84:87]
	v_mfma_f32_16x16x32_bf16 v[80:83], v[216:219], v[240:243], v[80:83]
	v_mfma_f32_16x16x32_bf16 v[68:71], v[208:211], v[248:251], v[68:71]
	v_mfma_f32_16x16x32_bf16 v[64:67], v[216:219], v[248:251], v[64:67]
	s_barrier
	s_add_i32 s4, s45, s33
	v_lshl_add_u64 v[142:143], v[142:143], 0, s[26:27]
	s_mov_b32 m0, s4
	ds_read_b128 v[220:223], v170 offset:49152
	ds_read_b128 v[224:227], v170 offset:50176
	ds_read_b128 v[228:231], v170 offset:51200
	ds_read_b128 v[232:235], v170 offset:52224
	ds_read_b128 v[236:239], v170 offset:53248
	ds_read_b128 v[240:243], v170 offset:54272
	ds_read_b128 v[244:247], v170 offset:55296
	ds_read_b128 v[248:251], v170 offset:56320
	global_load_lds_dwordx4 v[142:143], off
	s_add_i32 m0, s4, 0x2000
	s_add_u32 s4, s34, 0x40080
	v_lshl_add_u64 v[142:143], v[158:159], 0, s[26:27]
	s_addc_u32 s5, s35, 0
	s_add_i32 s34, s51, s33
	global_load_lds_dwordx4 v[142:143], off
	v_lshl_add_u64 v[142:143], s[4:5], 0, v[128:129]
	s_mov_b32 m0, s34
	s_nop 0
	global_load_lds_dwordx4 v[142:143], off
	v_lshl_add_u64 v[142:143], s[4:5], 0, v[130:131]
	s_add_i32 m0, s34, 0x2000
	s_nop 0
	global_load_lds_dwordx4 v[142:143], off
	v_lshl_add_u64 v[142:143], v[180:181], 0, s[26:27]
	s_mov_b32 m0, s73
	s_nop 0
	global_load_lds_dwordx4 v[142:143], off
	v_lshl_add_u64 v[142:143], v[202:203], 0, s[26:27]
	s_mov_b32 m0, s74
	s_nop 0
	global_load_lds_dwordx4 v[142:143], off
	s_waitcnt vmcnt(8)
	s_waitcnt lgkmcnt(0)
	s_barrier
	s_waitcnt lgkmcnt(0)
	v_mfma_f32_16x16x32_bf16 v[60:63], v[138:141], v[220:223], v[60:63]
	v_mfma_f32_16x16x32_bf16 v[56:59], v[172:175], v[220:223], v[56:59]
	v_mfma_f32_16x16x32_bf16 v[44:47], v[138:141], v[228:231], v[44:47]
	v_mfma_f32_16x16x32_bf16 v[40:43], v[172:175], v[228:231], v[40:43]
	v_mfma_f32_16x16x32_bf16 v[28:31], v[138:141], v[236:239], v[28:31]
	v_mfma_f32_16x16x32_bf16 v[24:27], v[172:175], v[236:239], v[24:27]
	v_mfma_f32_16x16x32_bf16 v[12:15], v[138:141], v[244:247], v[12:15]
	v_mfma_f32_16x16x32_bf16 v[8:11], v[172:175], v[244:247], v[8:11]
	v_mfma_f32_16x16x32_bf16 v[60:63], v[154:157], v[224:227], v[60:63]
	v_mfma_f32_16x16x32_bf16 v[56:59], v[176:179], v[224:227], v[56:59]
	v_mfma_f32_16x16x32_bf16 v[44:47], v[154:157], v[232:235], v[44:47]
	v_mfma_f32_16x16x32_bf16 v[40:43], v[176:179], v[232:235], v[40:43]
	v_mfma_f32_16x16x32_bf16 v[28:31], v[154:157], v[240:243], v[28:31]
	v_mfma_f32_16x16x32_bf16 v[24:27], v[176:179], v[240:243], v[24:27]
	v_mfma_f32_16x16x32_bf16 v[12:15], v[154:157], v[248:251], v[12:15]
	v_mfma_f32_16x16x32_bf16 v[8:11], v[176:179], v[248:251], v[8:11]
	v_mfma_f32_16x16x32_bf16 v[52:55], v[204:207], v[220:223], v[52:55]
	v_mfma_f32_16x16x32_bf16 v[48:51], v[212:215], v[220:223], v[48:51]
	v_mfma_f32_16x16x32_bf16 v[36:39], v[204:207], v[228:231], v[36:39]
	v_mfma_f32_16x16x32_bf16 v[32:35], v[212:215], v[228:231], v[32:35]
	v_mfma_f32_16x16x32_bf16 v[20:23], v[204:207], v[236:239], v[20:23]
	v_mfma_f32_16x16x32_bf16 v[16:19], v[212:215], v[236:239], v[16:19]
	v_mfma_f32_16x16x32_bf16 v[4:7], v[204:207], v[244:247], v[4:7]
	v_mfma_f32_16x16x32_bf16 v[0:3], v[212:215], v[244:247], v[0:3]
	v_mfma_f32_16x16x32_bf16 v[52:55], v[208:211], v[224:227], v[52:55]
	v_mfma_f32_16x16x32_bf16 v[48:51], v[216:219], v[224:227], v[48:51]
	v_mfma_f32_16x16x32_bf16 v[36:39], v[208:211], v[232:235], v[36:39]
	v_mfma_f32_16x16x32_bf16 v[32:35], v[216:219], v[232:235], v[32:35]
	v_mfma_f32_16x16x32_bf16 v[20:23], v[208:211], v[240:243], v[20:23]
	v_mfma_f32_16x16x32_bf16 v[16:19], v[216:219], v[240:243], v[16:19]
	v_mfma_f32_16x16x32_bf16 v[4:7], v[208:211], v[248:251], v[4:7]
	v_mfma_f32_16x16x32_bf16 v[0:3], v[216:219], v[248:251], v[0:3]
	s_barrier
	s_add_i32 s29, s29, 2
	s_add_u32 s3, s3, 0x100
	s_addc_u32 s28, s28, 0
	s_cmp_gt_u32 s29, 13
	s_mov_b64 s[60:61], s[62:63]
	s_cbranch_scc0 .LBB0_1207
	s_setprio 0
	s_and_b64 vcc, exec, s[48:49]
	s_cbranch_vccz .LBB0_1210
	s_barrier

.Lkprio_1305:
.LBB0_1305:
	v_add_u32_e32 v164, 0x10000, v143
	v_add_u32_e32 v180, 0x14000, v143
	ds_read_b128 v[138:141], v164
	ds_read_b128 v[156:159], v164 offset:1024
	ds_read_b128 v[160:163], v164 offset:2048
	ds_read_b128 v[164:167], v164 offset:3072
	ds_read_b128 v[168:171], v180
	ds_read_b128 v[172:175], v180 offset:1024
	ds_read_b128 v[176:179], v180 offset:2048
	ds_read_b128 v[204:207], v180 offset:3072
	ds_read_b128 v[208:211], v155
	ds_read_b128 v[212:215], v155 offset:1024
	ds_read_b128 v[216:219], v155 offset:2048
	ds_read_b128 v[220:223], v155 offset:3072
	ds_read_b128 v[224:227], v155 offset:4096
	ds_read_b128 v[228:231], v155 offset:5120
	ds_read_b128 v[232:235], v155 offset:6144
	ds_read_b128 v[236:239], v155 offset:7168
	s_add_u32 s4, s2, 0xfffc0080
	s_addc_u32 s5, s3, -1
	s_add_i32 s74, 0, 0x10000
	s_cmp_eq_u32 s73, 12
	s_cselect_b32 s61, s36, s5
	s_cselect_b32 s60, s51, s4
	s_cselect_b32 s35, s49, s72
	s_cselect_b32 s34, s70, s71
	s_add_i32 s75, 0, 0x14000
	v_lshl_add_u64 v[180:181], s[2:3], 0, v[134:135]
	s_add_i32 m0, s59, 0xc000
	s_nop 0
	global_load_lds_dwordx4 v[180:181], off
	v_lshl_add_u64 v[180:181], s[2:3], 0, v[136:137]
	s_add_i32 m0, s59, 0xe000
	s_nop 0
	global_load_lds_dwordx4 v[180:181], off
	s_waitcnt vmcnt(8)
	s_waitcnt lgkmcnt(0)
	s_barrier
	s_waitcnt lgkmcnt(0)
	v_mfma_f32_16x16x32_bf16 v[124:127], v[138:141], v[208:211], v[124:127]
	v_mfma_f32_16x16x32_bf16 v[120:123], v[160:163], v[208:211], v[120:123]
	v_mfma_f32_16x16x32_bf16 v[108:111], v[138:141], v[216:219], v[108:111]
	v_mfma_f32_16x16x32_bf16 v[104:107], v[160:163], v[216:219], v[104:107]
	v_mfma_f32_16x16x32_bf16 v[92:95], v[138:141], v[224:227], v[92:95]
	v_mfma_f32_16x16x32_bf16 v[88:91], v[160:163], v[224:227], v[88:91]
	v_mfma_f32_16x16x32_bf16 v[76:79], v[138:141], v[232:235], v[76:79]
	v_mfma_f32_16x16x32_bf16 v[72:75], v[160:163], v[232:235], v[72:75]
	v_mfma_f32_16x16x32_bf16 v[124:127], v[156:159], v[212:215], v[124:127]
	v_mfma_f32_16x16x32_bf16 v[120:123], v[164:167], v[212:215], v[120:123]
	v_mfma_f32_16x16x32_bf16 v[108:111], v[156:159], v[220:223], v[108:111]
	v_mfma_f32_16x16x32_bf16 v[104:107], v[164:167], v[220:223], v[104:107]
	v_mfma_f32_16x16x32_bf16 v[92:95], v[156:159], v[228:231], v[92:95]
	v_mfma_f32_16x16x32_bf16 v[88:91], v[164:167], v[228:231], v[88:91]
	v_mfma_f32_16x16x32_bf16 v[76:79], v[156:159], v[236:239], v[76:79]
	v_mfma_f32_16x16x32_bf16 v[72:75], v[164:167], v[236:239], v[72:75]
	v_mfma_f32_16x16x32_bf16 v[116:119], v[168:171], v[208:211], v[116:119]
	v_mfma_f32_16x16x32_bf16 v[112:115], v[176:179], v[208:211], v[112:115]
	v_mfma_f32_16x16x32_bf16 v[100:103], v[168:171], v[216:219], v[100:103]
	v_mfma_f32_16x16x32_bf16 v[96:99], v[176:179], v[216:219], v[96:99]
	v_mfma_f32_16x16x32_bf16 v[84:87], v[168:171], v[224:227], v[84:87]
	v_mfma_f32_16x16x32_bf16 v[80:83], v[176:179], v[224:227], v[80:83]
	v_mfma_f32_16x16x32_bf16 v[68:71], v[168:171], v[232:235], v[68:71]
	v_mfma_f32_16x16x32_bf16 v[64:67], v[176:179], v[232:235], v[64:67]
	v_mfma_f32_16x16x32_bf16 v[116:119], v[172:175], v[212:215], v[116:119]
	v_mfma_f32_16x16x32_bf16 v[112:115], v[204:207], v[212:215], v[112:115]
	v_mfma_f32_16x16x32_bf16 v[100:103], v[172:175], v[220:223], v[100:103]
	v_mfma_f32_16x16x32_bf16 v[96:99], v[204:207], v[220:223], v[96:99]
	v_mfma_f32_16x16x32_bf16 v[84:87], v[172:175], v[228:231], v[84:87]
	v_mfma_f32_16x16x32_bf16 v[80:83], v[204:207], v[228:231], v[80:83]
	v_mfma_f32_16x16x32_bf16 v[68:71], v[172:175], v[236:239], v[68:71]
	v_mfma_f32_16x16x32_bf16 v[64:67], v[204:207], v[236:239], v[64:67]
	s_barrier
	s_add_i32 s4, s74, s1
	v_lshl_add_u64 v[180:181], s[34:35], 0, v[144:145]
	s_mov_b32 m0, s4
	ds_read_b128 v[208:211], v155 offset:16384
	ds_read_b128 v[212:215], v155 offset:17408
	ds_read_b128 v[216:219], v155 offset:18432
	ds_read_b128 v[220:223], v155 offset:19456
	ds_read_b128 v[224:227], v155 offset:20480
	ds_read_b128 v[228:231], v155 offset:21504
	ds_read_b128 v[232:235], v155 offset:22528
	ds_read_b128 v[236:239], v155 offset:23552
	global_load_lds_dwordx4 v[180:181], off
	s_add_i32 m0, s4, 0x2000
	s_add_u32 s4, s34, 0x40000
	v_lshl_add_u64 v[202:203], s[34:35], 0, v[128:129]
	s_addc_u32 s5, s35, 0
	s_add_i32 s74, s75, s1
	global_load_lds_dwordx4 v[202:203], off
	v_lshl_add_u64 v[240:241], s[4:5], 0, v[144:145]
	s_mov_b32 m0, s74
	v_lshl_add_u64 v[242:243], s[60:61], 0, v[130:131]
	global_load_lds_dwordx4 v[240:241], off
	v_lshl_add_u64 v[240:241], s[4:5], 0, v[128:129]
	s_add_i32 m0, s74, 0x2000
	s_nop 0
	global_load_lds_dwordx4 v[240:241], off
	v_lshl_add_u64 v[240:241], s[60:61], 0, v[132:133]
	s_mov_b32 m0, s59
	s_nop 0
	global_load_lds_dwordx4 v[240:241], off
	s_mov_b32 m0, s64
	s_nop 0
	global_load_lds_dwordx4 v[242:243], off
	s_waitcnt vmcnt(8)
	s_waitcnt lgkmcnt(0)
	s_barrier
	s_waitcnt lgkmcnt(0)
	v_mfma_f32_16x16x32_bf16 v[60:63], v[138:141], v[208:211], v[60:63]
	v_mfma_f32_16x16x32_bf16 v[56:59], v[160:163], v[208:211], v[56:59]
	v_mfma_f32_16x16x32_bf16 v[44:47], v[138:141], v[216:219], v[44:47]
	v_mfma_f32_16x16x32_bf16 v[40:43], v[160:163], v[216:219], v[40:43]
	v_mfma_f32_16x16x32_bf16 v[28:31], v[138:141], v[224:227], v[28:31]
	v_mfma_f32_16x16x32_bf16 v[24:27], v[160:163], v[224:227], v[24:27]
	v_mfma_f32_16x16x32_bf16 v[12:15], v[138:141], v[232:235], v[12:15]
	v_mfma_f32_16x16x32_bf16 v[8:11], v[160:163], v[232:235], v[8:11]
	v_mfma_f32_16x16x32_bf16 v[60:63], v[156:159], v[212:215], v[60:63]
	v_mfma_f32_16x16x32_bf16 v[56:59], v[164:167], v[212:215], v[56:59]
	v_mfma_f32_16x16x32_bf16 v[44:47], v[156:159], v[220:223], v[44:47]
	v_mfma_f32_16x16x32_bf16 v[40:43], v[164:167], v[220:223], v[40:43]
	v_mfma_f32_16x16x32_bf16 v[28:31], v[156:159], v[228:231], v[28:31]
	v_mfma_f32_16x16x32_bf16 v[24:27], v[164:167], v[228:231], v[24:27]
	v_mfma_f32_16x16x32_bf16 v[12:15], v[156:159], v[236:239], v[12:15]
	v_mfma_f32_16x16x32_bf16 v[8:11], v[164:167], v[236:239], v[8:11]
	v_mfma_f32_16x16x32_bf16 v[52:55], v[168:171], v[208:211], v[52:55]
	v_mfma_f32_16x16x32_bf16 v[48:51], v[176:179], v[208:211], v[48:51]
	v_mfma_f32_16x16x32_bf16 v[36:39], v[168:171], v[216:219], v[36:39]
	v_mfma_f32_16x16x32_bf16 v[32:35], v[176:179], v[216:219], v[32:35]
	v_mfma_f32_16x16x32_bf16 v[20:23], v[168:171], v[224:227], v[20:23]
	v_mfma_f32_16x16x32_bf16 v[16:19], v[176:179], v[224:227], v[16:19]
	v_mfma_f32_16x16x32_bf16 v[4:7], v[168:171], v[232:235], v[4:7]
	v_mfma_f32_16x16x32_bf16 v[0:3], v[176:179], v[232:235], v[0:3]
	v_mfma_f32_16x16x32_bf16 v[52:55], v[172:175], v[212:215], v[52:55]
	v_mfma_f32_16x16x32_bf16 v[48:51], v[204:207], v[212:215], v[48:51]
	v_mfma_f32_16x16x32_bf16 v[36:39], v[172:175], v[220:223], v[36:39]
	v_mfma_f32_16x16x32_bf16 v[32:35], v[204:207], v[220:223], v[32:35]
	v_mfma_f32_16x16x32_bf16 v[20:23], v[172:175], v[228:231], v[20:23]
	v_mfma_f32_16x16x32_bf16 v[16:19], v[204:207], v[228:231], v[16:19]
	v_mfma_f32_16x16x32_bf16 v[4:7], v[172:175], v[236:239], v[4:7]
	v_mfma_f32_16x16x32_bf16 v[0:3], v[204:207], v[236:239], v[0:3]
	s_barrier
	v_add_u32_e32 v164, 0x18000, v143
	v_add_u32_e32 v204, 0x1c000, v143
	ds_read_b128 v[138:141], v164
	ds_read_b128 v[156:159], v164 offset:1024
	ds_read_b128 v[160:163], v164 offset:2048
	ds_read_b128 v[164:167], v164 offset:3072
	ds_read_b128 v[168:171], v204
	ds_read_b128 v[172:175], v204 offset:1024
	ds_read_b128 v[176:179], v204 offset:2048
	ds_read_b128 v[204:207], v204 offset:3072
	ds_read_b128 v[208:211], v155 offset:32768
	ds_read_b128 v[212:215], v155 offset:33792
	ds_read_b128 v[216:219], v155 offset:34816
	ds_read_b128 v[220:223], v155 offset:35840
	ds_read_b128 v[224:227], v155 offset:36864
	ds_read_b128 v[228:231], v155 offset:37888
	ds_read_b128 v[232:235], v155 offset:38912
	ds_read_b128 v[236:239], v155 offset:39936
	s_add_i32 s74, 0, 0x18000
	s_add_i32 s75, 0, 0x1c000
	s_add_u32 s4, s60, 0x40000
	s_addc_u32 s5, s61, 0
	s_mov_b32 m0, s65
	v_lshl_add_u64 v[244:245], s[4:5], 0, v[132:133]
	global_load_lds_dwordx4 v[244:245], off
	v_lshl_add_u64 v[244:245], s[4:5], 0, v[130:131]
	s_mov_b32 m0, s66
	s_nop 0
	global_load_lds_dwordx4 v[244:245], off
	s_waitcnt vmcnt(8)
	s_waitcnt lgkmcnt(0)
	s_barrier
	s_waitcnt lgkmcnt(0)
	v_mfma_f32_16x16x32_bf16 v[124:127], v[138:141], v[208:211], v[124:127]
	v_mfma_f32_16x16x32_bf16 v[120:123], v[160:163], v[208:211], v[120:123]
	v_mfma_f32_16x16x32_bf16 v[108:111], v[138:141], v[216:219], v[108:111]
	v_mfma_f32_16x16x32_bf16 v[104:107], v[160:163], v[216:219], v[104:107]
	v_mfma_f32_16x16x32_bf16 v[92:95], v[138:141], v[224:227], v[92:95]
	v_mfma_f32_16x16x32_bf16 v[88:91], v[160:163], v[224:227], v[88:91]
	v_mfma_f32_16x16x32_bf16 v[76:79], v[138:141], v[232:235], v[76:79]
	v_mfma_f32_16x16x32_bf16 v[72:75], v[160:163], v[232:235], v[72:75]
	v_mfma_f32_16x16x32_bf16 v[124:127], v[156:159], v[212:215], v[124:127]
	v_mfma_f32_16x16x32_bf16 v[120:123], v[164:167], v[212:215], v[120:123]
	v_mfma_f32_16x16x32_bf16 v[108:111], v[156:159], v[220:223], v[108:111]
	v_mfma_f32_16x16x32_bf16 v[104:107], v[164:167], v[220:223], v[104:107]
	v_mfma_f32_16x16x32_bf16 v[92:95], v[156:159], v[228:231], v[92:95]
	v_mfma_f32_16x16x32_bf16 v[88:91], v[164:167], v[228:231], v[88:91]
	v_mfma_f32_16x16x32_bf16 v[76:79], v[156:159], v[236:239], v[76:79]
	v_mfma_f32_16x16x32_bf16 v[72:75], v[164:167], v[236:239], v[72:75]
	v_mfma_f32_16x16x32_bf16 v[116:119], v[168:171], v[208:211], v[116:119]
	v_mfma_f32_16x16x32_bf16 v[112:115], v[176:179], v[208:211], v[112:115]
	v_mfma_f32_16x16x32_bf16 v[100:103], v[168:171], v[216:219], v[100:103]
	v_mfma_f32_16x16x32_bf16 v[96:99], v[176:179], v[216:219], v[96:99]
	v_mfma_f32_16x16x32_bf16 v[84:87], v[168:171], v[224:227], v[84:87]
	v_mfma_f32_16x16x32_bf16 v[80:83], v[176:179], v[224:227], v[80:83]
	v_mfma_f32_16x16x32_bf16 v[68:71], v[168:171], v[232:235], v[68:71]
	v_mfma_f32_16x16x32_bf16 v[64:67], v[176:179], v[232:235], v[64:67]
	v_mfma_f32_16x16x32_bf16 v[116:119], v[172:175], v[212:215], v[116:119]
	v_mfma_f32_16x16x32_bf16 v[112:115], v[204:207], v[212:215], v[112:115]
	v_mfma_f32_16x16x32_bf16 v[100:103], v[172:175], v[220:223], v[100:103]
	v_mfma_f32_16x16x32_bf16 v[96:99], v[204:207], v[220:223], v[96:99]
	v_mfma_f32_16x16x32_bf16 v[84:87], v[172:175], v[228:231], v[84:87]
	v_mfma_f32_16x16x32_bf16 v[80:83], v[204:207], v[228:231], v[80:83]
	v_mfma_f32_16x16x32_bf16 v[68:71], v[172:175], v[236:239], v[68:71]
	v_mfma_f32_16x16x32_bf16 v[64:67], v[204:207], v[236:239], v[64:67]
	s_barrier
	s_add_i32 s4, s74, s1
	v_lshl_add_u64 v[180:181], v[180:181], 0, s[26:27]
	s_mov_b32 m0, s4
	ds_read_b128 v[208:211], v155 offset:49152
	ds_read_b128 v[212:215], v155 offset:50176
	ds_read_b128 v[216:219], v155 offset:51200
	ds_read_b128 v[220:223], v155 offset:52224
	ds_read_b128 v[224:227], v155 offset:53248
	ds_read_b128 v[228:231], v155 offset:54272
	ds_read_b128 v[232:235], v155 offset:55296
	ds_read_b128 v[236:239], v155 offset:56320
	global_load_lds_dwordx4 v[180:181], off
	s_add_i32 m0, s4, 0x2000
	s_add_u32 s4, s34, 0x40080
	v_lshl_add_u64 v[180:181], v[202:203], 0, s[26:27]
	s_addc_u32 s5, s35, 0
	s_add_i32 s34, s75, s1
	global_load_lds_dwordx4 v[180:181], off
	v_lshl_add_u64 v[180:181], s[4:5], 0, v[144:145]
	s_mov_b32 m0, s34
	s_nop 0
	global_load_lds_dwordx4 v[180:181], off
	v_lshl_add_u64 v[180:181], s[4:5], 0, v[128:129]
	s_add_i32 m0, s34, 0x2000
	s_nop 0
	global_load_lds_dwordx4 v[180:181], off
	v_lshl_add_u64 v[180:181], v[240:241], 0, s[26:27]
	s_mov_b32 m0, s67
	s_nop 0
	global_load_lds_dwordx4 v[180:181], off
	v_lshl_add_u64 v[180:181], v[242:243], 0, s[26:27]
	s_mov_b32 m0, s68
	s_nop 0
	global_load_lds_dwordx4 v[180:181], off
	s_waitcnt vmcnt(8)
	s_waitcnt lgkmcnt(0)
	s_barrier
	s_waitcnt lgkmcnt(0)
	v_mfma_f32_16x16x32_bf16 v[60:63], v[138:141], v[208:211], v[60:63]
	v_mfma_f32_16x16x32_bf16 v[56:59], v[160:163], v[208:211], v[56:59]
	v_mfma_f32_16x16x32_bf16 v[44:47], v[138:141], v[216:219], v[44:47]
	v_mfma_f32_16x16x32_bf16 v[40:43], v[160:163], v[216:219], v[40:43]
	v_mfma_f32_16x16x32_bf16 v[28:31], v[138:141], v[224:227], v[28:31]
	v_mfma_f32_16x16x32_bf16 v[24:27], v[160:163], v[224:227], v[24:27]
	v_mfma_f32_16x16x32_bf16 v[12:15], v[138:141], v[232:235], v[12:15]
	v_mfma_f32_16x16x32_bf16 v[8:11], v[160:163], v[232:235], v[8:11]
	v_mfma_f32_16x16x32_bf16 v[60:63], v[156:159], v[212:215], v[60:63]
	v_mfma_f32_16x16x32_bf16 v[56:59], v[164:167], v[212:215], v[56:59]
	v_mfma_f32_16x16x32_bf16 v[44:47], v[156:159], v[220:223], v[44:47]
	v_mfma_f32_16x16x32_bf16 v[40:43], v[164:167], v[220:223], v[40:43]
	v_mfma_f32_16x16x32_bf16 v[28:31], v[156:159], v[228:231], v[28:31]
	v_mfma_f32_16x16x32_bf16 v[24:27], v[164:167], v[228:231], v[24:27]
	v_mfma_f32_16x16x32_bf16 v[12:15], v[156:159], v[236:239], v[12:15]
	v_mfma_f32_16x16x32_bf16 v[8:11], v[164:167], v[236:239], v[8:11]
	v_mfma_f32_16x16x32_bf16 v[52:55], v[168:171], v[208:211], v[52:55]
	v_mfma_f32_16x16x32_bf16 v[48:51], v[176:179], v[208:211], v[48:51]
	v_mfma_f32_16x16x32_bf16 v[36:39], v[168:171], v[216:219], v[36:39]
	v_mfma_f32_16x16x32_bf16 v[32:35], v[176:179], v[216:219], v[32:35]
	v_mfma_f32_16x16x32_bf16 v[20:23], v[168:171], v[224:227], v[20:23]
	v_mfma_f32_16x16x32_bf16 v[16:19], v[176:179], v[224:227], v[16:19]
	v_mfma_f32_16x16x32_bf16 v[4:7], v[168:171], v[232:235], v[4:7]
	v_mfma_f32_16x16x32_bf16 v[0:3], v[176:179], v[232:235], v[0:3]
	v_mfma_f32_16x16x32_bf16 v[52:55], v[172:175], v[212:215], v[52:55]
	v_mfma_f32_16x16x32_bf16 v[48:51], v[204:207], v[212:215], v[48:51]
	v_mfma_f32_16x16x32_bf16 v[36:39], v[172:175], v[220:223], v[36:39]
	v_mfma_f32_16x16x32_bf16 v[32:35], v[204:207], v[220:223], v[32:35]
	v_mfma_f32_16x16x32_bf16 v[20:23], v[172:175], v[228:231], v[20:23]
	v_mfma_f32_16x16x32_bf16 v[16:19], v[204:207], v[228:231], v[16:19]
	v_mfma_f32_16x16x32_bf16 v[4:7], v[172:175], v[236:239], v[4:7]
	v_mfma_f32_16x16x32_bf16 v[0:3], v[204:207], v[236:239], v[0:3]
	s_barrier
	s_add_i32 s73, s73, 2
	s_add_u32 s2, s2, 0x100
	s_addc_u32 s3, s3, 0
	s_add_u32 s71, s71, 0x100
	s_addc_u32 s72, s72, 0
	s_cmp_gt_u32 s73, 13
	s_cbranch_scc0 .LBB0_1305
	s_setprio 0
	v_lshl_add_u32 v140, s58, 8, v142
	v_ashrrev_i32_e32 v141, 31, v140
	v_lshl_add_u64 v[156:157], v[140:141], 4, s[44:45]
	global_load_dwordx4 v[208:211], v[156:157], off
	global_load_dwordx4 v[212:215], v[156:157], off offset:256
	global_load_dwordx4 v[216:219], v[156:157], off offset:512
	global_load_dwordx4 v[220:223], v[156:157], off offset:768
	global_load_dwordx4 v[224:227], v[156:157], off offset:2048
	global_load_dwordx4 v[228:231], v[156:157], off offset:2304
	global_load_dwordx4 v[232:235], v[156:157], off offset:2560
	global_load_dwordx4 v[236:239], v[156:157], off offset:2816
	s_and_b64 vcc, exec, s[46:47]
	s_cbranch_vccz .LBB0_1308
	s_barrier

.Lkprio_1399:
.LBB0_1399:
	v_add_u32_e32 v142, 0x10000, v160
	ds_read_b128 v[138:141], v142
	ds_read_b128 v[154:157], v142 offset:1024
	ds_read_b128 v[172:175], v142 offset:2048
	ds_read_b128 v[176:179], v142 offset:3072
	v_add_u32_e32 v142, 0x14000, v160
	ds_read_b128 v[204:207], v142
	ds_read_b128 v[208:211], v142 offset:1024
	ds_read_b128 v[212:215], v142 offset:2048
	ds_read_b128 v[216:219], v142 offset:3072
	ds_read_b128 v[220:223], v170
	ds_read_b128 v[224:227], v170 offset:1024
	ds_read_b128 v[228:231], v170 offset:2048
	ds_read_b128 v[232:235], v170 offset:3072
	ds_read_b128 v[236:239], v170 offset:4096
	ds_read_b128 v[240:243], v170 offset:5120
	ds_read_b128 v[244:247], v170 offset:6144
	ds_read_b128 v[248:251], v170 offset:7168
	s_add_u32 s58, s54, 0x100
	s_addc_u32 s59, s55, 0
	s_add_i32 s4, 0, 0x10000
	s_cmp_eq_u32 s29, 40
	s_cselect_b32 s61, s45, s59
	s_cselect_b32 s60, s44, s58
	s_cselect_b32 s35, s53, s28
	s_cselect_b32 s34, s52, s3
	s_add_i32 s47, 0, 0x14000
	v_lshl_add_u64 v[142:143], s[54:55], 0, v[134:135]
	s_add_i32 m0, s65, 0xc000
	s_nop 0
	global_load_lds_dwordx4 v[142:143], off
	v_lshl_add_u64 v[142:143], s[54:55], 0, v[136:137]
	s_add_i32 m0, s65, 0xe000
	s_nop 0
	global_load_lds_dwordx4 v[142:143], off
	s_waitcnt vmcnt(8)
	s_waitcnt lgkmcnt(0)
	s_barrier
	s_waitcnt lgkmcnt(0)
	v_mfma_f32_16x16x32_bf16 v[124:127], v[138:141], v[220:223], v[124:127]
	v_mfma_f32_16x16x32_bf16 v[120:123], v[172:175], v[220:223], v[120:123]
	v_mfma_f32_16x16x32_bf16 v[108:111], v[138:141], v[228:231], v[108:111]
	v_mfma_f32_16x16x32_bf16 v[104:107], v[172:175], v[228:231], v[104:107]
	v_mfma_f32_16x16x32_bf16 v[92:95], v[138:141], v[236:239], v[92:95]
	v_mfma_f32_16x16x32_bf16 v[88:91], v[172:175], v[236:239], v[88:91]
	v_mfma_f32_16x16x32_bf16 v[76:79], v[138:141], v[244:247], v[76:79]
	v_mfma_f32_16x16x32_bf16 v[72:75], v[172:175], v[244:247], v[72:75]
	v_mfma_f32_16x16x32_bf16 v[124:127], v[154:157], v[224:227], v[124:127]
	v_mfma_f32_16x16x32_bf16 v[120:123], v[176:179], v[224:227], v[120:123]
	v_mfma_f32_16x16x32_bf16 v[108:111], v[154:157], v[232:235], v[108:111]
	v_mfma_f32_16x16x32_bf16 v[104:107], v[176:179], v[232:235], v[104:107]
	v_mfma_f32_16x16x32_bf16 v[92:95], v[154:157], v[240:243], v[92:95]
	v_mfma_f32_16x16x32_bf16 v[88:91], v[176:179], v[240:243], v[88:91]
	v_mfma_f32_16x16x32_bf16 v[76:79], v[154:157], v[248:251], v[76:79]
	v_mfma_f32_16x16x32_bf16 v[72:75], v[176:179], v[248:251], v[72:75]
	v_mfma_f32_16x16x32_bf16 v[116:119], v[204:207], v[220:223], v[116:119]
	v_mfma_f32_16x16x32_bf16 v[112:115], v[212:215], v[220:223], v[112:115]
	v_mfma_f32_16x16x32_bf16 v[100:103], v[204:207], v[228:231], v[100:103]
	v_mfma_f32_16x16x32_bf16 v[96:99], v[212:215], v[228:231], v[96:99]
	v_mfma_f32_16x16x32_bf16 v[84:87], v[204:207], v[236:239], v[84:87]
	v_mfma_f32_16x16x32_bf16 v[80:83], v[212:215], v[236:239], v[80:83]
	v_mfma_f32_16x16x32_bf16 v[68:71], v[204:207], v[244:247], v[68:71]
	v_mfma_f32_16x16x32_bf16 v[64:67], v[212:215], v[244:247], v[64:67]
	v_mfma_f32_16x16x32_bf16 v[116:119], v[208:211], v[224:227], v[116:119]
	v_mfma_f32_16x16x32_bf16 v[112:115], v[216:219], v[224:227], v[112:115]
	v_mfma_f32_16x16x32_bf16 v[100:103], v[208:211], v[232:235], v[100:103]
	v_mfma_f32_16x16x32_bf16 v[96:99], v[216:219], v[232:235], v[96:99]
	v_mfma_f32_16x16x32_bf16 v[84:87], v[208:211], v[240:243], v[84:87]
	v_mfma_f32_16x16x32_bf16 v[80:83], v[216:219], v[240:243], v[80:83]
	v_mfma_f32_16x16x32_bf16 v[68:71], v[208:211], v[248:251], v[68:71]
	v_mfma_f32_16x16x32_bf16 v[64:67], v[216:219], v[248:251], v[64:67]
	s_barrier
	s_add_i32 s4, s4, s33
	v_lshl_add_u64 v[142:143], s[34:35], 0, v[128:129]
	s_mov_b32 m0, s4
	ds_read_b128 v[220:223], v170 offset:16384
	ds_read_b128 v[224:227], v170 offset:17408
	ds_read_b128 v[228:231], v170 offset:18432
	ds_read_b128 v[232:235], v170 offset:19456
	ds_read_b128 v[236:239], v170 offset:20480
	ds_read_b128 v[240:243], v170 offset:21504
	ds_read_b128 v[244:247], v170 offset:22528
	ds_read_b128 v[248:251], v170 offset:23552
	global_load_lds_dwordx4 v[142:143], off
	s_add_i32 m0, s4, 0x2000
	s_add_u32 s4, s34, 0xb0000
	v_lshl_add_u64 v[158:159], s[34:35], 0, v[130:131]
	s_addc_u32 s5, s35, 0
	s_add_i32 s47, s47, s33
	global_load_lds_dwordx4 v[158:159], off
	v_lshl_add_u64 v[180:181], s[4:5], 0, v[128:129]
	s_mov_b32 m0, s47
	v_lshl_add_u64 v[202:203], s[60:61], 0, v[130:131]
	global_load_lds_dwordx4 v[180:181], off
	v_lshl_add_u64 v[180:181], s[4:5], 0, v[130:131]
	s_add_i32 m0, s47, 0x2000
	s_nop 0
	global_load_lds_dwordx4 v[180:181], off
	v_lshl_add_u64 v[180:181], s[60:61], 0, v[128:129]
	s_mov_b32 m0, s65
	s_nop 0
	global_load_lds_dwordx4 v[180:181], off
	s_mov_b32 m0, s66
	s_nop 0
	global_load_lds_dwordx4 v[202:203], off
	s_waitcnt vmcnt(8)
	s_waitcnt lgkmcnt(0)
	s_barrier
	s_waitcnt lgkmcnt(0)
	v_mfma_f32_16x16x32_bf16 v[60:63], v[138:141], v[220:223], v[60:63]
	v_mfma_f32_16x16x32_bf16 v[56:59], v[172:175], v[220:223], v[56:59]
	v_mfma_f32_16x16x32_bf16 v[44:47], v[138:141], v[228:231], v[44:47]
	v_mfma_f32_16x16x32_bf16 v[40:43], v[172:175], v[228:231], v[40:43]
	v_mfma_f32_16x16x32_bf16 v[28:31], v[138:141], v[236:239], v[28:31]
	v_mfma_f32_16x16x32_bf16 v[24:27], v[172:175], v[236:239], v[24:27]
	v_mfma_f32_16x16x32_bf16 v[12:15], v[138:141], v[244:247], v[12:15]
	v_mfma_f32_16x16x32_bf16 v[8:11], v[172:175], v[244:247], v[8:11]
	v_mfma_f32_16x16x32_bf16 v[60:63], v[154:157], v[224:227], v[60:63]
	v_mfma_f32_16x16x32_bf16 v[56:59], v[176:179], v[224:227], v[56:59]
	v_mfma_f32_16x16x32_bf16 v[44:47], v[154:157], v[232:235], v[44:47]
	v_mfma_f32_16x16x32_bf16 v[40:43], v[176:179], v[232:235], v[40:43]
	v_mfma_f32_16x16x32_bf16 v[28:31], v[154:157], v[240:243], v[28:31]
	v_mfma_f32_16x16x32_bf16 v[24:27], v[176:179], v[240:243], v[24:27]
	v_mfma_f32_16x16x32_bf16 v[12:15], v[154:157], v[248:251], v[12:15]
	v_mfma_f32_16x16x32_bf16 v[8:11], v[176:179], v[248:251], v[8:11]
	v_mfma_f32_16x16x32_bf16 v[52:55], v[204:207], v[220:223], v[52:55]
	v_mfma_f32_16x16x32_bf16 v[48:51], v[212:215], v[220:223], v[48:51]
	v_mfma_f32_16x16x32_bf16 v[36:39], v[204:207], v[228:231], v[36:39]
	v_mfma_f32_16x16x32_bf16 v[32:35], v[212:215], v[228:231], v[32:35]
	v_mfma_f32_16x16x32_bf16 v[20:23], v[204:207], v[236:239], v[20:23]
	v_mfma_f32_16x16x32_bf16 v[16:19], v[212:215], v[236:239], v[16:19]
	v_mfma_f32_16x16x32_bf16 v[4:7], v[204:207], v[244:247], v[4:7]
	v_mfma_f32_16x16x32_bf16 v[0:3], v[212:215], v[244:247], v[0:3]
	v_mfma_f32_16x16x32_bf16 v[52:55], v[208:211], v[224:227], v[52:55]
	v_mfma_f32_16x16x32_bf16 v[48:51], v[216:219], v[224:227], v[48:51]
	v_mfma_f32_16x16x32_bf16 v[36:39], v[208:211], v[232:235], v[36:39]
	v_mfma_f32_16x16x32_bf16 v[32:35], v[216:219], v[232:235], v[32:35]
	v_mfma_f32_16x16x32_bf16 v[20:23], v[208:211], v[240:243], v[20:23]
	v_mfma_f32_16x16x32_bf16 v[16:19], v[216:219], v[240:243], v[16:19]
	v_mfma_f32_16x16x32_bf16 v[4:7], v[208:211], v[248:251], v[4:7]
	v_mfma_f32_16x16x32_bf16 v[0:3], v[216:219], v[248:251], v[0:3]
	s_barrier
	v_add_u32_e32 v144, 0x18000, v160
	ds_read_b128 v[138:141], v144
	ds_read_b128 v[154:157], v144 offset:1024
	ds_read_b128 v[172:175], v144 offset:2048
	ds_read_b128 v[176:179], v144 offset:3072
	v_add_u32_e32 v144, 0x1c000, v160
	ds_read_b128 v[204:207], v144
	ds_read_b128 v[208:211], v144 offset:1024
	ds_read_b128 v[212:215], v144 offset:2048
	ds_read_b128 v[216:219], v144 offset:3072
	ds_read_b128 v[220:223], v170 offset:32768
	ds_read_b128 v[224:227], v170 offset:33792
	ds_read_b128 v[228:231], v170 offset:34816
	ds_read_b128 v[232:235], v170 offset:35840
	ds_read_b128 v[236:239], v170 offset:36864
	ds_read_b128 v[240:243], v170 offset:37888
	ds_read_b128 v[244:247], v170 offset:38912
	ds_read_b128 v[248:251], v170 offset:39936
	s_add_i32 s47, 0, 0x18000
	s_add_i32 s54, 0, 0x1c000
	s_add_u32 s4, s60, 0xb0000
	s_addc_u32 s5, s61, 0
	s_mov_b32 m0, s67
	v_lshl_add_u64 v[252:253], s[4:5], 0, v[128:129]
	global_load_lds_dwordx4 v[252:253], off
	v_lshl_add_u64 v[252:253], s[4:5], 0, v[130:131]
	s_mov_b32 m0, s68
	s_nop 0
	global_load_lds_dwordx4 v[252:253], off
	s_waitcnt vmcnt(8)
	s_waitcnt lgkmcnt(0)
	s_barrier
	s_waitcnt lgkmcnt(0)
	v_mfma_f32_16x16x32_bf16 v[124:127], v[138:141], v[220:223], v[124:127]
	v_mfma_f32_16x16x32_bf16 v[120:123], v[172:175], v[220:223], v[120:123]
	v_mfma_f32_16x16x32_bf16 v[108:111], v[138:141], v[228:231], v[108:111]
	v_mfma_f32_16x16x32_bf16 v[104:107], v[172:175], v[228:231], v[104:107]
	v_mfma_f32_16x16x32_bf16 v[92:95], v[138:141], v[236:239], v[92:95]
	v_mfma_f32_16x16x32_bf16 v[88:91], v[172:175], v[236:239], v[88:91]
	v_mfma_f32_16x16x32_bf16 v[76:79], v[138:141], v[244:247], v[76:79]
	v_mfma_f32_16x16x32_bf16 v[72:75], v[172:175], v[244:247], v[72:75]
	v_mfma_f32_16x16x32_bf16 v[124:127], v[154:157], v[224:227], v[124:127]
	v_mfma_f32_16x16x32_bf16 v[120:123], v[176:179], v[224:227], v[120:123]
	v_mfma_f32_16x16x32_bf16 v[108:111], v[154:157], v[232:235], v[108:111]
	v_mfma_f32_16x16x32_bf16 v[104:107], v[176:179], v[232:235], v[104:107]
	v_mfma_f32_16x16x32_bf16 v[92:95], v[154:157], v[240:243], v[92:95]
	v_mfma_f32_16x16x32_bf16 v[88:91], v[176:179], v[240:243], v[88:91]
	v_mfma_f32_16x16x32_bf16 v[76:79], v[154:157], v[248:251], v[76:79]
	v_mfma_f32_16x16x32_bf16 v[72:75], v[176:179], v[248:251], v[72:75]
	v_mfma_f32_16x16x32_bf16 v[116:119], v[204:207], v[220:223], v[116:119]
	v_mfma_f32_16x16x32_bf16 v[112:115], v[212:215], v[220:223], v[112:115]
	v_mfma_f32_16x16x32_bf16 v[100:103], v[204:207], v[228:231], v[100:103]
	v_mfma_f32_16x16x32_bf16 v[96:99], v[212:215], v[228:231], v[96:99]
	v_mfma_f32_16x16x32_bf16 v[84:87], v[204:207], v[236:239], v[84:87]
	v_mfma_f32_16x16x32_bf16 v[80:83], v[212:215], v[236:239], v[80:83]
	v_mfma_f32_16x16x32_bf16 v[68:71], v[204:207], v[244:247], v[68:71]
	v_mfma_f32_16x16x32_bf16 v[64:67], v[212:215], v[244:247], v[64:67]
	v_mfma_f32_16x16x32_bf16 v[116:119], v[208:211], v[224:227], v[116:119]
	v_mfma_f32_16x16x32_bf16 v[112:115], v[216:219], v[224:227], v[112:115]
	v_mfma_f32_16x16x32_bf16 v[100:103], v[208:211], v[232:235], v[100:103]
	v_mfma_f32_16x16x32_bf16 v[96:99], v[216:219], v[232:235], v[96:99]
	v_mfma_f32_16x16x32_bf16 v[84:87], v[208:211], v[240:243], v[84:87]
	v_mfma_f32_16x16x32_bf16 v[80:83], v[216:219], v[240:243], v[80:83]
	v_mfma_f32_16x16x32_bf16 v[68:71], v[208:211], v[248:251], v[68:71]
	v_mfma_f32_16x16x32_bf16 v[64:67], v[216:219], v[248:251], v[64:67]
	s_barrier
	s_add_i32 s4, s47, s33
	v_lshl_add_u64 v[142:143], v[142:143], 0, s[26:27]
	s_mov_b32 m0, s4
	ds_read_b128 v[220:223], v170 offset:49152
	ds_read_b128 v[224:227], v170 offset:50176
	ds_read_b128 v[228:231], v170 offset:51200
	ds_read_b128 v[232:235], v170 offset:52224
	ds_read_b128 v[236:239], v170 offset:53248
	ds_read_b128 v[240:243], v170 offset:54272
	ds_read_b128 v[244:247], v170 offset:55296
	ds_read_b128 v[248:251], v170 offset:56320
	global_load_lds_dwordx4 v[142:143], off
	s_add_i32 m0, s4, 0x2000
	s_add_u32 s4, s34, 0xb0080
	v_lshl_add_u64 v[142:143], v[158:159], 0, s[26:27]
	s_addc_u32 s5, s35, 0
	s_add_i32 s34, s54, s33
	global_load_lds_dwordx4 v[142:143], off
	v_lshl_add_u64 v[142:143], s[4:5], 0, v[128:129]
	s_mov_b32 m0, s34
	s_nop 0
	global_load_lds_dwordx4 v[142:143], off
	v_lshl_add_u64 v[142:143], s[4:5], 0, v[130:131]
	s_add_i32 m0, s34, 0x2000
	s_nop 0
	global_load_lds_dwordx4 v[142:143], off
	v_lshl_add_u64 v[142:143], v[180:181], 0, s[26:27]
	s_mov_b32 m0, s69
	s_nop 0
	global_load_lds_dwordx4 v[142:143], off
	v_lshl_add_u64 v[142:143], v[202:203], 0, s[26:27]
	s_mov_b32 m0, s70
	s_nop 0
	global_load_lds_dwordx4 v[142:143], off
	s_waitcnt vmcnt(8)
	s_waitcnt lgkmcnt(0)
	s_barrier
	s_waitcnt lgkmcnt(0)
	v_mfma_f32_16x16x32_bf16 v[60:63], v[138:141], v[220:223], v[60:63]
	v_mfma_f32_16x16x32_bf16 v[56:59], v[172:175], v[220:223], v[56:59]
	v_mfma_f32_16x16x32_bf16 v[44:47], v[138:141], v[228:231], v[44:47]
	v_mfma_f32_16x16x32_bf16 v[40:43], v[172:175], v[228:231], v[40:43]
	v_mfma_f32_16x16x32_bf16 v[28:31], v[138:141], v[236:239], v[28:31]
	v_mfma_f32_16x16x32_bf16 v[24:27], v[172:175], v[236:239], v[24:27]
	v_mfma_f32_16x16x32_bf16 v[12:15], v[138:141], v[244:247], v[12:15]
	v_mfma_f32_16x16x32_bf16 v[8:11], v[172:175], v[244:247], v[8:11]
	v_mfma_f32_16x16x32_bf16 v[60:63], v[154:157], v[224:227], v[60:63]
	v_mfma_f32_16x16x32_bf16 v[56:59], v[176:179], v[224:227], v[56:59]
	v_mfma_f32_16x16x32_bf16 v[44:47], v[154:157], v[232:235], v[44:47]
	v_mfma_f32_16x16x32_bf16 v[40:43], v[176:179], v[232:235], v[40:43]
	v_mfma_f32_16x16x32_bf16 v[28:31], v[154:157], v[240:243], v[28:31]
	v_mfma_f32_16x16x32_bf16 v[24:27], v[176:179], v[240:243], v[24:27]
	v_mfma_f32_16x16x32_bf16 v[12:15], v[154:157], v[248:251], v[12:15]
	v_mfma_f32_16x16x32_bf16 v[8:11], v[176:179], v[248:251], v[8:11]
	v_mfma_f32_16x16x32_bf16 v[52:55], v[204:207], v[220:223], v[52:55]
	v_mfma_f32_16x16x32_bf16 v[48:51], v[212:215], v[220:223], v[48:51]
	v_mfma_f32_16x16x32_bf16 v[36:39], v[204:207], v[228:231], v[36:39]
	v_mfma_f32_16x16x32_bf16 v[32:35], v[212:215], v[228:231], v[32:35]
	v_mfma_f32_16x16x32_bf16 v[20:23], v[204:207], v[236:239], v[20:23]
	v_mfma_f32_16x16x32_bf16 v[16:19], v[212:215], v[236:239], v[16:19]
	v_mfma_f32_16x16x32_bf16 v[4:7], v[204:207], v[244:247], v[4:7]
	v_mfma_f32_16x16x32_bf16 v[0:3], v[212:215], v[244:247], v[0:3]
	v_mfma_f32_16x16x32_bf16 v[52:55], v[208:211], v[224:227], v[52:55]
	v_mfma_f32_16x16x32_bf16 v[48:51], v[216:219], v[224:227], v[48:51]
	v_mfma_f32_16x16x32_bf16 v[36:39], v[208:211], v[232:235], v[36:39]
	v_mfma_f32_16x16x32_bf16 v[32:35], v[216:219], v[232:235], v[32:35]
	v_mfma_f32_16x16x32_bf16 v[20:23], v[208:211], v[240:243], v[20:23]
	v_mfma_f32_16x16x32_bf16 v[16:19], v[216:219], v[240:243], v[16:19]
	v_mfma_f32_16x16x32_bf16 v[4:7], v[208:211], v[248:251], v[4:7]
	v_mfma_f32_16x16x32_bf16 v[0:3], v[216:219], v[248:251], v[0:3]
	s_barrier
	s_add_i32 s29, s29, 2
	s_add_u32 s3, s3, 0x100
	s_addc_u32 s28, s28, 0
	s_cmp_gt_u32 s29, 41
	s_mov_b64 s[54:55], s[58:59]
	s_cbranch_scc0 .LBB0_1399
	s_setprio 0
	s_and_b64 vcc, exec, s[50:51]
	s_cbranch_vccz .LBB0_1402
	s_barrier
